# GEMM K-loops: first iteration peeled with SrcC=0, accumulator zeroing v_movs removed (all 10 GEMM instances)
# speedup vs baseline: 1.0076x; 1.0076x over previous
.LBB0_275:
	s_ashr_i32 s17, s16, 31
	s_lshl_b64 s[18:19], s[16:17], 19
	s_add_u32 s18, s25, s18
	s_addc_u32 s19, s29, s19
	s_and_b64 s[20:21], s[4:5], exec
	s_cselect_b32 s17, s19, s23
	s_cselect_b32 s50, s18, s22
	s_ashr_i32 s15, s14, 31
	s_lshl_b64 s[20:21], s[14:15], 19
	s_add_u32 s20, s36, s20
	s_addc_u32 s21, s37, s21
	s_and_b64 s[34:35], s[4:5], exec
	s_cselect_b32 s15, s21, s31
	s_cselect_b32 s51, s20, s30
	s_add_u32 s22, s22, 0x40080
	s_addc_u32 s23, s23, 0
	s_add_u32 s55, s30, 0x100
	s_addc_u32 s58, s31, 0
	s_mov_b32 s59, -2
	s_add_u32 s30, s22, 0xfffc0080
	s_addc_u32 s31, s23, -1
	s_add_i32 s56, 0, 0x10000
	s_cmp_eq_u32 s59, 12
	s_cselect_b32 s35, s17, s31
	s_cselect_b32 s34, s50, s30
	s_cselect_b32 s31, s15, s58
	s_cselect_b32 s30, s51, s55
	s_add_i32 s62, 0, 0x14000
	v_add_u32_e32 v122, s56, v204
	v_add_u32_e32 v170, s62, v204
	ds_read_b128 v[76:79], v122
	ds_read_b128 v[80:83], v122 offset:1024
	ds_read_b128 v[118:121], v122 offset:2048
	ds_read_b128 v[122:125], v122 offset:3072
	ds_read_b128 v[146:149], v170
	ds_read_b128 v[150:153], v170 offset:1024
	ds_read_b128 v[166:169], v170 offset:2048
	ds_read_b128 v[170:173], v170 offset:3072
	v_lshl_add_u64 v[194:195], s[22:23], 0, v[162:163]
	s_add_i32 m0, s40, 0xc000
	ds_read_b128 v[174:177], v206
	ds_read_b128 v[178:181], v206 offset:1024
	ds_read_b128 v[182:185], v206 offset:2048
	ds_read_b128 v[198:201], v206 offset:3072
	ds_read_b128 v[208:211], v206 offset:4096
	ds_read_b128 v[212:215], v206 offset:5120
	ds_read_b128 v[216:219], v206 offset:6144
	ds_read_b128 v[220:223], v206 offset:7168
	global_load_lds_dwordx4 v[194:195], off
	v_lshl_add_u64 v[194:195], s[22:23], 0, v[164:165]
	s_add_i32 m0, s40, 0xe000
	s_nop 0
	global_load_lds_dwordx4 v[194:195], off
	s_waitcnt vmcnt(8)
	s_waitcnt lgkmcnt(0)
	s_barrier
	s_setprio 1
	s_waitcnt lgkmcnt(0)
	v_mfma_f32_16x16x32_bf16 v[142:145], v[76:79], v[174:177], 0
	v_mfma_f32_16x16x32_bf16 v[134:137], v[118:121], v[174:177], 0
	v_mfma_f32_16x16x32_bf16 v[126:129], v[76:79], v[182:185], 0
	v_mfma_f32_16x16x32_bf16 v[108:111], v[118:121], v[182:185], 0
	v_mfma_f32_16x16x32_bf16 v[100:103], v[76:79], v[208:211], 0
	v_mfma_f32_16x16x32_bf16 v[92:95], v[118:121], v[208:211], 0
	v_mfma_f32_16x16x32_bf16 v[84:87], v[76:79], v[216:219], 0
	v_mfma_f32_16x16x32_bf16 v[68:71], v[118:121], v[216:219], 0
	v_mfma_f32_16x16x32_bf16 v[142:145], v[80:83], v[178:181], v[142:145]
	v_mfma_f32_16x16x32_bf16 v[134:137], v[122:125], v[178:181], v[134:137]
	v_mfma_f32_16x16x32_bf16 v[126:129], v[80:83], v[198:201], v[126:129]
	v_mfma_f32_16x16x32_bf16 v[108:111], v[122:125], v[198:201], v[108:111]
	v_mfma_f32_16x16x32_bf16 v[100:103], v[80:83], v[212:215], v[100:103]
	v_mfma_f32_16x16x32_bf16 v[92:95], v[122:125], v[212:215], v[92:95]
	v_mfma_f32_16x16x32_bf16 v[84:87], v[80:83], v[220:223], v[84:87]
	v_mfma_f32_16x16x32_bf16 v[68:71], v[122:125], v[220:223], v[68:71]
	s_setprio 0
	s_setprio 1
	v_mfma_f32_16x16x32_bf16 v[138:141], v[146:149], v[174:177], 0
	v_mfma_f32_16x16x32_bf16 v[130:133], v[166:169], v[174:177], 0
	v_mfma_f32_16x16x32_bf16 v[114:117], v[146:149], v[182:185], 0
	v_mfma_f32_16x16x32_bf16 v[104:107], v[166:169], v[182:185], 0
	v_mfma_f32_16x16x32_bf16 v[96:99], v[146:149], v[208:211], 0
	v_mfma_f32_16x16x32_bf16 v[88:91], v[166:169], v[208:211], 0
	v_mfma_f32_16x16x32_bf16 v[72:75], v[146:149], v[216:219], 0
	v_mfma_f32_16x16x32_bf16 v[64:67], v[166:169], v[216:219], 0
	v_mfma_f32_16x16x32_bf16 v[138:141], v[150:153], v[178:181], v[138:141]
	v_mfma_f32_16x16x32_bf16 v[130:133], v[170:173], v[178:181], v[130:133]
	v_mfma_f32_16x16x32_bf16 v[114:117], v[150:153], v[198:201], v[114:117]
	v_mfma_f32_16x16x32_bf16 v[104:107], v[170:173], v[198:201], v[104:107]
	v_mfma_f32_16x16x32_bf16 v[96:99], v[150:153], v[212:215], v[96:99]
	v_mfma_f32_16x16x32_bf16 v[88:91], v[170:173], v[212:215], v[88:91]
	v_mfma_f32_16x16x32_bf16 v[72:75], v[150:153], v[220:223], v[72:75]
	v_mfma_f32_16x16x32_bf16 v[64:67], v[170:173], v[220:223], v[64:67]
	s_setprio 0
	s_barrier
	s_add_i32 s56, s56, s39
	v_lshl_add_u64 v[194:195], s[30:31], 0, v[112:113]
	s_mov_b32 m0, s56
	ds_read_b128 v[174:177], v206 offset:16384
	ds_read_b128 v[178:181], v206 offset:17408
	ds_read_b128 v[182:185], v206 offset:18432
	ds_read_b128 v[198:201], v206 offset:19456
	ds_read_b128 v[208:211], v206 offset:20480
	ds_read_b128 v[212:215], v206 offset:21504
	ds_read_b128 v[216:219], v206 offset:22528
	ds_read_b128 v[220:223], v206 offset:23552
	global_load_lds_dwordx4 v[194:195], off
	s_add_i32 m0, s56, 0x2000
	s_add_u32 s56, s30, 0x40000
	v_lshl_add_u64 v[196:197], s[30:31], 0, v[154:155]
	s_addc_u32 s57, s31, 0
	s_add_i32 s62, s62, s39
	global_load_lds_dwordx4 v[196:197], off
	v_lshl_add_u64 v[234:235], s[56:57], 0, v[112:113]
	s_mov_b32 m0, s62
	v_lshl_add_u64 v[236:237], s[34:35], 0, v[156:157]
	global_load_lds_dwordx4 v[234:235], off
	v_lshl_add_u64 v[234:235], s[56:57], 0, v[154:155]
	s_add_i32 m0, s62, 0x2000
	s_nop 0
	global_load_lds_dwordx4 v[234:235], off
	v_lshl_add_u64 v[234:235], s[34:35], 0, v[158:159]
	s_mov_b32 m0, s40
	s_nop 0
	global_load_lds_dwordx4 v[234:235], off
	s_mov_b32 m0, s41
	s_nop 0
	global_load_lds_dwordx4 v[236:237], off
	s_waitcnt vmcnt(8)
	s_waitcnt lgkmcnt(0)
	s_barrier
	s_setprio 1
	s_waitcnt lgkmcnt(0)
	v_mfma_f32_16x16x32_bf16 v[60:63], v[76:79], v[174:177], 0
	v_mfma_f32_16x16x32_bf16 v[52:55], v[118:121], v[174:177], 0
	v_mfma_f32_16x16x32_bf16 v[44:47], v[76:79], v[182:185], 0
	v_mfma_f32_16x16x32_bf16 v[36:39], v[118:121], v[182:185], 0
	v_mfma_f32_16x16x32_bf16 v[28:31], v[76:79], v[208:211], 0
	v_mfma_f32_16x16x32_bf16 v[20:23], v[118:121], v[208:211], 0
	v_mfma_f32_16x16x32_bf16 v[12:15], v[76:79], v[216:219], 0
	v_mfma_f32_16x16x32_bf16 v[4:7], v[118:121], v[216:219], 0
	v_mfma_f32_16x16x32_bf16 v[60:63], v[80:83], v[178:181], v[60:63]
	v_mfma_f32_16x16x32_bf16 v[52:55], v[122:125], v[178:181], v[52:55]
	v_mfma_f32_16x16x32_bf16 v[44:47], v[80:83], v[198:201], v[44:47]
	v_mfma_f32_16x16x32_bf16 v[36:39], v[122:125], v[198:201], v[36:39]
	v_mfma_f32_16x16x32_bf16 v[28:31], v[80:83], v[212:215], v[28:31]
	v_mfma_f32_16x16x32_bf16 v[20:23], v[122:125], v[212:215], v[20:23]
	v_mfma_f32_16x16x32_bf16 v[12:15], v[80:83], v[220:223], v[12:15]
	v_mfma_f32_16x16x32_bf16 v[4:7], v[122:125], v[220:223], v[4:7]
	s_setprio 0
	s_setprio 1
	v_mfma_f32_16x16x32_bf16 v[56:59], v[146:149], v[174:177], 0
	v_mfma_f32_16x16x32_bf16 v[48:51], v[166:169], v[174:177], 0
	v_mfma_f32_16x16x32_bf16 v[40:43], v[146:149], v[182:185], 0
	v_mfma_f32_16x16x32_bf16 v[32:35], v[166:169], v[182:185], 0
	v_mfma_f32_16x16x32_bf16 v[24:27], v[146:149], v[208:211], 0
	v_mfma_f32_16x16x32_bf16 v[16:19], v[166:169], v[208:211], 0
	v_mfma_f32_16x16x32_bf16 v[8:11], v[146:149], v[216:219], 0
	v_mfma_f32_16x16x32_bf16 v[0:3], v[166:169], v[216:219], 0
	v_mfma_f32_16x16x32_bf16 v[56:59], v[150:153], v[178:181], v[56:59]
	v_mfma_f32_16x16x32_bf16 v[48:51], v[170:173], v[178:181], v[48:51]
	v_mfma_f32_16x16x32_bf16 v[40:43], v[150:153], v[198:201], v[40:43]
	v_mfma_f32_16x16x32_bf16 v[32:35], v[170:173], v[198:201], v[32:35]
	v_mfma_f32_16x16x32_bf16 v[24:27], v[150:153], v[212:215], v[24:27]
	v_mfma_f32_16x16x32_bf16 v[16:19], v[170:173], v[212:215], v[16:19]
	v_mfma_f32_16x16x32_bf16 v[8:11], v[150:153], v[220:223], v[8:11]
	v_mfma_f32_16x16x32_bf16 v[0:3], v[170:173], v[220:223], v[0:3]
	s_setprio 0
	s_barrier
	s_add_i32 s56, 0, 0x18000
	s_add_i32 s57, 0, 0x1c000
	v_add_u32_e32 v122, s56, v204
	v_add_u32_e32 v170, s57, v204
	ds_read_b128 v[76:79], v122
	ds_read_b128 v[80:83], v122 offset:1024
	ds_read_b128 v[118:121], v122 offset:2048
	ds_read_b128 v[122:125], v122 offset:3072
	ds_read_b128 v[146:149], v170
	ds_read_b128 v[150:153], v170 offset:1024
	ds_read_b128 v[166:169], v170 offset:2048
	ds_read_b128 v[170:173], v170 offset:3072
	s_add_u32 s34, s34, 0x40000
	s_addc_u32 s35, s35, 0
	s_mov_b32 m0, s42
	v_lshl_add_u64 v[238:239], s[34:35], 0, v[158:159]
	ds_read_b128 v[174:177], v206 offset:32768
	ds_read_b128 v[178:181], v206 offset:33792
	ds_read_b128 v[182:185], v206 offset:34816
	ds_read_b128 v[198:201], v206 offset:35840
	ds_read_b128 v[208:211], v206 offset:36864
	ds_read_b128 v[212:215], v206 offset:37888
	ds_read_b128 v[216:219], v206 offset:38912
	ds_read_b128 v[220:223], v206 offset:39936
	global_load_lds_dwordx4 v[238:239], off
	v_lshl_add_u64 v[238:239], s[34:35], 0, v[156:157]
	s_mov_b32 m0, s43
	s_nop 0
	global_load_lds_dwordx4 v[238:239], off
	s_waitcnt vmcnt(8)
	s_waitcnt lgkmcnt(0)
	s_barrier
	s_setprio 1
	s_waitcnt lgkmcnt(0)
	v_mfma_f32_16x16x32_bf16 v[142:145], v[76:79], v[174:177], v[142:145]
	v_mfma_f32_16x16x32_bf16 v[134:137], v[118:121], v[174:177], v[134:137]
	v_mfma_f32_16x16x32_bf16 v[126:129], v[76:79], v[182:185], v[126:129]
	v_mfma_f32_16x16x32_bf16 v[108:111], v[118:121], v[182:185], v[108:111]
	v_mfma_f32_16x16x32_bf16 v[100:103], v[76:79], v[208:211], v[100:103]
	v_mfma_f32_16x16x32_bf16 v[92:95], v[118:121], v[208:211], v[92:95]
	v_mfma_f32_16x16x32_bf16 v[84:87], v[76:79], v[216:219], v[84:87]
	v_mfma_f32_16x16x32_bf16 v[68:71], v[118:121], v[216:219], v[68:71]
	v_mfma_f32_16x16x32_bf16 v[142:145], v[80:83], v[178:181], v[142:145]
	v_mfma_f32_16x16x32_bf16 v[134:137], v[122:125], v[178:181], v[134:137]
	v_mfma_f32_16x16x32_bf16 v[126:129], v[80:83], v[198:201], v[126:129]
	v_mfma_f32_16x16x32_bf16 v[108:111], v[122:125], v[198:201], v[108:111]
	v_mfma_f32_16x16x32_bf16 v[100:103], v[80:83], v[212:215], v[100:103]
	v_mfma_f32_16x16x32_bf16 v[92:95], v[122:125], v[212:215], v[92:95]
	v_mfma_f32_16x16x32_bf16 v[84:87], v[80:83], v[220:223], v[84:87]
	v_mfma_f32_16x16x32_bf16 v[68:71], v[122:125], v[220:223], v[68:71]
	s_setprio 0
	s_setprio 1
	v_mfma_f32_16x16x32_bf16 v[138:141], v[146:149], v[174:177], v[138:141]
	v_mfma_f32_16x16x32_bf16 v[130:133], v[166:169], v[174:177], v[130:133]
	v_mfma_f32_16x16x32_bf16 v[114:117], v[146:149], v[182:185], v[114:117]
	v_mfma_f32_16x16x32_bf16 v[104:107], v[166:169], v[182:185], v[104:107]
	v_mfma_f32_16x16x32_bf16 v[96:99], v[146:149], v[208:211], v[96:99]
	v_mfma_f32_16x16x32_bf16 v[88:91], v[166:169], v[208:211], v[88:91]
	v_mfma_f32_16x16x32_bf16 v[72:75], v[146:149], v[216:219], v[72:75]
	v_mfma_f32_16x16x32_bf16 v[64:67], v[166:169], v[216:219], v[64:67]
	v_mfma_f32_16x16x32_bf16 v[138:141], v[150:153], v[178:181], v[138:141]
	v_mfma_f32_16x16x32_bf16 v[130:133], v[170:173], v[178:181], v[130:133]
	v_mfma_f32_16x16x32_bf16 v[114:117], v[150:153], v[198:201], v[114:117]
	v_mfma_f32_16x16x32_bf16 v[104:107], v[170:173], v[198:201], v[104:107]
	v_mfma_f32_16x16x32_bf16 v[96:99], v[150:153], v[212:215], v[96:99]
	v_mfma_f32_16x16x32_bf16 v[88:91], v[170:173], v[212:215], v[88:91]
	v_mfma_f32_16x16x32_bf16 v[72:75], v[150:153], v[220:223], v[72:75]
	v_mfma_f32_16x16x32_bf16 v[64:67], v[170:173], v[220:223], v[64:67]
	s_setprio 0
	s_barrier
	s_add_i32 s34, s56, s39
	v_lshl_add_u64 v[194:195], v[194:195], 0, s[60:61]
	s_mov_b32 m0, s34
	ds_read_b128 v[174:177], v206 offset:49152
	ds_read_b128 v[178:181], v206 offset:50176
	ds_read_b128 v[182:185], v206 offset:51200
	ds_read_b128 v[198:201], v206 offset:52224
	ds_read_b128 v[208:211], v206 offset:53248
	ds_read_b128 v[212:215], v206 offset:54272
	ds_read_b128 v[216:219], v206 offset:55296
	ds_read_b128 v[220:223], v206 offset:56320
	global_load_lds_dwordx4 v[194:195], off
	s_add_i32 m0, s34, 0x2000
	s_add_u32 s30, s30, 0x40080
	v_lshl_add_u64 v[194:195], v[196:197], 0, s[60:61]
	s_addc_u32 s31, s31, 0
	s_add_i32 s34, s57, s39
	global_load_lds_dwordx4 v[194:195], off
	v_lshl_add_u64 v[194:195], s[30:31], 0, v[112:113]
	s_mov_b32 m0, s34
	s_nop 0
	global_load_lds_dwordx4 v[194:195], off
	v_lshl_add_u64 v[194:195], s[30:31], 0, v[154:155]
	s_add_i32 m0, s34, 0x2000
	s_nop 0
	global_load_lds_dwordx4 v[194:195], off
	v_lshl_add_u64 v[194:195], v[234:235], 0, s[60:61]
	s_mov_b32 m0, s44
	s_nop 0
	global_load_lds_dwordx4 v[194:195], off
	v_lshl_add_u64 v[194:195], v[236:237], 0, s[60:61]
	s_mov_b32 m0, s45
	s_nop 0
	global_load_lds_dwordx4 v[194:195], off
	s_waitcnt vmcnt(8)
	s_waitcnt lgkmcnt(0)
	s_barrier
	s_setprio 1
	s_waitcnt lgkmcnt(0)
	v_mfma_f32_16x16x32_bf16 v[60:63], v[76:79], v[174:177], v[60:63]
	v_mfma_f32_16x16x32_bf16 v[52:55], v[118:121], v[174:177], v[52:55]
	v_mfma_f32_16x16x32_bf16 v[44:47], v[76:79], v[182:185], v[44:47]
	v_mfma_f32_16x16x32_bf16 v[36:39], v[118:121], v[182:185], v[36:39]
	v_mfma_f32_16x16x32_bf16 v[28:31], v[76:79], v[208:211], v[28:31]
	v_mfma_f32_16x16x32_bf16 v[20:23], v[118:121], v[208:211], v[20:23]
	v_mfma_f32_16x16x32_bf16 v[12:15], v[76:79], v[216:219], v[12:15]
	v_mfma_f32_16x16x32_bf16 v[4:7], v[118:121], v[216:219], v[4:7]
	v_mfma_f32_16x16x32_bf16 v[60:63], v[80:83], v[178:181], v[60:63]
	v_mfma_f32_16x16x32_bf16 v[52:55], v[122:125], v[178:181], v[52:55]
	v_mfma_f32_16x16x32_bf16 v[44:47], v[80:83], v[198:201], v[44:47]
	v_mfma_f32_16x16x32_bf16 v[36:39], v[122:125], v[198:201], v[36:39]
	v_mfma_f32_16x16x32_bf16 v[28:31], v[80:83], v[212:215], v[28:31]
	v_mfma_f32_16x16x32_bf16 v[20:23], v[122:125], v[212:215], v[20:23]
	v_mfma_f32_16x16x32_bf16 v[12:15], v[80:83], v[220:223], v[12:15]
	v_mfma_f32_16x16x32_bf16 v[4:7], v[122:125], v[220:223], v[4:7]
	s_setprio 0
	s_setprio 1
	v_mfma_f32_16x16x32_bf16 v[56:59], v[146:149], v[174:177], v[56:59]
	v_mfma_f32_16x16x32_bf16 v[48:51], v[166:169], v[174:177], v[48:51]
	v_mfma_f32_16x16x32_bf16 v[40:43], v[146:149], v[182:185], v[40:43]
	v_mfma_f32_16x16x32_bf16 v[32:35], v[166:169], v[182:185], v[32:35]
	v_mfma_f32_16x16x32_bf16 v[24:27], v[146:149], v[208:211], v[24:27]
	v_mfma_f32_16x16x32_bf16 v[16:19], v[166:169], v[208:211], v[16:19]
	v_mfma_f32_16x16x32_bf16 v[8:11], v[146:149], v[216:219], v[8:11]
	v_mfma_f32_16x16x32_bf16 v[0:3], v[166:169], v[216:219], v[0:3]
	v_mfma_f32_16x16x32_bf16 v[56:59], v[150:153], v[178:181], v[56:59]
	v_mfma_f32_16x16x32_bf16 v[48:51], v[170:173], v[178:181], v[48:51]
	v_mfma_f32_16x16x32_bf16 v[40:43], v[150:153], v[198:201], v[40:43]
	v_mfma_f32_16x16x32_bf16 v[32:35], v[170:173], v[198:201], v[32:35]
	v_mfma_f32_16x16x32_bf16 v[24:27], v[150:153], v[212:215], v[24:27]
	v_mfma_f32_16x16x32_bf16 v[16:19], v[170:173], v[212:215], v[16:19]
	v_mfma_f32_16x16x32_bf16 v[8:11], v[150:153], v[220:223], v[8:11]
	v_mfma_f32_16x16x32_bf16 v[0:3], v[170:173], v[220:223], v[0:3]
	s_setprio 0
	s_barrier
	s_add_i32 s59, s59, 2
	s_add_u32 s22, s22, 0x100
	s_addc_u32 s23, s23, 0
	s_add_u32 s55, s55, 0x100
	s_addc_u32 s58, s58, 0
	s_cmp_gt_u32 s59, 13
	s_cbranch_scc0 .LBB0_276
	s_branch .Lpeel_after_0

.Lpeel_after_0:
	s_and_b64 vcc, exec, s[12:13]
	s_cbranch_vccz .LBB0_279
	s_barrier

.LBB0_363:
	s_add_u32 s73, s40, 0x100
	s_addc_u32 s82, s41, 0
	s_mov_b32 s83, -2
	s_waitcnt lgkmcnt(0)
	s_add_u32 s40, s36, 0x100
	s_addc_u32 s41, s37, 0
	s_add_i32 s56, 0, 0x10000
	s_cmp_eq_u32 s83, 40
	s_cselect_b32 s45, s9, s41
	s_cselect_b32 s44, s8, s40
	s_cselect_b32 s43, s35, s82
	s_cselect_b32 s42, s34, s73
	s_add_i32 s57, 0, 0x14000
	v_add_u32_e32 v142, s56, v213
	v_add_u32_e32 v158, s57, v213
	ds_read_b128 v[130:133], v142
	ds_read_b128 v[134:137], v142 offset:1024
	ds_read_b128 v[138:141], v142 offset:2048
	ds_read_b128 v[142:145], v142 offset:3072
	ds_read_b128 v[146:149], v158
	ds_read_b128 v[150:153], v158 offset:1024
	ds_read_b128 v[154:157], v158 offset:2048
	ds_read_b128 v[158:161], v158 offset:3072
	v_lshl_add_u64 v[194:195], s[36:37], 0, v[184:185]
	s_add_i32 m0, s50, 0xc000
	ds_read_b128 v[162:165], v215
	ds_read_b128 v[166:169], v215 offset:1024
	ds_read_b128 v[170:173], v215 offset:2048
	ds_read_b128 v[174:177], v215 offset:3072
	ds_read_b128 v[200:203], v215 offset:4096
	ds_read_b128 v[204:207], v215 offset:5120
	ds_read_b128 v[208:211], v215 offset:6144
	ds_read_b128 v[216:219], v215 offset:7168
	global_load_lds_dwordx4 v[194:195], off
	v_lshl_add_u64 v[194:195], s[36:37], 0, v[198:199]
	s_add_i32 m0, s50, 0xe000
	s_nop 0
	global_load_lds_dwordx4 v[194:195], off
	s_waitcnt vmcnt(8)
	s_waitcnt lgkmcnt(0)
	s_barrier
	s_setprio 1
	s_waitcnt lgkmcnt(0)
	v_mfma_f32_16x16x32_bf16 v[126:129], v[130:133], v[162:165], 0
	v_mfma_f32_16x16x32_bf16 v[122:125], v[138:141], v[162:165], 0
	v_mfma_f32_16x16x32_bf16 v[108:111], v[130:133], v[170:173], 0
	v_mfma_f32_16x16x32_bf16 v[104:107], v[138:141], v[170:173], 0
	v_mfma_f32_16x16x32_bf16 v[92:95], v[130:133], v[200:203], 0
	v_mfma_f32_16x16x32_bf16 v[88:91], v[138:141], v[200:203], 0
	v_mfma_f32_16x16x32_bf16 v[76:79], v[130:133], v[208:211], 0
	v_mfma_f32_16x16x32_bf16 v[72:75], v[138:141], v[208:211], 0
	v_mfma_f32_16x16x32_bf16 v[126:129], v[134:137], v[166:169], v[126:129]
	v_mfma_f32_16x16x32_bf16 v[122:125], v[142:145], v[166:169], v[122:125]
	v_mfma_f32_16x16x32_bf16 v[108:111], v[134:137], v[174:177], v[108:111]
	v_mfma_f32_16x16x32_bf16 v[104:107], v[142:145], v[174:177], v[104:107]
	v_mfma_f32_16x16x32_bf16 v[92:95], v[134:137], v[204:207], v[92:95]
	v_mfma_f32_16x16x32_bf16 v[88:91], v[142:145], v[204:207], v[88:91]
	v_mfma_f32_16x16x32_bf16 v[76:79], v[134:137], v[216:219], v[76:79]
	v_mfma_f32_16x16x32_bf16 v[72:75], v[142:145], v[216:219], v[72:75]
	s_setprio 0
	s_setprio 1
	v_mfma_f32_16x16x32_bf16 v[118:121], v[146:149], v[162:165], 0
	v_mfma_f32_16x16x32_bf16 v[114:117], v[154:157], v[162:165], 0
	v_mfma_f32_16x16x32_bf16 v[100:103], v[146:149], v[170:173], 0
	v_mfma_f32_16x16x32_bf16 v[96:99], v[154:157], v[170:173], 0
	v_mfma_f32_16x16x32_bf16 v[84:87], v[146:149], v[200:203], 0
	v_mfma_f32_16x16x32_bf16 v[80:83], v[154:157], v[200:203], 0
	v_mfma_f32_16x16x32_bf16 v[68:71], v[146:149], v[208:211], 0
	v_mfma_f32_16x16x32_bf16 v[64:67], v[154:157], v[208:211], 0
	v_mfma_f32_16x16x32_bf16 v[118:121], v[150:153], v[166:169], v[118:121]
	v_mfma_f32_16x16x32_bf16 v[114:117], v[158:161], v[166:169], v[114:117]
	v_mfma_f32_16x16x32_bf16 v[100:103], v[150:153], v[174:177], v[100:103]
	v_mfma_f32_16x16x32_bf16 v[96:99], v[158:161], v[174:177], v[96:99]
	v_mfma_f32_16x16x32_bf16 v[84:87], v[150:153], v[204:207], v[84:87]
	v_mfma_f32_16x16x32_bf16 v[80:83], v[158:161], v[204:207], v[80:83]
	v_mfma_f32_16x16x32_bf16 v[68:71], v[150:153], v[216:219], v[68:71]
	v_mfma_f32_16x16x32_bf16 v[64:67], v[158:161], v[216:219], v[64:67]
	s_setprio 0
	s_barrier
	s_add_i32 s36, s56, s19
	v_lshl_add_u64 v[194:195], s[42:43], 0, v[112:113]
	s_mov_b32 m0, s36
	ds_read_b128 v[162:165], v215 offset:16384
	ds_read_b128 v[166:169], v215 offset:17408
	ds_read_b128 v[170:173], v215 offset:18432
	ds_read_b128 v[174:177], v215 offset:19456
	ds_read_b128 v[200:203], v215 offset:20480
	ds_read_b128 v[204:207], v215 offset:21504
	ds_read_b128 v[208:211], v215 offset:22528
	ds_read_b128 v[216:219], v215 offset:23552
	global_load_lds_dwordx4 v[194:195], off
	s_add_i32 m0, s36, 0x2000
	s_add_u32 s36, s42, 0xb0000
	v_lshl_add_u64 v[196:197], s[42:43], 0, v[182:183]
	s_addc_u32 s37, s43, 0
	s_add_i32 s56, s57, s19
	global_load_lds_dwordx4 v[196:197], off
	v_lshl_add_u64 v[220:221], s[36:37], 0, v[112:113]
	s_mov_b32 m0, s56
	v_lshl_add_u64 v[222:223], s[44:45], 0, v[180:181]
	global_load_lds_dwordx4 v[220:221], off
	v_lshl_add_u64 v[220:221], s[36:37], 0, v[182:183]
	s_add_i32 m0, s56, 0x2000
	s_nop 0
	global_load_lds_dwordx4 v[220:221], off
	v_lshl_add_u64 v[220:221], s[44:45], 0, v[178:179]
	s_mov_b32 m0, s50
	s_nop 0
	global_load_lds_dwordx4 v[220:221], off
	s_mov_b32 m0, s51
	s_nop 0
	global_load_lds_dwordx4 v[222:223], off
	s_waitcnt vmcnt(8)
	s_waitcnt lgkmcnt(0)
	s_barrier
	s_setprio 1
	s_waitcnt lgkmcnt(0)
	v_mfma_f32_16x16x32_bf16 v[60:63], v[130:133], v[162:165], 0
	v_mfma_f32_16x16x32_bf16 v[56:59], v[138:141], v[162:165], 0
	v_mfma_f32_16x16x32_bf16 v[44:47], v[130:133], v[170:173], 0
	v_mfma_f32_16x16x32_bf16 v[40:43], v[138:141], v[170:173], 0
	v_mfma_f32_16x16x32_bf16 v[28:31], v[130:133], v[200:203], 0
	v_mfma_f32_16x16x32_bf16 v[24:27], v[138:141], v[200:203], 0
	v_mfma_f32_16x16x32_bf16 v[12:15], v[130:133], v[208:211], 0
	v_mfma_f32_16x16x32_bf16 v[8:11], v[138:141], v[208:211], 0
	v_mfma_f32_16x16x32_bf16 v[60:63], v[134:137], v[166:169], v[60:63]
	v_mfma_f32_16x16x32_bf16 v[56:59], v[142:145], v[166:169], v[56:59]
	v_mfma_f32_16x16x32_bf16 v[44:47], v[134:137], v[174:177], v[44:47]
	v_mfma_f32_16x16x32_bf16 v[40:43], v[142:145], v[174:177], v[40:43]
	v_mfma_f32_16x16x32_bf16 v[28:31], v[134:137], v[204:207], v[28:31]
	v_mfma_f32_16x16x32_bf16 v[24:27], v[142:145], v[204:207], v[24:27]
	v_mfma_f32_16x16x32_bf16 v[12:15], v[134:137], v[216:219], v[12:15]
	v_mfma_f32_16x16x32_bf16 v[8:11], v[142:145], v[216:219], v[8:11]
	s_setprio 0
	s_setprio 1
	v_mfma_f32_16x16x32_bf16 v[52:55], v[146:149], v[162:165], 0
	v_mfma_f32_16x16x32_bf16 v[48:51], v[154:157], v[162:165], 0
	v_mfma_f32_16x16x32_bf16 v[36:39], v[146:149], v[170:173], 0
	v_mfma_f32_16x16x32_bf16 v[32:35], v[154:157], v[170:173], 0
	v_mfma_f32_16x16x32_bf16 v[20:23], v[146:149], v[200:203], 0
	v_mfma_f32_16x16x32_bf16 v[16:19], v[154:157], v[200:203], 0
	v_mfma_f32_16x16x32_bf16 v[4:7], v[146:149], v[208:211], 0
	v_mfma_f32_16x16x32_bf16 v[0:3], v[154:157], v[208:211], 0
	v_mfma_f32_16x16x32_bf16 v[52:55], v[150:153], v[166:169], v[52:55]
	v_mfma_f32_16x16x32_bf16 v[48:51], v[158:161], v[166:169], v[48:51]
	v_mfma_f32_16x16x32_bf16 v[36:39], v[150:153], v[174:177], v[36:39]
	v_mfma_f32_16x16x32_bf16 v[32:35], v[158:161], v[174:177], v[32:35]
	v_mfma_f32_16x16x32_bf16 v[20:23], v[150:153], v[204:207], v[20:23]
	v_mfma_f32_16x16x32_bf16 v[16:19], v[158:161], v[204:207], v[16:19]
	v_mfma_f32_16x16x32_bf16 v[4:7], v[150:153], v[216:219], v[4:7]
	v_mfma_f32_16x16x32_bf16 v[0:3], v[158:161], v[216:219], v[0:3]
	s_setprio 0
	s_barrier
	s_add_i32 s56, 0, 0x18000
	s_add_i32 s57, 0, 0x1c000
	v_add_u32_e32 v142, s56, v213
	v_add_u32_e32 v158, s57, v213
	ds_read_b128 v[130:133], v142
	ds_read_b128 v[134:137], v142 offset:1024
	ds_read_b128 v[138:141], v142 offset:2048
	ds_read_b128 v[142:145], v142 offset:3072
	ds_read_b128 v[146:149], v158
	ds_read_b128 v[150:153], v158 offset:1024
	ds_read_b128 v[154:157], v158 offset:2048
	ds_read_b128 v[158:161], v158 offset:3072
	s_add_u32 s36, s44, 0xb0000
	s_addc_u32 s37, s45, 0
	s_mov_b32 m0, s55
	v_lshl_add_u64 v[234:235], s[36:37], 0, v[178:179]
	ds_read_b128 v[162:165], v215 offset:32768
	ds_read_b128 v[166:169], v215 offset:33792
	ds_read_b128 v[170:173], v215 offset:34816
	ds_read_b128 v[174:177], v215 offset:35840
	ds_read_b128 v[200:203], v215 offset:36864
	ds_read_b128 v[204:207], v215 offset:37888
	ds_read_b128 v[208:211], v215 offset:38912
	ds_read_b128 v[216:219], v215 offset:39936
	global_load_lds_dwordx4 v[234:235], off
	v_lshl_add_u64 v[234:235], s[36:37], 0, v[180:181]
	s_mov_b32 m0, s58
	s_nop 0
	global_load_lds_dwordx4 v[234:235], off
	s_waitcnt vmcnt(8)
	s_waitcnt lgkmcnt(0)
	s_barrier
	s_setprio 1
	s_waitcnt lgkmcnt(0)
	v_mfma_f32_16x16x32_bf16 v[126:129], v[130:133], v[162:165], v[126:129]
	v_mfma_f32_16x16x32_bf16 v[122:125], v[138:141], v[162:165], v[122:125]
	v_mfma_f32_16x16x32_bf16 v[108:111], v[130:133], v[170:173], v[108:111]
	v_mfma_f32_16x16x32_bf16 v[104:107], v[138:141], v[170:173], v[104:107]
	v_mfma_f32_16x16x32_bf16 v[92:95], v[130:133], v[200:203], v[92:95]
	v_mfma_f32_16x16x32_bf16 v[88:91], v[138:141], v[200:203], v[88:91]
	v_mfma_f32_16x16x32_bf16 v[76:79], v[130:133], v[208:211], v[76:79]
	v_mfma_f32_16x16x32_bf16 v[72:75], v[138:141], v[208:211], v[72:75]
	v_mfma_f32_16x16x32_bf16 v[126:129], v[134:137], v[166:169], v[126:129]
	v_mfma_f32_16x16x32_bf16 v[122:125], v[142:145], v[166:169], v[122:125]
	v_mfma_f32_16x16x32_bf16 v[108:111], v[134:137], v[174:177], v[108:111]
	v_mfma_f32_16x16x32_bf16 v[104:107], v[142:145], v[174:177], v[104:107]
	v_mfma_f32_16x16x32_bf16 v[92:95], v[134:137], v[204:207], v[92:95]
	v_mfma_f32_16x16x32_bf16 v[88:91], v[142:145], v[204:207], v[88:91]
	v_mfma_f32_16x16x32_bf16 v[76:79], v[134:137], v[216:219], v[76:79]
	v_mfma_f32_16x16x32_bf16 v[72:75], v[142:145], v[216:219], v[72:75]
	s_setprio 0
	s_setprio 1
	v_mfma_f32_16x16x32_bf16 v[118:121], v[146:149], v[162:165], v[118:121]
	v_mfma_f32_16x16x32_bf16 v[114:117], v[154:157], v[162:165], v[114:117]
	v_mfma_f32_16x16x32_bf16 v[100:103], v[146:149], v[170:173], v[100:103]
	v_mfma_f32_16x16x32_bf16 v[96:99], v[154:157], v[170:173], v[96:99]
	v_mfma_f32_16x16x32_bf16 v[84:87], v[146:149], v[200:203], v[84:87]
	v_mfma_f32_16x16x32_bf16 v[80:83], v[154:157], v[200:203], v[80:83]
	v_mfma_f32_16x16x32_bf16 v[68:71], v[146:149], v[208:211], v[68:71]
	v_mfma_f32_16x16x32_bf16 v[64:67], v[154:157], v[208:211], v[64:67]
	v_mfma_f32_16x16x32_bf16 v[118:121], v[150:153], v[166:169], v[118:121]
	v_mfma_f32_16x16x32_bf16 v[114:117], v[158:161], v[166:169], v[114:117]
	v_mfma_f32_16x16x32_bf16 v[100:103], v[150:153], v[174:177], v[100:103]
	v_mfma_f32_16x16x32_bf16 v[96:99], v[158:161], v[174:177], v[96:99]
	v_mfma_f32_16x16x32_bf16 v[84:87], v[150:153], v[204:207], v[84:87]
	v_mfma_f32_16x16x32_bf16 v[80:83], v[158:161], v[204:207], v[80:83]
	v_mfma_f32_16x16x32_bf16 v[68:71], v[150:153], v[216:219], v[68:71]
	v_mfma_f32_16x16x32_bf16 v[64:67], v[158:161], v[216:219], v[64:67]
	s_setprio 0
	s_barrier
	s_add_i32 s36, s56, s19
	v_lshl_add_u64 v[194:195], v[194:195], 0, s[60:61]
	s_mov_b32 m0, s36
	ds_read_b128 v[162:165], v215 offset:49152
	ds_read_b128 v[166:169], v215 offset:50176
	ds_read_b128 v[170:173], v215 offset:51200
	ds_read_b128 v[174:177], v215 offset:52224
	ds_read_b128 v[200:203], v215 offset:53248
	ds_read_b128 v[204:207], v215 offset:54272
	ds_read_b128 v[208:211], v215 offset:55296
	ds_read_b128 v[216:219], v215 offset:56320
	global_load_lds_dwordx4 v[194:195], off
	s_add_i32 m0, s36, 0x2000
	s_add_u32 s36, s42, 0xb0080
	v_lshl_add_u64 v[194:195], v[196:197], 0, s[60:61]
	s_addc_u32 s37, s43, 0
	s_add_i32 s42, s57, s19
	global_load_lds_dwordx4 v[194:195], off
	v_lshl_add_u64 v[194:195], s[36:37], 0, v[112:113]
	s_mov_b32 m0, s42
	s_nop 0
	global_load_lds_dwordx4 v[194:195], off
	v_lshl_add_u64 v[194:195], s[36:37], 0, v[182:183]
	s_add_i32 m0, s42, 0x2000
	s_nop 0
	global_load_lds_dwordx4 v[194:195], off
	v_lshl_add_u64 v[194:195], v[220:221], 0, s[60:61]
	s_mov_b32 m0, s62
	s_nop 0
	global_load_lds_dwordx4 v[194:195], off
	v_lshl_add_u64 v[194:195], v[222:223], 0, s[60:61]
	s_mov_b32 m0, s63
	s_nop 0
	global_load_lds_dwordx4 v[194:195], off
	s_waitcnt vmcnt(8)
	s_waitcnt lgkmcnt(0)
	s_barrier
	s_setprio 1
	s_waitcnt lgkmcnt(0)
	v_mfma_f32_16x16x32_bf16 v[60:63], v[130:133], v[162:165], v[60:63]
	v_mfma_f32_16x16x32_bf16 v[56:59], v[138:141], v[162:165], v[56:59]
	v_mfma_f32_16x16x32_bf16 v[44:47], v[130:133], v[170:173], v[44:47]
	v_mfma_f32_16x16x32_bf16 v[40:43], v[138:141], v[170:173], v[40:43]
	v_mfma_f32_16x16x32_bf16 v[28:31], v[130:133], v[200:203], v[28:31]
	v_mfma_f32_16x16x32_bf16 v[24:27], v[138:141], v[200:203], v[24:27]
	v_mfma_f32_16x16x32_bf16 v[12:15], v[130:133], v[208:211], v[12:15]
	v_mfma_f32_16x16x32_bf16 v[8:11], v[138:141], v[208:211], v[8:11]
	v_mfma_f32_16x16x32_bf16 v[60:63], v[134:137], v[166:169], v[60:63]
	v_mfma_f32_16x16x32_bf16 v[56:59], v[142:145], v[166:169], v[56:59]
	v_mfma_f32_16x16x32_bf16 v[44:47], v[134:137], v[174:177], v[44:47]
	v_mfma_f32_16x16x32_bf16 v[40:43], v[142:145], v[174:177], v[40:43]
	v_mfma_f32_16x16x32_bf16 v[28:31], v[134:137], v[204:207], v[28:31]
	v_mfma_f32_16x16x32_bf16 v[24:27], v[142:145], v[204:207], v[24:27]
	v_mfma_f32_16x16x32_bf16 v[12:15], v[134:137], v[216:219], v[12:15]
	v_mfma_f32_16x16x32_bf16 v[8:11], v[142:145], v[216:219], v[8:11]
	s_setprio 0
	s_setprio 1
	v_mfma_f32_16x16x32_bf16 v[52:55], v[146:149], v[162:165], v[52:55]
	v_mfma_f32_16x16x32_bf16 v[48:51], v[154:157], v[162:165], v[48:51]
	v_mfma_f32_16x16x32_bf16 v[36:39], v[146:149], v[170:173], v[36:39]
	v_mfma_f32_16x16x32_bf16 v[32:35], v[154:157], v[170:173], v[32:35]
	v_mfma_f32_16x16x32_bf16 v[20:23], v[146:149], v[200:203], v[20:23]
	v_mfma_f32_16x16x32_bf16 v[16:19], v[154:157], v[200:203], v[16:19]
	v_mfma_f32_16x16x32_bf16 v[4:7], v[146:149], v[208:211], v[4:7]
	v_mfma_f32_16x16x32_bf16 v[0:3], v[154:157], v[208:211], v[0:3]
	v_mfma_f32_16x16x32_bf16 v[52:55], v[150:153], v[166:169], v[52:55]
	v_mfma_f32_16x16x32_bf16 v[48:51], v[158:161], v[166:169], v[48:51]
	v_mfma_f32_16x16x32_bf16 v[36:39], v[150:153], v[174:177], v[36:39]
	v_mfma_f32_16x16x32_bf16 v[32:35], v[158:161], v[174:177], v[32:35]
	v_mfma_f32_16x16x32_bf16 v[20:23], v[150:153], v[204:207], v[20:23]
	v_mfma_f32_16x16x32_bf16 v[16:19], v[158:161], v[204:207], v[16:19]
	v_mfma_f32_16x16x32_bf16 v[4:7], v[150:153], v[216:219], v[4:7]
	v_mfma_f32_16x16x32_bf16 v[0:3], v[158:161], v[216:219], v[0:3]
	s_setprio 0
	s_barrier
	s_add_i32 s83, s83, 2
	s_add_u32 s73, s73, 0x100
	s_addc_u32 s82, s82, 0
	s_cmp_gt_u32 s83, 41
	s_mov_b64 s[36:37], s[40:41]
	s_cbranch_scc0 .LBB0_364
	s_branch .Lpeel_after_1

.Lpeel_after_1:
	s_and_b64 vcc, exec, s[30:31]
	s_cbranch_vccz .LBB0_367
	s_barrier

.LBB0_453:
	s_ashr_i32 s97, s96, 31
	s_lshl_b64 s[10:11], s[96:97], 19
	s_add_u32 s30, s70, s10
	s_addc_u32 s31, s71, s11
	s_and_b64 s[10:11], s[6:7], exec
	s_cselect_b32 s9, s31, s51
	s_cselect_b32 s13, s30, s50
	s_ashr_i32 s95, s94, 31
	s_lshl_b64 s[10:11], s[94:95], 19
	s_add_u32 s40, s38, s10
	s_addc_u32 s41, s39, s11
	s_and_b64 s[10:11], s[6:7], exec
	s_cselect_b32 s24, s41, s45
	s_cselect_b32 s25, s40, s44
	s_add_u32 s10, s50, 0x40080
	s_addc_u32 s11, s51, 0
	s_add_u32 s90, s44, 0x100
	s_addc_u32 s95, s45, 0
	s_mov_b32 s97, -2
	s_waitcnt lgkmcnt(0)
	s_add_u32 s44, s10, 0xfffc0080
	s_addc_u32 s45, s11, -1
	s_add_i32 s56, 0, 0x10000
	s_cmp_eq_u32 s97, 12
	s_cselect_b32 s51, s9, s45
	s_cselect_b32 s50, s13, s44
	s_cselect_b32 s45, s24, s95
	s_cselect_b32 s44, s25, s90
	s_add_i32 s64, 0, 0x14000
	v_add_u32_e32 v118, s56, v205
	v_add_u32_e32 v158, s64, v205
	ds_read_b128 v[64:67], v118
	ds_read_b128 v[76:79], v118 offset:1024
	ds_read_b128 v[96:99], v118 offset:2048
	ds_read_b128 v[118:121], v118 offset:3072
	ds_read_b128 v[138:141], v158
	ds_read_b128 v[142:145], v158 offset:1024
	ds_read_b128 v[154:157], v158 offset:2048
	ds_read_b128 v[158:161], v158 offset:3072
	v_lshl_add_u64 v[194:195], s[10:11], 0, v[170:171]
	s_add_i32 m0, s83, 0xc000
	ds_read_b128 v[174:177], v207
	ds_read_b128 v[178:181], v207 offset:1024
	ds_read_b128 v[182:185], v207 offset:2048
	ds_read_b128 v[198:201], v207 offset:3072
	ds_read_b128 v[208:211], v207 offset:4096
	ds_read_b128 v[212:215], v207 offset:5120
	ds_read_b128 v[216:219], v207 offset:6144
	ds_read_b128 v[220:223], v207 offset:7168
	global_load_lds_dwordx4 v[194:195], off
	v_lshl_add_u64 v[194:195], s[10:11], 0, v[172:173]
	s_add_i32 m0, s83, 0xe000
	s_nop 0
	global_load_lds_dwordx4 v[194:195], off
	s_waitcnt vmcnt(8)
	s_waitcnt lgkmcnt(0)
	s_barrier
	s_setprio 1
	s_waitcnt lgkmcnt(0)
	v_mfma_f32_16x16x32_bf16 v[150:153], v[64:67], v[174:177], 0
	v_mfma_f32_16x16x32_bf16 v[146:149], v[96:99], v[174:177], 0
	v_mfma_f32_16x16x32_bf16 v[126:129], v[64:67], v[182:185], 0
	v_mfma_f32_16x16x32_bf16 v[122:125], v[96:99], v[182:185], 0
	v_mfma_f32_16x16x32_bf16 v[104:107], v[64:67], v[208:211], 0
	v_mfma_f32_16x16x32_bf16 v[100:103], v[96:99], v[208:211], 0
	v_mfma_f32_16x16x32_bf16 v[84:87], v[64:67], v[216:219], 0
	v_mfma_f32_16x16x32_bf16 v[80:83], v[96:99], v[216:219], 0
	v_mfma_f32_16x16x32_bf16 v[150:153], v[76:79], v[178:181], v[150:153]
	v_mfma_f32_16x16x32_bf16 v[146:149], v[118:121], v[178:181], v[146:149]
	v_mfma_f32_16x16x32_bf16 v[126:129], v[76:79], v[198:201], v[126:129]
	v_mfma_f32_16x16x32_bf16 v[122:125], v[118:121], v[198:201], v[122:125]
	v_mfma_f32_16x16x32_bf16 v[104:107], v[76:79], v[212:215], v[104:107]
	v_mfma_f32_16x16x32_bf16 v[100:103], v[118:121], v[212:215], v[100:103]
	v_mfma_f32_16x16x32_bf16 v[84:87], v[76:79], v[220:223], v[84:87]
	v_mfma_f32_16x16x32_bf16 v[80:83], v[118:121], v[220:223], v[80:83]
	s_setprio 0
	s_setprio 1
	v_mfma_f32_16x16x32_bf16 v[134:137], v[138:141], v[174:177], 0
	v_mfma_f32_16x16x32_bf16 v[130:133], v[154:157], v[174:177], 0
	v_mfma_f32_16x16x32_bf16 v[114:117], v[138:141], v[182:185], 0
	v_mfma_f32_16x16x32_bf16 v[108:111], v[154:157], v[182:185], 0
	v_mfma_f32_16x16x32_bf16 v[92:95], v[138:141], v[208:211], 0
	v_mfma_f32_16x16x32_bf16 v[88:91], v[154:157], v[208:211], 0
	v_mfma_f32_16x16x32_bf16 v[72:75], v[138:141], v[216:219], 0
	v_mfma_f32_16x16x32_bf16 v[68:71], v[154:157], v[216:219], 0
	v_mfma_f32_16x16x32_bf16 v[134:137], v[142:145], v[178:181], v[134:137]
	v_mfma_f32_16x16x32_bf16 v[130:133], v[158:161], v[178:181], v[130:133]
	v_mfma_f32_16x16x32_bf16 v[114:117], v[142:145], v[198:201], v[114:117]
	v_mfma_f32_16x16x32_bf16 v[108:111], v[158:161], v[198:201], v[108:111]
	v_mfma_f32_16x16x32_bf16 v[92:95], v[142:145], v[212:215], v[92:95]
	v_mfma_f32_16x16x32_bf16 v[88:91], v[158:161], v[212:215], v[88:91]
	v_mfma_f32_16x16x32_bf16 v[72:75], v[142:145], v[220:223], v[72:75]
	v_mfma_f32_16x16x32_bf16 v[68:71], v[158:161], v[220:223], v[68:71]
	s_setprio 0
	s_barrier
	s_add_i32 s56, s56, s82
	v_lshl_add_u64 v[194:195], s[44:45], 0, v[112:113]
	s_mov_b32 m0, s56
	ds_read_b128 v[174:177], v207 offset:16384
	ds_read_b128 v[178:181], v207 offset:17408
	ds_read_b128 v[182:185], v207 offset:18432
	ds_read_b128 v[198:201], v207 offset:19456
	ds_read_b128 v[208:211], v207 offset:20480
	ds_read_b128 v[212:215], v207 offset:21504
	ds_read_b128 v[216:219], v207 offset:22528
	ds_read_b128 v[220:223], v207 offset:23552
	global_load_lds_dwordx4 v[194:195], off
	s_add_i32 m0, s56, 0x2000
	s_add_u32 s56, s44, 0x40000
	v_lshl_add_u64 v[196:197], s[44:45], 0, v[166:167]
	s_addc_u32 s57, s45, 0
	s_add_i32 s64, s64, s82
	global_load_lds_dwordx4 v[196:197], off
	v_lshl_add_u64 v[202:203], s[56:57], 0, v[112:113]
	s_mov_b32 m0, s64
	v_lshl_add_u64 v[234:235], s[50:51], 0, v[164:165]
	global_load_lds_dwordx4 v[202:203], off
	v_lshl_add_u64 v[202:203], s[56:57], 0, v[166:167]
	s_add_i32 m0, s64, 0x2000
	s_nop 0
	global_load_lds_dwordx4 v[202:203], off
	v_lshl_add_u64 v[202:203], s[50:51], 0, v[162:163]
	s_mov_b32 m0, s83
	s_nop 0
	global_load_lds_dwordx4 v[202:203], off
	s_mov_b32 m0, s85
	s_nop 0
	global_load_lds_dwordx4 v[234:235], off
	s_waitcnt vmcnt(8)
	s_waitcnt lgkmcnt(0)
	s_barrier
	s_setprio 1
	s_waitcnt lgkmcnt(0)
	v_mfma_f32_16x16x32_bf16 v[60:63], v[64:67], v[174:177], 0
	v_mfma_f32_16x16x32_bf16 v[56:59], v[96:99], v[174:177], 0
	v_mfma_f32_16x16x32_bf16 v[44:47], v[64:67], v[182:185], 0
	v_mfma_f32_16x16x32_bf16 v[40:43], v[96:99], v[182:185], 0
	v_mfma_f32_16x16x32_bf16 v[28:31], v[64:67], v[208:211], 0
	v_mfma_f32_16x16x32_bf16 v[24:27], v[96:99], v[208:211], 0
	v_mfma_f32_16x16x32_bf16 v[12:15], v[64:67], v[216:219], 0
	v_mfma_f32_16x16x32_bf16 v[8:11], v[96:99], v[216:219], 0
	v_mfma_f32_16x16x32_bf16 v[60:63], v[76:79], v[178:181], v[60:63]
	v_mfma_f32_16x16x32_bf16 v[56:59], v[118:121], v[178:181], v[56:59]
	v_mfma_f32_16x16x32_bf16 v[44:47], v[76:79], v[198:201], v[44:47]
	v_mfma_f32_16x16x32_bf16 v[40:43], v[118:121], v[198:201], v[40:43]
	v_mfma_f32_16x16x32_bf16 v[28:31], v[76:79], v[212:215], v[28:31]
	v_mfma_f32_16x16x32_bf16 v[24:27], v[118:121], v[212:215], v[24:27]
	v_mfma_f32_16x16x32_bf16 v[12:15], v[76:79], v[220:223], v[12:15]
	v_mfma_f32_16x16x32_bf16 v[8:11], v[118:121], v[220:223], v[8:11]
	s_setprio 0
	s_setprio 1
	v_mfma_f32_16x16x32_bf16 v[52:55], v[138:141], v[174:177], 0
	v_mfma_f32_16x16x32_bf16 v[48:51], v[154:157], v[174:177], 0
	v_mfma_f32_16x16x32_bf16 v[36:39], v[138:141], v[182:185], 0
	v_mfma_f32_16x16x32_bf16 v[32:35], v[154:157], v[182:185], 0
	v_mfma_f32_16x16x32_bf16 v[20:23], v[138:141], v[208:211], 0
	v_mfma_f32_16x16x32_bf16 v[16:19], v[154:157], v[208:211], 0
	v_mfma_f32_16x16x32_bf16 v[4:7], v[138:141], v[216:219], 0
	v_mfma_f32_16x16x32_bf16 v[0:3], v[154:157], v[216:219], 0
	v_mfma_f32_16x16x32_bf16 v[52:55], v[142:145], v[178:181], v[52:55]
	v_mfma_f32_16x16x32_bf16 v[48:51], v[158:161], v[178:181], v[48:51]
	v_mfma_f32_16x16x32_bf16 v[36:39], v[142:145], v[198:201], v[36:39]
	v_mfma_f32_16x16x32_bf16 v[32:35], v[158:161], v[198:201], v[32:35]
	v_mfma_f32_16x16x32_bf16 v[20:23], v[142:145], v[212:215], v[20:23]
	v_mfma_f32_16x16x32_bf16 v[16:19], v[158:161], v[212:215], v[16:19]
	v_mfma_f32_16x16x32_bf16 v[4:7], v[142:145], v[220:223], v[4:7]
	v_mfma_f32_16x16x32_bf16 v[0:3], v[158:161], v[220:223], v[0:3]
	s_setprio 0
	s_barrier
	s_add_i32 s56, 0, 0x18000
	s_add_i32 s57, 0, 0x1c000
	v_add_u32_e32 v118, s56, v205
	v_add_u32_e32 v158, s57, v205
	ds_read_b128 v[64:67], v118
	ds_read_b128 v[76:79], v118 offset:1024
	ds_read_b128 v[96:99], v118 offset:2048
	ds_read_b128 v[118:121], v118 offset:3072
	ds_read_b128 v[138:141], v158
	ds_read_b128 v[142:145], v158 offset:1024
	ds_read_b128 v[154:157], v158 offset:2048
	ds_read_b128 v[158:161], v158 offset:3072
	s_add_u32 s50, s50, 0x40000
	s_addc_u32 s51, s51, 0
	s_mov_b32 m0, s84
	v_lshl_add_u64 v[236:237], s[50:51], 0, v[162:163]
	ds_read_b128 v[174:177], v207 offset:32768
	ds_read_b128 v[178:181], v207 offset:33792
	ds_read_b128 v[182:185], v207 offset:34816
	ds_read_b128 v[198:201], v207 offset:35840
	ds_read_b128 v[208:211], v207 offset:36864
	ds_read_b128 v[212:215], v207 offset:37888
	ds_read_b128 v[216:219], v207 offset:38912
	ds_read_b128 v[220:223], v207 offset:39936
	global_load_lds_dwordx4 v[236:237], off
	v_lshl_add_u64 v[236:237], s[50:51], 0, v[164:165]
	s_mov_b32 m0, s18
	s_nop 0
	global_load_lds_dwordx4 v[236:237], off
	s_waitcnt vmcnt(8)
	s_waitcnt lgkmcnt(0)
	s_barrier
	s_setprio 1
	s_waitcnt lgkmcnt(0)
	v_mfma_f32_16x16x32_bf16 v[150:153], v[64:67], v[174:177], v[150:153]
	v_mfma_f32_16x16x32_bf16 v[146:149], v[96:99], v[174:177], v[146:149]
	v_mfma_f32_16x16x32_bf16 v[126:129], v[64:67], v[182:185], v[126:129]
	v_mfma_f32_16x16x32_bf16 v[122:125], v[96:99], v[182:185], v[122:125]
	v_mfma_f32_16x16x32_bf16 v[104:107], v[64:67], v[208:211], v[104:107]
	v_mfma_f32_16x16x32_bf16 v[100:103], v[96:99], v[208:211], v[100:103]
	v_mfma_f32_16x16x32_bf16 v[84:87], v[64:67], v[216:219], v[84:87]
	v_mfma_f32_16x16x32_bf16 v[80:83], v[96:99], v[216:219], v[80:83]
	v_mfma_f32_16x16x32_bf16 v[150:153], v[76:79], v[178:181], v[150:153]
	v_mfma_f32_16x16x32_bf16 v[146:149], v[118:121], v[178:181], v[146:149]
	v_mfma_f32_16x16x32_bf16 v[126:129], v[76:79], v[198:201], v[126:129]
	v_mfma_f32_16x16x32_bf16 v[122:125], v[118:121], v[198:201], v[122:125]
	v_mfma_f32_16x16x32_bf16 v[104:107], v[76:79], v[212:215], v[104:107]
	v_mfma_f32_16x16x32_bf16 v[100:103], v[118:121], v[212:215], v[100:103]
	v_mfma_f32_16x16x32_bf16 v[84:87], v[76:79], v[220:223], v[84:87]
	v_mfma_f32_16x16x32_bf16 v[80:83], v[118:121], v[220:223], v[80:83]
	s_setprio 0
	s_setprio 1
	v_mfma_f32_16x16x32_bf16 v[134:137], v[138:141], v[174:177], v[134:137]
	v_mfma_f32_16x16x32_bf16 v[130:133], v[154:157], v[174:177], v[130:133]
	v_mfma_f32_16x16x32_bf16 v[114:117], v[138:141], v[182:185], v[114:117]
	v_mfma_f32_16x16x32_bf16 v[108:111], v[154:157], v[182:185], v[108:111]
	v_mfma_f32_16x16x32_bf16 v[92:95], v[138:141], v[208:211], v[92:95]
	v_mfma_f32_16x16x32_bf16 v[88:91], v[154:157], v[208:211], v[88:91]
	v_mfma_f32_16x16x32_bf16 v[72:75], v[138:141], v[216:219], v[72:75]
	v_mfma_f32_16x16x32_bf16 v[68:71], v[154:157], v[216:219], v[68:71]
	v_mfma_f32_16x16x32_bf16 v[134:137], v[142:145], v[178:181], v[134:137]
	v_mfma_f32_16x16x32_bf16 v[130:133], v[158:161], v[178:181], v[130:133]
	v_mfma_f32_16x16x32_bf16 v[114:117], v[142:145], v[198:201], v[114:117]
	v_mfma_f32_16x16x32_bf16 v[108:111], v[158:161], v[198:201], v[108:111]
	v_mfma_f32_16x16x32_bf16 v[92:95], v[142:145], v[212:215], v[92:95]
	v_mfma_f32_16x16x32_bf16 v[88:91], v[158:161], v[212:215], v[88:91]
	v_mfma_f32_16x16x32_bf16 v[72:75], v[142:145], v[220:223], v[72:75]
	v_mfma_f32_16x16x32_bf16 v[68:71], v[158:161], v[220:223], v[68:71]
	s_setprio 0
	s_barrier
	s_add_i32 s50, s56, s82
	v_lshl_add_u64 v[194:195], v[194:195], 0, s[60:61]
	s_mov_b32 m0, s50
	ds_read_b128 v[174:177], v207 offset:49152
	ds_read_b128 v[178:181], v207 offset:50176
	ds_read_b128 v[182:185], v207 offset:51200
	ds_read_b128 v[198:201], v207 offset:52224
	ds_read_b128 v[208:211], v207 offset:53248
	ds_read_b128 v[212:215], v207 offset:54272
	ds_read_b128 v[216:219], v207 offset:55296
	ds_read_b128 v[220:223], v207 offset:56320
	global_load_lds_dwordx4 v[194:195], off
	s_add_i32 m0, s50, 0x2000
	s_add_u32 s44, s44, 0x40080
	v_lshl_add_u64 v[194:195], v[196:197], 0, s[60:61]
	s_addc_u32 s45, s45, 0
	s_add_i32 s50, s57, s82
	global_load_lds_dwordx4 v[194:195], off
	v_lshl_add_u64 v[194:195], s[44:45], 0, v[112:113]
	s_mov_b32 m0, s50
	s_nop 0
	global_load_lds_dwordx4 v[194:195], off
	v_lshl_add_u64 v[194:195], s[44:45], 0, v[166:167]
	s_add_i32 m0, s50, 0x2000
	s_nop 0
	global_load_lds_dwordx4 v[194:195], off
	v_lshl_add_u64 v[194:195], v[202:203], 0, s[60:61]
	s_mov_b32 m0, s14
	s_nop 0
	global_load_lds_dwordx4 v[194:195], off
	v_lshl_add_u64 v[194:195], v[234:235], 0, s[60:61]
	s_mov_b32 m0, s15
	s_nop 0
	global_load_lds_dwordx4 v[194:195], off
	s_waitcnt vmcnt(8)
	s_waitcnt lgkmcnt(0)
	s_barrier
	s_setprio 1
	s_waitcnt lgkmcnt(0)
	v_mfma_f32_16x16x32_bf16 v[60:63], v[64:67], v[174:177], v[60:63]
	v_mfma_f32_16x16x32_bf16 v[56:59], v[96:99], v[174:177], v[56:59]
	v_mfma_f32_16x16x32_bf16 v[44:47], v[64:67], v[182:185], v[44:47]
	v_mfma_f32_16x16x32_bf16 v[40:43], v[96:99], v[182:185], v[40:43]
	v_mfma_f32_16x16x32_bf16 v[28:31], v[64:67], v[208:211], v[28:31]
	v_mfma_f32_16x16x32_bf16 v[24:27], v[96:99], v[208:211], v[24:27]
	v_mfma_f32_16x16x32_bf16 v[12:15], v[64:67], v[216:219], v[12:15]
	v_mfma_f32_16x16x32_bf16 v[8:11], v[96:99], v[216:219], v[8:11]
	v_mfma_f32_16x16x32_bf16 v[60:63], v[76:79], v[178:181], v[60:63]
	v_mfma_f32_16x16x32_bf16 v[56:59], v[118:121], v[178:181], v[56:59]
	v_mfma_f32_16x16x32_bf16 v[44:47], v[76:79], v[198:201], v[44:47]
	v_mfma_f32_16x16x32_bf16 v[40:43], v[118:121], v[198:201], v[40:43]
	v_mfma_f32_16x16x32_bf16 v[28:31], v[76:79], v[212:215], v[28:31]
	v_mfma_f32_16x16x32_bf16 v[24:27], v[118:121], v[212:215], v[24:27]
	v_mfma_f32_16x16x32_bf16 v[12:15], v[76:79], v[220:223], v[12:15]
	v_mfma_f32_16x16x32_bf16 v[8:11], v[118:121], v[220:223], v[8:11]
	s_setprio 0
	s_setprio 1
	v_mfma_f32_16x16x32_bf16 v[52:55], v[138:141], v[174:177], v[52:55]
	v_mfma_f32_16x16x32_bf16 v[48:51], v[154:157], v[174:177], v[48:51]
	v_mfma_f32_16x16x32_bf16 v[36:39], v[138:141], v[182:185], v[36:39]
	v_mfma_f32_16x16x32_bf16 v[32:35], v[154:157], v[182:185], v[32:35]
	v_mfma_f32_16x16x32_bf16 v[20:23], v[138:141], v[208:211], v[20:23]
	v_mfma_f32_16x16x32_bf16 v[16:19], v[154:157], v[208:211], v[16:19]
	v_mfma_f32_16x16x32_bf16 v[4:7], v[138:141], v[216:219], v[4:7]
	v_mfma_f32_16x16x32_bf16 v[0:3], v[154:157], v[216:219], v[0:3]
	v_mfma_f32_16x16x32_bf16 v[52:55], v[142:145], v[178:181], v[52:55]
	v_mfma_f32_16x16x32_bf16 v[48:51], v[158:161], v[178:181], v[48:51]
	v_mfma_f32_16x16x32_bf16 v[36:39], v[142:145], v[198:201], v[36:39]
	v_mfma_f32_16x16x32_bf16 v[32:35], v[158:161], v[198:201], v[32:35]
	v_mfma_f32_16x16x32_bf16 v[20:23], v[142:145], v[212:215], v[20:23]
	v_mfma_f32_16x16x32_bf16 v[16:19], v[158:161], v[212:215], v[16:19]
	v_mfma_f32_16x16x32_bf16 v[4:7], v[142:145], v[220:223], v[4:7]
	v_mfma_f32_16x16x32_bf16 v[0:3], v[158:161], v[220:223], v[0:3]
	s_setprio 0
	s_barrier
	s_add_i32 s97, s97, 2
	s_add_u32 s10, s10, 0x100
	s_addc_u32 s11, s11, 0
	s_add_u32 s90, s90, 0x100
	s_addc_u32 s95, s95, 0
	s_cmp_gt_u32 s97, 13
	s_cbranch_scc0 .LBB0_454
	s_branch .Lpeel_after_2

.Lpeel_after_2:
	s_and_b64 vcc, exec, s[62:63]
	s_cbranch_vccz .LBB0_457
	s_barrier

.LBB0_598:
	s_ashr_i32 s19, s18, 31
	s_lshl_b64 s[20:21], s[18:19], 19
	s_add_u32 s20, s24, s20
	s_addc_u32 s21, s25, s21
	s_and_b64 s[22:23], s[30:31], exec
	s_cselect_b32 s19, s21, s37
	s_cselect_b32 s62, s20, s36
	s_ashr_i32 s13, s12, 31
	s_lshl_b64 s[22:23], s[12:13], 19
	s_add_u32 s22, s38, s22
	s_addc_u32 s23, s39, s23
	s_and_b64 s[42:43], s[30:31], exec
	s_cselect_b32 s13, s23, s41
	s_cselect_b32 s63, s22, s40
	s_add_u32 s36, s36, 0x40080
	s_addc_u32 s37, s37, 0
	s_add_u32 s69, s40, 0x100
	s_addc_u32 s70, s41, 0
	s_mov_b32 s71, -2
	s_add_u32 s40, s36, 0xfffc0080
	s_addc_u32 s41, s37, -1
	s_add_i32 s56, 0, 0x10000
	s_cmp_eq_u32 s71, 12
	s_cselect_b32 s43, s19, s41
	s_cselect_b32 s42, s62, s40
	s_cselect_b32 s41, s13, s70
	s_cselect_b32 s40, s63, s69
	s_add_i32 s64, 0, 0x14000
	v_add_u32_e32 v156, s56, v149
	v_add_u32_e32 v172, s64, v149
	ds_read_b128 v[140:143], v156
	ds_read_b128 v[144:147], v156 offset:1024
	ds_read_b128 v[152:155], v156 offset:2048
	ds_read_b128 v[156:159], v156 offset:3072
	ds_read_b128 v[160:163], v172
	ds_read_b128 v[164:167], v172 offset:1024
	ds_read_b128 v[168:171], v172 offset:2048
	ds_read_b128 v[172:175], v172 offset:3072
	v_lshl_add_u64 v[184:185], s[36:37], 0, v[136:137]
	s_add_i32 m0, s45, 0xc000
	ds_read_b128 v[176:179], v151
	ds_read_b128 v[180:183], v151 offset:1024
	ds_read_b128 v[198:201], v151 offset:2048
	ds_read_b128 v[202:205], v151 offset:3072
	ds_read_b128 v[206:209], v151 offset:4096
	ds_read_b128 v[210:213], v151 offset:5120
	ds_read_b128 v[214:217], v151 offset:6144
	ds_read_b128 v[218:221], v151 offset:7168
	global_load_lds_dwordx4 v[184:185], off
	v_lshl_add_u64 v[184:185], s[36:37], 0, v[138:139]
	s_add_i32 m0, s45, 0xe000
	s_nop 0
	global_load_lds_dwordx4 v[184:185], off
	s_waitcnt vmcnt(8)
	s_waitcnt lgkmcnt(0)
	s_barrier
	s_setprio 1
	s_waitcnt lgkmcnt(0)
	v_mfma_f32_16x16x32_bf16 v[126:129], v[140:143], v[176:179], 0
	v_mfma_f32_16x16x32_bf16 v[122:125], v[152:155], v[176:179], 0
	v_mfma_f32_16x16x32_bf16 v[108:111], v[140:143], v[198:201], 0
	v_mfma_f32_16x16x32_bf16 v[104:107], v[152:155], v[198:201], 0
	v_mfma_f32_16x16x32_bf16 v[92:95], v[140:143], v[206:209], 0
	v_mfma_f32_16x16x32_bf16 v[88:91], v[152:155], v[206:209], 0
	v_mfma_f32_16x16x32_bf16 v[76:79], v[140:143], v[214:217], 0
	v_mfma_f32_16x16x32_bf16 v[72:75], v[152:155], v[214:217], 0
	v_mfma_f32_16x16x32_bf16 v[126:129], v[144:147], v[180:183], v[126:129]
	v_mfma_f32_16x16x32_bf16 v[122:125], v[156:159], v[180:183], v[122:125]
	v_mfma_f32_16x16x32_bf16 v[108:111], v[144:147], v[202:205], v[108:111]
	v_mfma_f32_16x16x32_bf16 v[104:107], v[156:159], v[202:205], v[104:107]
	v_mfma_f32_16x16x32_bf16 v[92:95], v[144:147], v[210:213], v[92:95]
	v_mfma_f32_16x16x32_bf16 v[88:91], v[156:159], v[210:213], v[88:91]
	v_mfma_f32_16x16x32_bf16 v[76:79], v[144:147], v[218:221], v[76:79]
	v_mfma_f32_16x16x32_bf16 v[72:75], v[156:159], v[218:221], v[72:75]
	s_setprio 0
	s_setprio 1
	v_mfma_f32_16x16x32_bf16 v[118:121], v[160:163], v[176:179], 0
	v_mfma_f32_16x16x32_bf16 v[114:117], v[168:171], v[176:179], 0
	v_mfma_f32_16x16x32_bf16 v[100:103], v[160:163], v[198:201], 0
	v_mfma_f32_16x16x32_bf16 v[96:99], v[168:171], v[198:201], 0
	v_mfma_f32_16x16x32_bf16 v[84:87], v[160:163], v[206:209], 0
	v_mfma_f32_16x16x32_bf16 v[80:83], v[168:171], v[206:209], 0
	v_mfma_f32_16x16x32_bf16 v[68:71], v[160:163], v[214:217], 0
	v_mfma_f32_16x16x32_bf16 v[64:67], v[168:171], v[214:217], 0
	v_mfma_f32_16x16x32_bf16 v[118:121], v[164:167], v[180:183], v[118:121]
	v_mfma_f32_16x16x32_bf16 v[114:117], v[172:175], v[180:183], v[114:117]
	v_mfma_f32_16x16x32_bf16 v[100:103], v[164:167], v[202:205], v[100:103]
	v_mfma_f32_16x16x32_bf16 v[96:99], v[172:175], v[202:205], v[96:99]
	v_mfma_f32_16x16x32_bf16 v[84:87], v[164:167], v[210:213], v[84:87]
	v_mfma_f32_16x16x32_bf16 v[80:83], v[172:175], v[210:213], v[80:83]
	v_mfma_f32_16x16x32_bf16 v[68:71], v[164:167], v[218:221], v[68:71]
	v_mfma_f32_16x16x32_bf16 v[64:67], v[172:175], v[218:221], v[64:67]
	s_setprio 0
	s_barrier
	s_add_i32 s56, s56, s44
	v_lshl_add_u64 v[184:185], s[40:41], 0, v[112:113]
	s_mov_b32 m0, s56
	ds_read_b128 v[176:179], v151 offset:16384
	ds_read_b128 v[180:183], v151 offset:17408
	ds_read_b128 v[198:201], v151 offset:18432
	ds_read_b128 v[202:205], v151 offset:19456
	ds_read_b128 v[206:209], v151 offset:20480
	ds_read_b128 v[210:213], v151 offset:21504
	ds_read_b128 v[214:217], v151 offset:22528
	ds_read_b128 v[218:221], v151 offset:23552
	global_load_lds_dwordx4 v[184:185], off
	s_add_i32 m0, s56, 0x2000
	s_add_u32 s56, s40, 0x40000
	v_lshl_add_u64 v[194:195], s[40:41], 0, v[134:135]
	s_addc_u32 s57, s41, 0
	s_add_i32 s64, s64, s44
	global_load_lds_dwordx4 v[194:195], off
	v_lshl_add_u64 v[196:197], s[56:57], 0, v[112:113]
	s_mov_b32 m0, s64
	v_lshl_add_u64 v[222:223], s[42:43], 0, v[132:133]
	global_load_lds_dwordx4 v[196:197], off
	v_lshl_add_u64 v[196:197], s[56:57], 0, v[134:135]
	s_add_i32 m0, s64, 0x2000
	s_nop 0
	global_load_lds_dwordx4 v[196:197], off
	v_lshl_add_u64 v[196:197], s[42:43], 0, v[130:131]
	s_mov_b32 m0, s45
	s_nop 0
	global_load_lds_dwordx4 v[196:197], off
	s_mov_b32 m0, s47
	s_nop 0
	global_load_lds_dwordx4 v[222:223], off
	s_waitcnt vmcnt(8)
	s_waitcnt lgkmcnt(0)
	s_barrier
	s_setprio 1
	s_waitcnt lgkmcnt(0)
	v_mfma_f32_16x16x32_bf16 v[60:63], v[140:143], v[176:179], 0
	v_mfma_f32_16x16x32_bf16 v[56:59], v[152:155], v[176:179], 0
	v_mfma_f32_16x16x32_bf16 v[44:47], v[140:143], v[198:201], 0
	v_mfma_f32_16x16x32_bf16 v[40:43], v[152:155], v[198:201], 0
	v_mfma_f32_16x16x32_bf16 v[28:31], v[140:143], v[206:209], 0
	v_mfma_f32_16x16x32_bf16 v[24:27], v[152:155], v[206:209], 0
	v_mfma_f32_16x16x32_bf16 v[12:15], v[140:143], v[214:217], 0
	v_mfma_f32_16x16x32_bf16 v[8:11], v[152:155], v[214:217], 0
	v_mfma_f32_16x16x32_bf16 v[60:63], v[144:147], v[180:183], v[60:63]
	v_mfma_f32_16x16x32_bf16 v[56:59], v[156:159], v[180:183], v[56:59]
	v_mfma_f32_16x16x32_bf16 v[44:47], v[144:147], v[202:205], v[44:47]
	v_mfma_f32_16x16x32_bf16 v[40:43], v[156:159], v[202:205], v[40:43]
	v_mfma_f32_16x16x32_bf16 v[28:31], v[144:147], v[210:213], v[28:31]
	v_mfma_f32_16x16x32_bf16 v[24:27], v[156:159], v[210:213], v[24:27]
	v_mfma_f32_16x16x32_bf16 v[12:15], v[144:147], v[218:221], v[12:15]
	v_mfma_f32_16x16x32_bf16 v[8:11], v[156:159], v[218:221], v[8:11]
	s_setprio 0
	s_setprio 1
	v_mfma_f32_16x16x32_bf16 v[52:55], v[160:163], v[176:179], 0
	v_mfma_f32_16x16x32_bf16 v[48:51], v[168:171], v[176:179], 0
	v_mfma_f32_16x16x32_bf16 v[36:39], v[160:163], v[198:201], 0
	v_mfma_f32_16x16x32_bf16 v[32:35], v[168:171], v[198:201], 0
	v_mfma_f32_16x16x32_bf16 v[20:23], v[160:163], v[206:209], 0
	v_mfma_f32_16x16x32_bf16 v[16:19], v[168:171], v[206:209], 0
	v_mfma_f32_16x16x32_bf16 v[4:7], v[160:163], v[214:217], 0
	v_mfma_f32_16x16x32_bf16 v[0:3], v[168:171], v[214:217], 0
	v_mfma_f32_16x16x32_bf16 v[52:55], v[164:167], v[180:183], v[52:55]
	v_mfma_f32_16x16x32_bf16 v[48:51], v[172:175], v[180:183], v[48:51]
	v_mfma_f32_16x16x32_bf16 v[36:39], v[164:167], v[202:205], v[36:39]
	v_mfma_f32_16x16x32_bf16 v[32:35], v[172:175], v[202:205], v[32:35]
	v_mfma_f32_16x16x32_bf16 v[20:23], v[164:167], v[210:213], v[20:23]
	v_mfma_f32_16x16x32_bf16 v[16:19], v[172:175], v[210:213], v[16:19]
	v_mfma_f32_16x16x32_bf16 v[4:7], v[164:167], v[218:221], v[4:7]
	v_mfma_f32_16x16x32_bf16 v[0:3], v[172:175], v[218:221], v[0:3]
	s_setprio 0
	s_barrier
	s_add_i32 s56, 0, 0x18000
	s_add_i32 s57, 0, 0x1c000
	v_add_u32_e32 v156, s56, v149
	v_add_u32_e32 v172, s57, v149
	ds_read_b128 v[140:143], v156
	ds_read_b128 v[144:147], v156 offset:1024
	ds_read_b128 v[152:155], v156 offset:2048
	ds_read_b128 v[156:159], v156 offset:3072
	ds_read_b128 v[160:163], v172
	ds_read_b128 v[164:167], v172 offset:1024
	ds_read_b128 v[168:171], v172 offset:2048
	ds_read_b128 v[172:175], v172 offset:3072
	s_add_u32 s42, s42, 0x40000
	s_addc_u32 s43, s43, 0
	s_mov_b32 m0, s50
	v_lshl_add_u64 v[234:235], s[42:43], 0, v[130:131]
	ds_read_b128 v[176:179], v151 offset:32768
	ds_read_b128 v[180:183], v151 offset:33792
	ds_read_b128 v[198:201], v151 offset:34816
	ds_read_b128 v[202:205], v151 offset:35840
	ds_read_b128 v[206:209], v151 offset:36864
	ds_read_b128 v[210:213], v151 offset:37888
	ds_read_b128 v[214:217], v151 offset:38912
	ds_read_b128 v[218:221], v151 offset:39936
	global_load_lds_dwordx4 v[234:235], off
	v_lshl_add_u64 v[234:235], s[42:43], 0, v[132:133]
	s_mov_b32 m0, s51
	s_nop 0
	global_load_lds_dwordx4 v[234:235], off
	s_waitcnt vmcnt(8)
	s_waitcnt lgkmcnt(0)
	s_barrier
	s_setprio 1
	s_waitcnt lgkmcnt(0)
	v_mfma_f32_16x16x32_bf16 v[126:129], v[140:143], v[176:179], v[126:129]
	v_mfma_f32_16x16x32_bf16 v[122:125], v[152:155], v[176:179], v[122:125]
	v_mfma_f32_16x16x32_bf16 v[108:111], v[140:143], v[198:201], v[108:111]
	v_mfma_f32_16x16x32_bf16 v[104:107], v[152:155], v[198:201], v[104:107]
	v_mfma_f32_16x16x32_bf16 v[92:95], v[140:143], v[206:209], v[92:95]
	v_mfma_f32_16x16x32_bf16 v[88:91], v[152:155], v[206:209], v[88:91]
	v_mfma_f32_16x16x32_bf16 v[76:79], v[140:143], v[214:217], v[76:79]
	v_mfma_f32_16x16x32_bf16 v[72:75], v[152:155], v[214:217], v[72:75]
	v_mfma_f32_16x16x32_bf16 v[126:129], v[144:147], v[180:183], v[126:129]
	v_mfma_f32_16x16x32_bf16 v[122:125], v[156:159], v[180:183], v[122:125]
	v_mfma_f32_16x16x32_bf16 v[108:111], v[144:147], v[202:205], v[108:111]
	v_mfma_f32_16x16x32_bf16 v[104:107], v[156:159], v[202:205], v[104:107]
	v_mfma_f32_16x16x32_bf16 v[92:95], v[144:147], v[210:213], v[92:95]
	v_mfma_f32_16x16x32_bf16 v[88:91], v[156:159], v[210:213], v[88:91]
	v_mfma_f32_16x16x32_bf16 v[76:79], v[144:147], v[218:221], v[76:79]
	v_mfma_f32_16x16x32_bf16 v[72:75], v[156:159], v[218:221], v[72:75]
	s_setprio 0
	s_setprio 1
	v_mfma_f32_16x16x32_bf16 v[118:121], v[160:163], v[176:179], v[118:121]
	v_mfma_f32_16x16x32_bf16 v[114:117], v[168:171], v[176:179], v[114:117]
	v_mfma_f32_16x16x32_bf16 v[100:103], v[160:163], v[198:201], v[100:103]
	v_mfma_f32_16x16x32_bf16 v[96:99], v[168:171], v[198:201], v[96:99]
	v_mfma_f32_16x16x32_bf16 v[84:87], v[160:163], v[206:209], v[84:87]
	v_mfma_f32_16x16x32_bf16 v[80:83], v[168:171], v[206:209], v[80:83]
	v_mfma_f32_16x16x32_bf16 v[68:71], v[160:163], v[214:217], v[68:71]
	v_mfma_f32_16x16x32_bf16 v[64:67], v[168:171], v[214:217], v[64:67]
	v_mfma_f32_16x16x32_bf16 v[118:121], v[164:167], v[180:183], v[118:121]
	v_mfma_f32_16x16x32_bf16 v[114:117], v[172:175], v[180:183], v[114:117]
	v_mfma_f32_16x16x32_bf16 v[100:103], v[164:167], v[202:205], v[100:103]
	v_mfma_f32_16x16x32_bf16 v[96:99], v[172:175], v[202:205], v[96:99]
	v_mfma_f32_16x16x32_bf16 v[84:87], v[164:167], v[210:213], v[84:87]
	v_mfma_f32_16x16x32_bf16 v[80:83], v[172:175], v[210:213], v[80:83]
	v_mfma_f32_16x16x32_bf16 v[68:71], v[164:167], v[218:221], v[68:71]
	v_mfma_f32_16x16x32_bf16 v[64:67], v[172:175], v[218:221], v[64:67]
	s_setprio 0
	s_barrier
	s_add_i32 s42, s56, s44
	v_lshl_add_u64 v[184:185], v[184:185], 0, s[60:61]
	s_mov_b32 m0, s42
	ds_read_b128 v[176:179], v151 offset:49152
	ds_read_b128 v[180:183], v151 offset:50176
	ds_read_b128 v[198:201], v151 offset:51200
	ds_read_b128 v[202:205], v151 offset:52224
	ds_read_b128 v[206:209], v151 offset:53248
	ds_read_b128 v[210:213], v151 offset:54272
	ds_read_b128 v[214:217], v151 offset:55296
	ds_read_b128 v[218:221], v151 offset:56320
	global_load_lds_dwordx4 v[184:185], off
	s_add_i32 m0, s42, 0x2000
	s_add_u32 s40, s40, 0x40080
	v_lshl_add_u64 v[184:185], v[194:195], 0, s[60:61]
	s_addc_u32 s41, s41, 0
	s_add_i32 s42, s57, s44
	global_load_lds_dwordx4 v[184:185], off
	v_lshl_add_u64 v[184:185], s[40:41], 0, v[112:113]
	s_mov_b32 m0, s42
	s_nop 0
	global_load_lds_dwordx4 v[184:185], off
	v_lshl_add_u64 v[184:185], s[40:41], 0, v[134:135]
	s_add_i32 m0, s42, 0x2000
	s_nop 0
	global_load_lds_dwordx4 v[184:185], off
	v_lshl_add_u64 v[184:185], v[196:197], 0, s[60:61]
	s_mov_b32 m0, s55
	s_nop 0
	global_load_lds_dwordx4 v[184:185], off
	v_lshl_add_u64 v[184:185], v[222:223], 0, s[60:61]
	s_mov_b32 m0, s58
	s_nop 0
	global_load_lds_dwordx4 v[184:185], off
	s_waitcnt vmcnt(8)
	s_waitcnt lgkmcnt(0)
	s_barrier
	s_setprio 1
	s_waitcnt lgkmcnt(0)
	v_mfma_f32_16x16x32_bf16 v[60:63], v[140:143], v[176:179], v[60:63]
	v_mfma_f32_16x16x32_bf16 v[56:59], v[152:155], v[176:179], v[56:59]
	v_mfma_f32_16x16x32_bf16 v[44:47], v[140:143], v[198:201], v[44:47]
	v_mfma_f32_16x16x32_bf16 v[40:43], v[152:155], v[198:201], v[40:43]
	v_mfma_f32_16x16x32_bf16 v[28:31], v[140:143], v[206:209], v[28:31]
	v_mfma_f32_16x16x32_bf16 v[24:27], v[152:155], v[206:209], v[24:27]
	v_mfma_f32_16x16x32_bf16 v[12:15], v[140:143], v[214:217], v[12:15]
	v_mfma_f32_16x16x32_bf16 v[8:11], v[152:155], v[214:217], v[8:11]
	v_mfma_f32_16x16x32_bf16 v[60:63], v[144:147], v[180:183], v[60:63]
	v_mfma_f32_16x16x32_bf16 v[56:59], v[156:159], v[180:183], v[56:59]
	v_mfma_f32_16x16x32_bf16 v[44:47], v[144:147], v[202:205], v[44:47]
	v_mfma_f32_16x16x32_bf16 v[40:43], v[156:159], v[202:205], v[40:43]
	v_mfma_f32_16x16x32_bf16 v[28:31], v[144:147], v[210:213], v[28:31]
	v_mfma_f32_16x16x32_bf16 v[24:27], v[156:159], v[210:213], v[24:27]
	v_mfma_f32_16x16x32_bf16 v[12:15], v[144:147], v[218:221], v[12:15]
	v_mfma_f32_16x16x32_bf16 v[8:11], v[156:159], v[218:221], v[8:11]
	s_setprio 0
	s_setprio 1
	v_mfma_f32_16x16x32_bf16 v[52:55], v[160:163], v[176:179], v[52:55]
	v_mfma_f32_16x16x32_bf16 v[48:51], v[168:171], v[176:179], v[48:51]
	v_mfma_f32_16x16x32_bf16 v[36:39], v[160:163], v[198:201], v[36:39]
	v_mfma_f32_16x16x32_bf16 v[32:35], v[168:171], v[198:201], v[32:35]
	v_mfma_f32_16x16x32_bf16 v[20:23], v[160:163], v[206:209], v[20:23]
	v_mfma_f32_16x16x32_bf16 v[16:19], v[168:171], v[206:209], v[16:19]
	v_mfma_f32_16x16x32_bf16 v[4:7], v[160:163], v[214:217], v[4:7]
	v_mfma_f32_16x16x32_bf16 v[0:3], v[168:171], v[214:217], v[0:3]
	v_mfma_f32_16x16x32_bf16 v[52:55], v[164:167], v[180:183], v[52:55]
	v_mfma_f32_16x16x32_bf16 v[48:51], v[172:175], v[180:183], v[48:51]
	v_mfma_f32_16x16x32_bf16 v[36:39], v[164:167], v[202:205], v[36:39]
	v_mfma_f32_16x16x32_bf16 v[32:35], v[172:175], v[202:205], v[32:35]
	v_mfma_f32_16x16x32_bf16 v[20:23], v[164:167], v[210:213], v[20:23]
	v_mfma_f32_16x16x32_bf16 v[16:19], v[172:175], v[210:213], v[16:19]
	v_mfma_f32_16x16x32_bf16 v[4:7], v[164:167], v[218:221], v[4:7]
	v_mfma_f32_16x16x32_bf16 v[0:3], v[172:175], v[218:221], v[0:3]
	s_setprio 0
	s_barrier
	s_add_i32 s71, s71, 2
	s_add_u32 s36, s36, 0x100
	s_addc_u32 s37, s37, 0
	s_add_u32 s69, s69, 0x100
	s_addc_u32 s70, s70, 0
	s_cmp_gt_u32 s71, 13
	s_cbranch_scc0 .LBB0_599
	s_branch .Lpeel_after_3

.Lpeel_after_3:
	v_readlane_b32 s62, v255, 36
	s_and_b64 vcc, exec, s[10:11]
	s_movk_i32 s64, 0x900
	s_movk_i32 s69, 0xc00
	s_movk_i32 s70, 0x5f
	s_movk_i32 s71, 0xfe20
	v_readlane_b32 s63, v255, 37
	s_cbranch_vccz .LBB0_602
	s_barrier

.LBB0_730:
	s_ashr_i32 s23, s22, 31
	s_lshl_b64 s[34:35], s[22:23], 19
	s_add_u32 s34, s15, s34
	s_addc_u32 s35, s24, s35
	s_and_b64 s[6:7], s[6:7], exec
	s_cselect_b32 s9, s35, s41
	s_cselect_b32 s23, s34, s40
	s_add_u32 s6, s40, 0x40080
	s_addc_u32 s7, s41, 0
	s_add_u32 s62, s36, 0x100
	s_addc_u32 s63, s37, 0
	s_mov_b32 s69, -2
	s_add_u32 s36, s6, 0xfffc0080
	s_addc_u32 s37, s7, -1
	s_add_i32 s56, 0, 0x10000
	s_cmp_eq_u32 s69, 2
	s_cselect_b32 s41, s9, s37
	s_cselect_b32 s40, s23, s36
	v_add_u32_e32 v144, s56, v147
	s_cselect_b32 s37, s31, s63
	s_cselect_b32 s36, s30, s62
	s_add_i32 s64, 0, 0x14000
	ds_read_b128 v[140:143], v144
	ds_read_b128 v[150:153], v144 offset:1024
	ds_read_b128 v[154:157], v144 offset:2048
	ds_read_b128 v[158:161], v144 offset:3072
	v_add_u32_e32 v144, s64, v147
	ds_read_b128 v[162:165], v144
	ds_read_b128 v[166:169], v144 offset:1024
	ds_read_b128 v[170:173], v144 offset:2048
	ds_read_b128 v[174:177], v144 offset:3072
	v_lshl_add_u64 v[144:145], s[6:7], 0, v[136:137]
	s_add_i32 m0, s42, 0xc000
	ds_read_b128 v[178:181], v149
	ds_read_b128 v[182:185], v149 offset:1024
	ds_read_b128 v[198:201], v149 offset:2048
	ds_read_b128 v[202:205], v149 offset:3072
	ds_read_b128 v[206:209], v149 offset:4096
	ds_read_b128 v[210:213], v149 offset:5120
	ds_read_b128 v[214:217], v149 offset:6144
	ds_read_b128 v[218:221], v149 offset:7168
	global_load_lds_dwordx4 v[144:145], off
	v_lshl_add_u64 v[144:145], s[6:7], 0, v[138:139]
	s_add_i32 m0, s42, 0xe000
	s_nop 0
	global_load_lds_dwordx4 v[144:145], off
	s_waitcnt vmcnt(8)
	s_waitcnt lgkmcnt(0)
	s_barrier
	s_setprio 1
	s_waitcnt lgkmcnt(0)
	v_mfma_f32_16x16x32_bf16 v[126:129], v[140:143], v[178:181], 0
	v_mfma_f32_16x16x32_bf16 v[122:125], v[154:157], v[178:181], 0
	v_mfma_f32_16x16x32_bf16 v[108:111], v[140:143], v[198:201], 0
	v_mfma_f32_16x16x32_bf16 v[104:107], v[154:157], v[198:201], 0
	v_mfma_f32_16x16x32_bf16 v[92:95], v[140:143], v[206:209], 0
	v_mfma_f32_16x16x32_bf16 v[88:91], v[154:157], v[206:209], 0
	v_mfma_f32_16x16x32_bf16 v[76:79], v[140:143], v[214:217], 0
	v_mfma_f32_16x16x32_bf16 v[72:75], v[154:157], v[214:217], 0
	v_mfma_f32_16x16x32_bf16 v[126:129], v[150:153], v[182:185], v[126:129]
	v_mfma_f32_16x16x32_bf16 v[122:125], v[158:161], v[182:185], v[122:125]
	v_mfma_f32_16x16x32_bf16 v[108:111], v[150:153], v[202:205], v[108:111]
	v_mfma_f32_16x16x32_bf16 v[104:107], v[158:161], v[202:205], v[104:107]
	v_mfma_f32_16x16x32_bf16 v[92:95], v[150:153], v[210:213], v[92:95]
	v_mfma_f32_16x16x32_bf16 v[88:91], v[158:161], v[210:213], v[88:91]
	v_mfma_f32_16x16x32_bf16 v[76:79], v[150:153], v[218:221], v[76:79]
	v_mfma_f32_16x16x32_bf16 v[72:75], v[158:161], v[218:221], v[72:75]
	s_setprio 0
	s_setprio 1
	v_mfma_f32_16x16x32_bf16 v[118:121], v[162:165], v[178:181], 0
	v_mfma_f32_16x16x32_bf16 v[114:117], v[170:173], v[178:181], 0
	v_mfma_f32_16x16x32_bf16 v[100:103], v[162:165], v[198:201], 0
	v_mfma_f32_16x16x32_bf16 v[96:99], v[170:173], v[198:201], 0
	v_mfma_f32_16x16x32_bf16 v[84:87], v[162:165], v[206:209], 0
	v_mfma_f32_16x16x32_bf16 v[80:83], v[170:173], v[206:209], 0
	v_mfma_f32_16x16x32_bf16 v[68:71], v[162:165], v[214:217], 0
	v_mfma_f32_16x16x32_bf16 v[64:67], v[170:173], v[214:217], 0
	v_mfma_f32_16x16x32_bf16 v[118:121], v[166:169], v[182:185], v[118:121]
	v_mfma_f32_16x16x32_bf16 v[114:117], v[174:177], v[182:185], v[114:117]
	v_mfma_f32_16x16x32_bf16 v[100:103], v[166:169], v[202:205], v[100:103]
	v_mfma_f32_16x16x32_bf16 v[96:99], v[174:177], v[202:205], v[96:99]
	v_mfma_f32_16x16x32_bf16 v[84:87], v[166:169], v[210:213], v[84:87]
	v_mfma_f32_16x16x32_bf16 v[80:83], v[174:177], v[210:213], v[80:83]
	v_mfma_f32_16x16x32_bf16 v[68:71], v[166:169], v[218:221], v[68:71]
	v_mfma_f32_16x16x32_bf16 v[64:67], v[174:177], v[218:221], v[64:67]
	s_setprio 0
	s_barrier
	s_add_i32 s56, s56, s39
	v_lshl_add_u64 v[144:145], s[36:37], 0, v[112:113]
	s_mov_b32 m0, s56
	ds_read_b128 v[178:181], v149 offset:16384
	ds_read_b128 v[182:185], v149 offset:17408
	ds_read_b128 v[198:201], v149 offset:18432
	ds_read_b128 v[202:205], v149 offset:19456
	ds_read_b128 v[206:209], v149 offset:20480
	ds_read_b128 v[210:213], v149 offset:21504
	ds_read_b128 v[214:217], v149 offset:22528
	ds_read_b128 v[218:221], v149 offset:23552
	global_load_lds_dwordx4 v[144:145], off
	s_add_i32 m0, s56, 0x2000
	s_add_u32 s56, s36, 0x18000
	v_lshl_add_u64 v[194:195], s[36:37], 0, v[134:135]
	s_addc_u32 s57, s37, 0
	s_add_i32 s64, s64, s39
	global_load_lds_dwordx4 v[194:195], off
	v_lshl_add_u64 v[196:197], s[56:57], 0, v[112:113]
	s_mov_b32 m0, s64
	v_lshl_add_u64 v[222:223], s[40:41], 0, v[132:133]
	global_load_lds_dwordx4 v[196:197], off
	v_lshl_add_u64 v[196:197], s[56:57], 0, v[134:135]
	s_add_i32 m0, s64, 0x2000
	s_nop 0
	global_load_lds_dwordx4 v[196:197], off
	v_lshl_add_u64 v[196:197], s[40:41], 0, v[130:131]
	s_mov_b32 m0, s42
	s_nop 0
	global_load_lds_dwordx4 v[196:197], off
	s_mov_b32 m0, s43
	s_nop 0
	global_load_lds_dwordx4 v[222:223], off
	s_waitcnt vmcnt(8)
	s_waitcnt lgkmcnt(0)
	s_barrier
	s_setprio 1
	s_waitcnt lgkmcnt(0)
	v_mfma_f32_16x16x32_bf16 v[60:63], v[140:143], v[178:181], 0
	v_mfma_f32_16x16x32_bf16 v[56:59], v[154:157], v[178:181], 0
	v_mfma_f32_16x16x32_bf16 v[44:47], v[140:143], v[198:201], 0
	v_mfma_f32_16x16x32_bf16 v[40:43], v[154:157], v[198:201], 0
	v_mfma_f32_16x16x32_bf16 v[28:31], v[140:143], v[206:209], 0
	v_mfma_f32_16x16x32_bf16 v[24:27], v[154:157], v[206:209], 0
	v_mfma_f32_16x16x32_bf16 v[12:15], v[140:143], v[214:217], 0
	v_mfma_f32_16x16x32_bf16 v[8:11], v[154:157], v[214:217], 0
	v_mfma_f32_16x16x32_bf16 v[60:63], v[150:153], v[182:185], v[60:63]
	v_mfma_f32_16x16x32_bf16 v[56:59], v[158:161], v[182:185], v[56:59]
	v_mfma_f32_16x16x32_bf16 v[44:47], v[150:153], v[202:205], v[44:47]
	v_mfma_f32_16x16x32_bf16 v[40:43], v[158:161], v[202:205], v[40:43]
	v_mfma_f32_16x16x32_bf16 v[28:31], v[150:153], v[210:213], v[28:31]
	v_mfma_f32_16x16x32_bf16 v[24:27], v[158:161], v[210:213], v[24:27]
	v_mfma_f32_16x16x32_bf16 v[12:15], v[150:153], v[218:221], v[12:15]
	v_mfma_f32_16x16x32_bf16 v[8:11], v[158:161], v[218:221], v[8:11]
	s_setprio 0
	s_setprio 1
	v_mfma_f32_16x16x32_bf16 v[52:55], v[162:165], v[178:181], 0
	v_mfma_f32_16x16x32_bf16 v[48:51], v[170:173], v[178:181], 0
	v_mfma_f32_16x16x32_bf16 v[36:39], v[162:165], v[198:201], 0
	v_mfma_f32_16x16x32_bf16 v[32:35], v[170:173], v[198:201], 0
	v_mfma_f32_16x16x32_bf16 v[20:23], v[162:165], v[206:209], 0
	v_mfma_f32_16x16x32_bf16 v[16:19], v[170:173], v[206:209], 0
	v_mfma_f32_16x16x32_bf16 v[4:7], v[162:165], v[214:217], 0
	v_mfma_f32_16x16x32_bf16 v[0:3], v[170:173], v[214:217], 0
	v_mfma_f32_16x16x32_bf16 v[52:55], v[166:169], v[182:185], v[52:55]
	v_mfma_f32_16x16x32_bf16 v[48:51], v[174:177], v[182:185], v[48:51]
	v_mfma_f32_16x16x32_bf16 v[36:39], v[166:169], v[202:205], v[36:39]
	v_mfma_f32_16x16x32_bf16 v[32:35], v[174:177], v[202:205], v[32:35]
	v_mfma_f32_16x16x32_bf16 v[20:23], v[166:169], v[210:213], v[20:23]
	v_mfma_f32_16x16x32_bf16 v[16:19], v[174:177], v[210:213], v[16:19]
	v_mfma_f32_16x16x32_bf16 v[4:7], v[166:169], v[218:221], v[4:7]
	v_mfma_f32_16x16x32_bf16 v[0:3], v[174:177], v[218:221], v[0:3]
	s_setprio 0
	s_barrier
	s_add_i32 s56, 0, 0x18000
	s_add_i32 s57, 0, 0x1c000
	v_add_u32_e32 v158, s56, v147
	v_add_u32_e32 v174, s57, v147
	ds_read_b128 v[140:143], v158
	ds_read_b128 v[150:153], v158 offset:1024
	ds_read_b128 v[154:157], v158 offset:2048
	ds_read_b128 v[158:161], v158 offset:3072
	ds_read_b128 v[162:165], v174
	ds_read_b128 v[166:169], v174 offset:1024
	ds_read_b128 v[170:173], v174 offset:2048
	ds_read_b128 v[174:177], v174 offset:3072
	s_add_u32 s40, s40, 0x40000
	s_addc_u32 s41, s41, 0
	s_mov_b32 m0, s44
	v_lshl_add_u64 v[234:235], s[40:41], 0, v[130:131]
	ds_read_b128 v[178:181], v149 offset:32768
	ds_read_b128 v[182:185], v149 offset:33792
	ds_read_b128 v[198:201], v149 offset:34816
	ds_read_b128 v[202:205], v149 offset:35840
	ds_read_b128 v[206:209], v149 offset:36864
	ds_read_b128 v[210:213], v149 offset:37888
	ds_read_b128 v[214:217], v149 offset:38912
	ds_read_b128 v[218:221], v149 offset:39936
	global_load_lds_dwordx4 v[234:235], off
	v_lshl_add_u64 v[234:235], s[40:41], 0, v[132:133]
	s_mov_b32 m0, s45
	s_nop 0
	global_load_lds_dwordx4 v[234:235], off
	s_waitcnt vmcnt(8)
	s_waitcnt lgkmcnt(0)
	s_barrier
	s_setprio 1
	s_waitcnt lgkmcnt(0)
	v_mfma_f32_16x16x32_bf16 v[126:129], v[140:143], v[178:181], v[126:129]
	v_mfma_f32_16x16x32_bf16 v[122:125], v[154:157], v[178:181], v[122:125]
	v_mfma_f32_16x16x32_bf16 v[108:111], v[140:143], v[198:201], v[108:111]
	v_mfma_f32_16x16x32_bf16 v[104:107], v[154:157], v[198:201], v[104:107]
	v_mfma_f32_16x16x32_bf16 v[92:95], v[140:143], v[206:209], v[92:95]
	v_mfma_f32_16x16x32_bf16 v[88:91], v[154:157], v[206:209], v[88:91]
	v_mfma_f32_16x16x32_bf16 v[76:79], v[140:143], v[214:217], v[76:79]
	v_mfma_f32_16x16x32_bf16 v[72:75], v[154:157], v[214:217], v[72:75]
	v_mfma_f32_16x16x32_bf16 v[126:129], v[150:153], v[182:185], v[126:129]
	v_mfma_f32_16x16x32_bf16 v[122:125], v[158:161], v[182:185], v[122:125]
	v_mfma_f32_16x16x32_bf16 v[108:111], v[150:153], v[202:205], v[108:111]
	v_mfma_f32_16x16x32_bf16 v[104:107], v[158:161], v[202:205], v[104:107]
	v_mfma_f32_16x16x32_bf16 v[92:95], v[150:153], v[210:213], v[92:95]
	v_mfma_f32_16x16x32_bf16 v[88:91], v[158:161], v[210:213], v[88:91]
	v_mfma_f32_16x16x32_bf16 v[76:79], v[150:153], v[218:221], v[76:79]
	v_mfma_f32_16x16x32_bf16 v[72:75], v[158:161], v[218:221], v[72:75]
	s_setprio 0
	s_setprio 1
	v_mfma_f32_16x16x32_bf16 v[118:121], v[162:165], v[178:181], v[118:121]
	v_mfma_f32_16x16x32_bf16 v[114:117], v[170:173], v[178:181], v[114:117]
	v_mfma_f32_16x16x32_bf16 v[100:103], v[162:165], v[198:201], v[100:103]
	v_mfma_f32_16x16x32_bf16 v[96:99], v[170:173], v[198:201], v[96:99]
	v_mfma_f32_16x16x32_bf16 v[84:87], v[162:165], v[206:209], v[84:87]
	v_mfma_f32_16x16x32_bf16 v[80:83], v[170:173], v[206:209], v[80:83]
	v_mfma_f32_16x16x32_bf16 v[68:71], v[162:165], v[214:217], v[68:71]
	v_mfma_f32_16x16x32_bf16 v[64:67], v[170:173], v[214:217], v[64:67]
	v_mfma_f32_16x16x32_bf16 v[118:121], v[166:169], v[182:185], v[118:121]
	v_mfma_f32_16x16x32_bf16 v[114:117], v[174:177], v[182:185], v[114:117]
	v_mfma_f32_16x16x32_bf16 v[100:103], v[166:169], v[202:205], v[100:103]
	v_mfma_f32_16x16x32_bf16 v[96:99], v[174:177], v[202:205], v[96:99]
	v_mfma_f32_16x16x32_bf16 v[84:87], v[166:169], v[210:213], v[84:87]
	v_mfma_f32_16x16x32_bf16 v[80:83], v[174:177], v[210:213], v[80:83]
	v_mfma_f32_16x16x32_bf16 v[68:71], v[166:169], v[218:221], v[68:71]
	v_mfma_f32_16x16x32_bf16 v[64:67], v[174:177], v[218:221], v[64:67]
	s_setprio 0
	s_barrier
	s_add_i32 s40, s56, s39
	v_lshl_add_u64 v[144:145], v[144:145], 0, s[60:61]
	s_mov_b32 m0, s40
	ds_read_b128 v[178:181], v149 offset:49152
	ds_read_b128 v[182:185], v149 offset:50176
	ds_read_b128 v[198:201], v149 offset:51200
	ds_read_b128 v[202:205], v149 offset:52224
	ds_read_b128 v[206:209], v149 offset:53248
	ds_read_b128 v[210:213], v149 offset:54272
	ds_read_b128 v[214:217], v149 offset:55296
	ds_read_b128 v[218:221], v149 offset:56320
	global_load_lds_dwordx4 v[144:145], off
	s_add_i32 m0, s40, 0x2000
	s_add_u32 s36, s36, 0x18080
	v_lshl_add_u64 v[144:145], v[194:195], 0, s[60:61]
	s_addc_u32 s37, s37, 0
	s_add_i32 s40, s57, s39
	global_load_lds_dwordx4 v[144:145], off
	v_lshl_add_u64 v[144:145], s[36:37], 0, v[112:113]
	s_mov_b32 m0, s40
	s_nop 0
	global_load_lds_dwordx4 v[144:145], off
	v_lshl_add_u64 v[144:145], s[36:37], 0, v[134:135]
	s_add_i32 m0, s40, 0x2000
	s_nop 0
	global_load_lds_dwordx4 v[144:145], off
	v_lshl_add_u64 v[144:145], v[196:197], 0, s[60:61]
	s_mov_b32 m0, s47
	s_nop 0
	global_load_lds_dwordx4 v[144:145], off
	v_lshl_add_u64 v[144:145], v[222:223], 0, s[60:61]
	s_mov_b32 m0, s50
	s_nop 0
	global_load_lds_dwordx4 v[144:145], off
	s_waitcnt vmcnt(8)
	s_waitcnt lgkmcnt(0)
	s_barrier
	s_setprio 1
	s_waitcnt lgkmcnt(0)
	v_mfma_f32_16x16x32_bf16 v[60:63], v[140:143], v[178:181], v[60:63]
	v_mfma_f32_16x16x32_bf16 v[56:59], v[154:157], v[178:181], v[56:59]
	v_mfma_f32_16x16x32_bf16 v[44:47], v[140:143], v[198:201], v[44:47]
	v_mfma_f32_16x16x32_bf16 v[40:43], v[154:157], v[198:201], v[40:43]
	v_mfma_f32_16x16x32_bf16 v[28:31], v[140:143], v[206:209], v[28:31]
	v_mfma_f32_16x16x32_bf16 v[24:27], v[154:157], v[206:209], v[24:27]
	v_mfma_f32_16x16x32_bf16 v[12:15], v[140:143], v[214:217], v[12:15]
	v_mfma_f32_16x16x32_bf16 v[8:11], v[154:157], v[214:217], v[8:11]
	v_mfma_f32_16x16x32_bf16 v[60:63], v[150:153], v[182:185], v[60:63]
	v_mfma_f32_16x16x32_bf16 v[56:59], v[158:161], v[182:185], v[56:59]
	v_mfma_f32_16x16x32_bf16 v[44:47], v[150:153], v[202:205], v[44:47]
	v_mfma_f32_16x16x32_bf16 v[40:43], v[158:161], v[202:205], v[40:43]
	v_mfma_f32_16x16x32_bf16 v[28:31], v[150:153], v[210:213], v[28:31]
	v_mfma_f32_16x16x32_bf16 v[24:27], v[158:161], v[210:213], v[24:27]
	v_mfma_f32_16x16x32_bf16 v[12:15], v[150:153], v[218:221], v[12:15]
	v_mfma_f32_16x16x32_bf16 v[8:11], v[158:161], v[218:221], v[8:11]
	s_setprio 0
	s_setprio 1
	v_mfma_f32_16x16x32_bf16 v[52:55], v[162:165], v[178:181], v[52:55]
	v_mfma_f32_16x16x32_bf16 v[48:51], v[170:173], v[178:181], v[48:51]
	v_mfma_f32_16x16x32_bf16 v[36:39], v[162:165], v[198:201], v[36:39]
	v_mfma_f32_16x16x32_bf16 v[32:35], v[170:173], v[198:201], v[32:35]
	v_mfma_f32_16x16x32_bf16 v[20:23], v[162:165], v[206:209], v[20:23]
	v_mfma_f32_16x16x32_bf16 v[16:19], v[170:173], v[206:209], v[16:19]
	v_mfma_f32_16x16x32_bf16 v[4:7], v[162:165], v[214:217], v[4:7]
	v_mfma_f32_16x16x32_bf16 v[0:3], v[170:173], v[214:217], v[0:3]
	v_mfma_f32_16x16x32_bf16 v[52:55], v[166:169], v[182:185], v[52:55]
	v_mfma_f32_16x16x32_bf16 v[48:51], v[174:177], v[182:185], v[48:51]
	v_mfma_f32_16x16x32_bf16 v[36:39], v[166:169], v[202:205], v[36:39]
	v_mfma_f32_16x16x32_bf16 v[32:35], v[174:177], v[202:205], v[32:35]
	v_mfma_f32_16x16x32_bf16 v[20:23], v[166:169], v[210:213], v[20:23]
	v_mfma_f32_16x16x32_bf16 v[16:19], v[174:177], v[210:213], v[16:19]
	v_mfma_f32_16x16x32_bf16 v[4:7], v[166:169], v[218:221], v[4:7]
	v_mfma_f32_16x16x32_bf16 v[0:3], v[174:177], v[218:221], v[0:3]
	s_setprio 0
	s_barrier
	s_add_i32 s69, s69, 2
	s_add_u32 s6, s6, 0x100
	s_addc_u32 s7, s7, 0
	s_add_u32 s62, s62, 0x100
	s_addc_u32 s63, s63, 0
	s_cmp_gt_u32 s69, 3
	s_cbranch_scc0 .LBB0_731
	s_branch .Lpeel_after_4

.Lpeel_after_4:
	s_and_b64 vcc, exec, s[20:21]
	s_cbranch_vccz .LBB0_734
	s_barrier

.LBB0_780:
	s_ashr_i32 s23, s22, 31
	s_lshl_b64 s[12:13], s[22:23], 19
	s_add_u32 s30, s39, s12
	s_addc_u32 s31, s47, s13
	s_and_b64 s[12:13], s[4:5], exec
	s_cselect_b32 s7, s31, s41
	s_cselect_b32 s9, s30, s40
	s_ashr_i32 s21, s20, 31
	s_lshl_b64 s[12:13], s[20:21], 17
	s_add_u32 s34, s55, s12
	s_addc_u32 s35, s58, s13
	s_and_b64 s[12:13], s[4:5], exec
	s_cselect_b32 s21, s35, s37
	s_cselect_b32 s23, s34, s36
	s_mov_b32 s24, 0
	s_mov_b64 s[42:43], -1
	s_mov_b64 s[44:45], 0
	s_add_u32 s25, s40, s24
	s_addc_u32 s50, s41, 0
	s_add_u32 s51, s25, 0x100
	s_addc_u32 s56, s50, 0
	s_and_b64 s[12:13], s[44:45], exec
	s_cselect_b32 s63, s7, s56
	s_cselect_b32 s62, s9, s51
	s_add_u32 s12, s36, s24
	s_addc_u32 s13, s37, 0
	s_add_u32 s24, s12, 0x100
	s_addc_u32 s51, s13, 0
	s_add_i32 s56, 0, 0x10000
	s_and_b64 s[12:13], s[44:45], exec
	s_cselect_b32 s73, s21, s51
	s_cselect_b32 s72, s23, s24
	s_add_i32 s57, 0, 0x14000
	s_add_u32 s96, s25, 0x40080
	s_addc_u32 s97, s50, 0
	s_add_i32 s75, s56, s59
	s_add_i32 m0, s69, 0xc000
	s_add_i32 s76, s69, 0xe000
	s_add_i32 s64, s75, 0x2000
	s_add_u32 vcc_lo, s72, 0x10000
	v_add_u32_e32 v140, s56, v143
	s_addc_u32 vcc_hi, s73, 0
	s_add_i32 s13, s57, s59
	ds_read_b128 v[136:139], v140
	ds_read_b128 v[146:149], v140 offset:1024
	ds_read_b128 v[150:153], v140 offset:2048
	ds_read_b128 v[154:157], v140 offset:3072
	v_add_u32_e32 v140, s57, v143
	s_add_i32 s12, s13, 0x2000
	s_add_i32 s94, 0, 0x18000
	s_add_i32 s95, 0, 0x1c000
	ds_read_b128 v[158:161], v140
	ds_read_b128 v[162:165], v140 offset:1024
	ds_read_b128 v[166:169], v140 offset:2048
	ds_read_b128 v[170:173], v140 offset:3072
	s_add_u32 s50, s62, 0x40000
	s_addc_u32 s51, s63, 0
	s_add_i32 s25, s94, s59
	s_add_i32 s87, s25, 0x2000
	s_add_u32 s44, s72, 0x10080
	s_addc_u32 s45, s73, 0
	s_add_i32 s90, s95, s59
	s_add_i32 s24, s90, 0x2000
	v_lshl_add_u64 v[140:141], s[96:97], 0, v[130:131]
	ds_read_b128 v[174:177], v145
	ds_read_b128 v[178:181], v145 offset:1024
	ds_read_b128 v[182:185], v145 offset:2048
	ds_read_b128 v[198:201], v145 offset:3072
	ds_read_b128 v[202:205], v145 offset:4096
	ds_read_b128 v[206:209], v145 offset:5120
	ds_read_b128 v[210:213], v145 offset:6144
	ds_read_b128 v[214:217], v145 offset:7168
	global_load_lds_dwordx4 v[140:141], off
	v_lshl_add_u64 v[140:141], s[96:97], 0, v[132:133]
	s_mov_b32 m0, s76
	s_nop 0
	global_load_lds_dwordx4 v[140:141], off
	s_waitcnt vmcnt(8)
	s_waitcnt lgkmcnt(0)
	s_barrier
	s_setprio 1
	s_waitcnt lgkmcnt(0)
	v_mfma_f32_16x16x32_bf16 v[126:129], v[136:139], v[174:177], 0
	v_mfma_f32_16x16x32_bf16 v[122:125], v[150:153], v[174:177], 0
	v_mfma_f32_16x16x32_bf16 v[108:111], v[136:139], v[182:185], 0
	v_mfma_f32_16x16x32_bf16 v[104:107], v[150:153], v[182:185], 0
	v_mfma_f32_16x16x32_bf16 v[92:95], v[136:139], v[202:205], 0
	v_mfma_f32_16x16x32_bf16 v[88:91], v[150:153], v[202:205], 0
	v_mfma_f32_16x16x32_bf16 v[76:79], v[136:139], v[210:213], 0
	v_mfma_f32_16x16x32_bf16 v[72:75], v[150:153], v[210:213], 0
	v_mfma_f32_16x16x32_bf16 v[126:129], v[146:149], v[178:181], v[126:129]
	v_mfma_f32_16x16x32_bf16 v[122:125], v[154:157], v[178:181], v[122:125]
	v_mfma_f32_16x16x32_bf16 v[108:111], v[146:149], v[198:201], v[108:111]
	v_mfma_f32_16x16x32_bf16 v[104:107], v[154:157], v[198:201], v[104:107]
	v_mfma_f32_16x16x32_bf16 v[92:95], v[146:149], v[206:209], v[92:95]
	v_mfma_f32_16x16x32_bf16 v[88:91], v[154:157], v[206:209], v[88:91]
	v_mfma_f32_16x16x32_bf16 v[76:79], v[146:149], v[214:217], v[76:79]
	v_mfma_f32_16x16x32_bf16 v[72:75], v[154:157], v[214:217], v[72:75]
	s_setprio 0
	s_setprio 1
	v_mfma_f32_16x16x32_bf16 v[118:121], v[158:161], v[174:177], 0
	v_mfma_f32_16x16x32_bf16 v[114:117], v[166:169], v[174:177], 0
	v_mfma_f32_16x16x32_bf16 v[100:103], v[158:161], v[182:185], 0
	v_mfma_f32_16x16x32_bf16 v[96:99], v[166:169], v[182:185], 0
	v_mfma_f32_16x16x32_bf16 v[84:87], v[158:161], v[202:205], 0
	v_mfma_f32_16x16x32_bf16 v[80:83], v[166:169], v[202:205], 0
	v_mfma_f32_16x16x32_bf16 v[68:71], v[158:161], v[210:213], 0
	v_mfma_f32_16x16x32_bf16 v[64:67], v[166:169], v[210:213], 0
	v_mfma_f32_16x16x32_bf16 v[118:121], v[162:165], v[178:181], v[118:121]
	v_mfma_f32_16x16x32_bf16 v[114:117], v[170:173], v[178:181], v[114:117]
	v_mfma_f32_16x16x32_bf16 v[100:103], v[162:165], v[198:201], v[100:103]
	v_mfma_f32_16x16x32_bf16 v[96:99], v[170:173], v[198:201], v[96:99]
	v_mfma_f32_16x16x32_bf16 v[84:87], v[162:165], v[206:209], v[84:87]
	v_mfma_f32_16x16x32_bf16 v[80:83], v[170:173], v[206:209], v[80:83]
	v_mfma_f32_16x16x32_bf16 v[68:71], v[162:165], v[214:217], v[68:71]
	v_mfma_f32_16x16x32_bf16 v[64:67], v[170:173], v[214:217], v[64:67]
	s_setprio 0
	s_barrier
	s_mov_b32 m0, s75
	v_lshl_add_u64 v[140:141], s[72:73], 0, v[112:113]
	ds_read_b128 v[174:177], v145 offset:16384
	ds_read_b128 v[178:181], v145 offset:17408
	ds_read_b128 v[182:185], v145 offset:18432
	ds_read_b128 v[198:201], v145 offset:19456
	ds_read_b128 v[202:205], v145 offset:20480
	ds_read_b128 v[206:209], v145 offset:21504
	ds_read_b128 v[210:213], v145 offset:22528
	ds_read_b128 v[214:217], v145 offset:23552
	global_load_lds_dwordx4 v[140:141], off
	v_lshl_add_u64 v[194:195], s[72:73], 0, v[134:135]
	s_mov_b32 m0, s64
	v_lshl_add_u64 v[196:197], vcc, 0, v[112:113]
	global_load_lds_dwordx4 v[194:195], off
	s_mov_b32 m0, s13
	v_lshl_add_u64 v[218:219], s[62:63], 0, v[132:133]
	global_load_lds_dwordx4 v[196:197], off
	v_lshl_add_u64 v[196:197], vcc, 0, v[134:135]
	s_mov_b32 m0, s12
	s_nop 0
	global_load_lds_dwordx4 v[196:197], off
	v_lshl_add_u64 v[196:197], s[62:63], 0, v[130:131]
	s_mov_b32 m0, s69
	s_nop 0
	global_load_lds_dwordx4 v[196:197], off
	s_mov_b32 m0, s70
	s_nop 0
	global_load_lds_dwordx4 v[218:219], off
	s_waitcnt vmcnt(8)
	s_waitcnt lgkmcnt(0)
	s_barrier
	s_setprio 1
	s_waitcnt lgkmcnt(0)
	v_mfma_f32_16x16x32_bf16 v[60:63], v[136:139], v[174:177], 0
	v_mfma_f32_16x16x32_bf16 v[56:59], v[150:153], v[174:177], 0
	v_mfma_f32_16x16x32_bf16 v[44:47], v[136:139], v[182:185], 0
	v_mfma_f32_16x16x32_bf16 v[40:43], v[150:153], v[182:185], 0
	v_mfma_f32_16x16x32_bf16 v[28:31], v[136:139], v[202:205], 0
	v_mfma_f32_16x16x32_bf16 v[24:27], v[150:153], v[202:205], 0
	v_mfma_f32_16x16x32_bf16 v[12:15], v[136:139], v[210:213], 0
	v_mfma_f32_16x16x32_bf16 v[8:11], v[150:153], v[210:213], 0
	v_mfma_f32_16x16x32_bf16 v[60:63], v[146:149], v[178:181], v[60:63]
	v_mfma_f32_16x16x32_bf16 v[56:59], v[154:157], v[178:181], v[56:59]
	v_mfma_f32_16x16x32_bf16 v[44:47], v[146:149], v[198:201], v[44:47]
	v_mfma_f32_16x16x32_bf16 v[40:43], v[154:157], v[198:201], v[40:43]
	v_mfma_f32_16x16x32_bf16 v[28:31], v[146:149], v[206:209], v[28:31]
	v_mfma_f32_16x16x32_bf16 v[24:27], v[154:157], v[206:209], v[24:27]
	v_mfma_f32_16x16x32_bf16 v[12:15], v[146:149], v[214:217], v[12:15]
	v_mfma_f32_16x16x32_bf16 v[8:11], v[154:157], v[214:217], v[8:11]
	s_setprio 0
	s_setprio 1
	v_mfma_f32_16x16x32_bf16 v[52:55], v[158:161], v[174:177], 0
	v_mfma_f32_16x16x32_bf16 v[48:51], v[166:169], v[174:177], 0
	v_mfma_f32_16x16x32_bf16 v[36:39], v[158:161], v[182:185], 0
	v_mfma_f32_16x16x32_bf16 v[32:35], v[166:169], v[182:185], 0
	v_mfma_f32_16x16x32_bf16 v[20:23], v[158:161], v[202:205], 0
	v_mfma_f32_16x16x32_bf16 v[16:19], v[166:169], v[202:205], 0
	v_mfma_f32_16x16x32_bf16 v[4:7], v[158:161], v[210:213], 0
	v_mfma_f32_16x16x32_bf16 v[0:3], v[166:169], v[210:213], 0
	v_mfma_f32_16x16x32_bf16 v[52:55], v[162:165], v[178:181], v[52:55]
	v_mfma_f32_16x16x32_bf16 v[48:51], v[170:173], v[178:181], v[48:51]
	v_mfma_f32_16x16x32_bf16 v[36:39], v[162:165], v[198:201], v[36:39]
	v_mfma_f32_16x16x32_bf16 v[32:35], v[170:173], v[198:201], v[32:35]
	v_mfma_f32_16x16x32_bf16 v[20:23], v[162:165], v[206:209], v[20:23]
	v_mfma_f32_16x16x32_bf16 v[16:19], v[170:173], v[206:209], v[16:19]
	v_mfma_f32_16x16x32_bf16 v[4:7], v[162:165], v[214:217], v[4:7]
	v_mfma_f32_16x16x32_bf16 v[0:3], v[170:173], v[214:217], v[0:3]
	s_setprio 0
	s_barrier
	v_add_u32_e32 v154, s94, v143
	v_add_u32_e32 v170, s95, v143
	ds_read_b128 v[136:139], v154
	ds_read_b128 v[146:149], v154 offset:1024
	ds_read_b128 v[150:153], v154 offset:2048
	ds_read_b128 v[154:157], v154 offset:3072
	ds_read_b128 v[158:161], v170
	ds_read_b128 v[162:165], v170 offset:1024
	ds_read_b128 v[166:169], v170 offset:2048
	ds_read_b128 v[170:173], v170 offset:3072
	s_mov_b32 m0, s71
	v_lshl_add_u64 v[220:221], s[50:51], 0, v[130:131]
	ds_read_b128 v[174:177], v145 offset:32768
	ds_read_b128 v[178:181], v145 offset:33792
	ds_read_b128 v[182:185], v145 offset:34816
	ds_read_b128 v[198:201], v145 offset:35840
	ds_read_b128 v[202:205], v145 offset:36864
	ds_read_b128 v[206:209], v145 offset:37888
	ds_read_b128 v[210:213], v145 offset:38912
	ds_read_b128 v[214:217], v145 offset:39936
	global_load_lds_dwordx4 v[220:221], off
	v_lshl_add_u64 v[220:221], s[50:51], 0, v[132:133]
	s_mov_b32 m0, s82
	s_nop 0
	global_load_lds_dwordx4 v[220:221], off
	s_waitcnt vmcnt(8)
	s_waitcnt lgkmcnt(0)
	s_barrier
	s_setprio 1
	s_waitcnt lgkmcnt(0)
	v_mfma_f32_16x16x32_bf16 v[126:129], v[136:139], v[174:177], v[126:129]
	v_mfma_f32_16x16x32_bf16 v[122:125], v[150:153], v[174:177], v[122:125]
	v_mfma_f32_16x16x32_bf16 v[108:111], v[136:139], v[182:185], v[108:111]
	v_mfma_f32_16x16x32_bf16 v[104:107], v[150:153], v[182:185], v[104:107]
	v_mfma_f32_16x16x32_bf16 v[92:95], v[136:139], v[202:205], v[92:95]
	v_mfma_f32_16x16x32_bf16 v[88:91], v[150:153], v[202:205], v[88:91]
	v_mfma_f32_16x16x32_bf16 v[76:79], v[136:139], v[210:213], v[76:79]
	v_mfma_f32_16x16x32_bf16 v[72:75], v[150:153], v[210:213], v[72:75]
	v_mfma_f32_16x16x32_bf16 v[126:129], v[146:149], v[178:181], v[126:129]
	v_mfma_f32_16x16x32_bf16 v[122:125], v[154:157], v[178:181], v[122:125]
	v_mfma_f32_16x16x32_bf16 v[108:111], v[146:149], v[198:201], v[108:111]
	v_mfma_f32_16x16x32_bf16 v[104:107], v[154:157], v[198:201], v[104:107]
	v_mfma_f32_16x16x32_bf16 v[92:95], v[146:149], v[206:209], v[92:95]
	v_mfma_f32_16x16x32_bf16 v[88:91], v[154:157], v[206:209], v[88:91]
	v_mfma_f32_16x16x32_bf16 v[76:79], v[146:149], v[214:217], v[76:79]
	v_mfma_f32_16x16x32_bf16 v[72:75], v[154:157], v[214:217], v[72:75]
	s_setprio 0
	s_setprio 1
	v_mfma_f32_16x16x32_bf16 v[118:121], v[158:161], v[174:177], v[118:121]
	v_mfma_f32_16x16x32_bf16 v[114:117], v[166:169], v[174:177], v[114:117]
	v_mfma_f32_16x16x32_bf16 v[100:103], v[158:161], v[182:185], v[100:103]
	v_mfma_f32_16x16x32_bf16 v[96:99], v[166:169], v[182:185], v[96:99]
	v_mfma_f32_16x16x32_bf16 v[84:87], v[158:161], v[202:205], v[84:87]
	v_mfma_f32_16x16x32_bf16 v[80:83], v[166:169], v[202:205], v[80:83]
	v_mfma_f32_16x16x32_bf16 v[68:71], v[158:161], v[210:213], v[68:71]
	v_mfma_f32_16x16x32_bf16 v[64:67], v[166:169], v[210:213], v[64:67]
	v_mfma_f32_16x16x32_bf16 v[118:121], v[162:165], v[178:181], v[118:121]
	v_mfma_f32_16x16x32_bf16 v[114:117], v[170:173], v[178:181], v[114:117]
	v_mfma_f32_16x16x32_bf16 v[100:103], v[162:165], v[198:201], v[100:103]
	v_mfma_f32_16x16x32_bf16 v[96:99], v[170:173], v[198:201], v[96:99]
	v_mfma_f32_16x16x32_bf16 v[84:87], v[162:165], v[206:209], v[84:87]
	v_mfma_f32_16x16x32_bf16 v[80:83], v[170:173], v[206:209], v[80:83]
	v_mfma_f32_16x16x32_bf16 v[68:71], v[162:165], v[214:217], v[68:71]
	v_mfma_f32_16x16x32_bf16 v[64:67], v[170:173], v[214:217], v[64:67]
	s_setprio 0
	s_barrier
	s_mov_b32 m0, s25
	v_lshl_add_u64 v[140:141], v[140:141], 0, s[60:61]
	ds_read_b128 v[174:177], v145 offset:49152
	ds_read_b128 v[178:181], v145 offset:50176
	ds_read_b128 v[182:185], v145 offset:51200
	ds_read_b128 v[198:201], v145 offset:52224
	ds_read_b128 v[202:205], v145 offset:53248
	ds_read_b128 v[206:209], v145 offset:54272
	ds_read_b128 v[210:213], v145 offset:55296
	ds_read_b128 v[214:217], v145 offset:56320
	global_load_lds_dwordx4 v[140:141], off
	v_lshl_add_u64 v[140:141], v[194:195], 0, s[60:61]
	s_mov_b32 m0, s87
	s_nop 0
	global_load_lds_dwordx4 v[140:141], off
	v_lshl_add_u64 v[140:141], s[44:45], 0, v[112:113]
	s_mov_b32 m0, s90
	s_nop 0
	global_load_lds_dwordx4 v[140:141], off
	v_lshl_add_u64 v[140:141], s[44:45], 0, v[134:135]
	s_mov_b32 m0, s24
	s_nop 0
	global_load_lds_dwordx4 v[140:141], off
	v_lshl_add_u64 v[140:141], v[196:197], 0, s[60:61]
	s_mov_b32 m0, s83
	s_nop 0
	global_load_lds_dwordx4 v[140:141], off
	v_lshl_add_u64 v[140:141], v[218:219], 0, s[60:61]
	s_mov_b32 m0, s84
	s_nop 0
	global_load_lds_dwordx4 v[140:141], off
	s_waitcnt vmcnt(8)
	s_waitcnt lgkmcnt(0)
	s_barrier
	s_setprio 1
	s_waitcnt lgkmcnt(0)
	v_mfma_f32_16x16x32_bf16 v[60:63], v[136:139], v[174:177], v[60:63]
	v_mfma_f32_16x16x32_bf16 v[56:59], v[150:153], v[174:177], v[56:59]
	v_mfma_f32_16x16x32_bf16 v[44:47], v[136:139], v[182:185], v[44:47]
	v_mfma_f32_16x16x32_bf16 v[40:43], v[150:153], v[182:185], v[40:43]
	v_mfma_f32_16x16x32_bf16 v[28:31], v[136:139], v[202:205], v[28:31]
	v_mfma_f32_16x16x32_bf16 v[24:27], v[150:153], v[202:205], v[24:27]
	v_mfma_f32_16x16x32_bf16 v[12:15], v[136:139], v[210:213], v[12:15]
	v_mfma_f32_16x16x32_bf16 v[8:11], v[150:153], v[210:213], v[8:11]
	v_mfma_f32_16x16x32_bf16 v[60:63], v[146:149], v[178:181], v[60:63]
	v_mfma_f32_16x16x32_bf16 v[56:59], v[154:157], v[178:181], v[56:59]
	v_mfma_f32_16x16x32_bf16 v[44:47], v[146:149], v[198:201], v[44:47]
	v_mfma_f32_16x16x32_bf16 v[40:43], v[154:157], v[198:201], v[40:43]
	v_mfma_f32_16x16x32_bf16 v[28:31], v[146:149], v[206:209], v[28:31]
	v_mfma_f32_16x16x32_bf16 v[24:27], v[154:157], v[206:209], v[24:27]
	v_mfma_f32_16x16x32_bf16 v[12:15], v[146:149], v[214:217], v[12:15]
	v_mfma_f32_16x16x32_bf16 v[8:11], v[154:157], v[214:217], v[8:11]
	s_setprio 0
	s_setprio 1
	v_mfma_f32_16x16x32_bf16 v[52:55], v[158:161], v[174:177], v[52:55]
	v_mfma_f32_16x16x32_bf16 v[48:51], v[166:169], v[174:177], v[48:51]
	v_mfma_f32_16x16x32_bf16 v[36:39], v[158:161], v[182:185], v[36:39]
	v_mfma_f32_16x16x32_bf16 v[32:35], v[166:169], v[182:185], v[32:35]
	v_mfma_f32_16x16x32_bf16 v[20:23], v[158:161], v[202:205], v[20:23]
	v_mfma_f32_16x16x32_bf16 v[16:19], v[166:169], v[202:205], v[16:19]
	v_mfma_f32_16x16x32_bf16 v[4:7], v[158:161], v[210:213], v[4:7]
	v_mfma_f32_16x16x32_bf16 v[0:3], v[166:169], v[210:213], v[0:3]
	v_mfma_f32_16x16x32_bf16 v[52:55], v[162:165], v[178:181], v[52:55]
	v_mfma_f32_16x16x32_bf16 v[48:51], v[170:173], v[178:181], v[48:51]
	v_mfma_f32_16x16x32_bf16 v[36:39], v[162:165], v[198:201], v[36:39]
	v_mfma_f32_16x16x32_bf16 v[32:35], v[170:173], v[198:201], v[32:35]
	v_mfma_f32_16x16x32_bf16 v[20:23], v[162:165], v[206:209], v[20:23]
	v_mfma_f32_16x16x32_bf16 v[16:19], v[170:173], v[206:209], v[16:19]
	v_mfma_f32_16x16x32_bf16 v[4:7], v[162:165], v[214:217], v[4:7]
	v_mfma_f32_16x16x32_bf16 v[0:3], v[170:173], v[214:217], v[0:3]
	s_setprio 0
	s_barrier
	s_movk_i32 s24, 0x100
	s_andn2_b64 vcc, exec, s[42:43]
	s_mov_b64 s[44:45], -1
	s_mov_b64 s[42:43], 0
	s_cbranch_vccz .LBB0_781
	s_branch .Lpeel_after_5

.Lpeel_after_5:
	s_and_b64 vcc, exec, s[18:19]
	s_cbranch_vccz .LBB0_784
	s_barrier

.LBB0_828:
	s_ashr_i32 s19, s18, 31
	s_lshl_b64 s[20:21], s[18:19], 17
	s_add_u32 s20, s25, s20
	s_addc_u32 s21, s38, s21
	s_and_b64 s[22:23], s[4:5], exec
	s_cselect_b32 s19, s21, s35
	s_cselect_b32 s90, s20, s34
	s_ashr_i32 s17, s16, 31
	s_lshl_b64 s[22:23], s[16:17], 19
	s_add_u32 s22, s39, s22
	s_addc_u32 s23, s47, s23
	s_and_b64 s[36:37], s[4:5], exec
	s_cselect_b32 s17, s23, s31
	s_cselect_b32 s94, s22, s30
	s_mov_b64 s[42:43], 0
	s_mov_b64 s[36:37], -1
	s_mov_b64 s[40:41], 0
	s_add_u32 s57, s34, s42
	s_addc_u32 s59, s35, s43
	s_add_u32 s50, s57, 0x100
	s_addc_u32 s51, s59, 0
	s_and_b64 s[44:45], s[40:41], exec
	s_cselect_b32 s45, s19, s51
	s_cselect_b32 s44, s90, s50
	s_add_u32 s42, s30, s42
	s_addc_u32 s43, s31, s43
	s_add_u32 s42, s42, 0x100
	s_addc_u32 s43, s43, 0
	s_add_i32 s64, 0, 0x10000
	s_and_b64 s[40:41], s[40:41], exec
	s_cselect_b32 s51, s17, s43
	s_cselect_b32 s50, s94, s42
	s_add_i32 s93, 0, 0x14000
	s_add_u32 s72, s57, 0x10080
	s_addc_u32 s73, s59, 0
	s_add_i32 s57, s64, s55
	s_add_i32 m0, s56, 0xc000
	s_add_i32 s59, s56, 0xe000
	s_add_i32 s76, s57, 0x2000
	v_add_u32_e32 v112, s64, v173
	s_add_u32 s62, s50, 0x40000
	ds_read_b128 v[130:133], v112
	ds_read_b128 v[134:137], v112 offset:1024
	ds_read_b128 v[138:141], v112 offset:2048
	ds_read_b128 v[142:145], v112 offset:3072
	v_add_u32_e32 v112, s93, v173
	s_addc_u32 s63, s51, 0
	s_add_i32 s75, s93, s55
	ds_read_b128 v[146:149], v112
	ds_read_b128 v[150:153], v112 offset:1024
	ds_read_b128 v[154:157], v112 offset:2048
	ds_read_b128 v[158:161], v112 offset:3072
	s_add_i32 s3, s75, 0x2000
	s_add_i32 s87, 0, 0x18000
	s_add_i32 vcc_hi, 0, 0x1c000
	s_add_u32 s42, s44, 0x10000
	s_addc_u32 s43, s45, 0
	s_add_i32 vcc_lo, s87, s55
	s_add_i32 s96, vcc_lo, 0x2000
	s_add_u32 s40, s50, 0x40080
	s_addc_u32 s41, s51, 0
	s_add_i32 s97, vcc_hi, s55
	s_add_i32 s95, s97, 0x2000
	v_lshl_add_u64 v[194:195], s[72:73], 0, v[168:169]
	ds_read_b128 v[178:181], v175
	ds_read_b128 v[182:185], v175 offset:1024
	ds_read_b128 v[198:201], v175 offset:2048
	ds_read_b128 v[202:205], v175 offset:3072
	ds_read_b128 v[206:209], v175 offset:4096
	ds_read_b128 v[210:213], v175 offset:5120
	ds_read_b128 v[214:217], v175 offset:6144
	ds_read_b128 v[218:221], v175 offset:7168
	global_load_lds_dwordx4 v[194:195], off
	v_lshl_add_u64 v[194:195], s[72:73], 0, v[164:165]
	s_mov_b32 m0, s59
	s_nop 0
	global_load_lds_dwordx4 v[194:195], off
	s_waitcnt vmcnt(8)
	s_waitcnt lgkmcnt(0)
	s_barrier
	s_setprio 1
	s_waitcnt lgkmcnt(0)
	v_mfma_f32_16x16x32_bf16 v[126:129], v[130:133], v[178:181], 0
	v_mfma_f32_16x16x32_bf16 v[122:125], v[138:141], v[178:181], 0
	v_mfma_f32_16x16x32_bf16 v[118:121], v[130:133], v[198:201], 0
	v_mfma_f32_16x16x32_bf16 v[114:117], v[138:141], v[198:201], 0
	v_mfma_f32_16x16x32_bf16 v[108:111], v[130:133], v[206:209], 0
	v_mfma_f32_16x16x32_bf16 v[104:107], v[138:141], v[206:209], 0
	v_mfma_f32_16x16x32_bf16 v[100:103], v[130:133], v[214:217], 0
	v_mfma_f32_16x16x32_bf16 v[96:99], v[138:141], v[214:217], 0
	v_mfma_f32_16x16x32_bf16 v[126:129], v[134:137], v[182:185], v[126:129]
	v_mfma_f32_16x16x32_bf16 v[122:125], v[142:145], v[182:185], v[122:125]
	v_mfma_f32_16x16x32_bf16 v[118:121], v[134:137], v[202:205], v[118:121]
	v_mfma_f32_16x16x32_bf16 v[114:117], v[142:145], v[202:205], v[114:117]
	v_mfma_f32_16x16x32_bf16 v[108:111], v[134:137], v[210:213], v[108:111]
	v_mfma_f32_16x16x32_bf16 v[104:107], v[142:145], v[210:213], v[104:107]
	v_mfma_f32_16x16x32_bf16 v[100:103], v[134:137], v[218:221], v[100:103]
	v_mfma_f32_16x16x32_bf16 v[96:99], v[142:145], v[218:221], v[96:99]
	s_setprio 0
	s_setprio 1
	v_mfma_f32_16x16x32_bf16 v[60:63], v[146:149], v[178:181], 0
	v_mfma_f32_16x16x32_bf16 v[56:59], v[154:157], v[178:181], 0
	v_mfma_f32_16x16x32_bf16 v[52:55], v[146:149], v[198:201], 0
	v_mfma_f32_16x16x32_bf16 v[48:51], v[154:157], v[198:201], 0
	v_mfma_f32_16x16x32_bf16 v[44:47], v[146:149], v[206:209], 0
	v_mfma_f32_16x16x32_bf16 v[40:43], v[154:157], v[206:209], 0
	v_mfma_f32_16x16x32_bf16 v[36:39], v[146:149], v[214:217], 0
	v_mfma_f32_16x16x32_bf16 v[32:35], v[154:157], v[214:217], 0
	v_mfma_f32_16x16x32_bf16 v[60:63], v[150:153], v[182:185], v[60:63]
	v_mfma_f32_16x16x32_bf16 v[56:59], v[158:161], v[182:185], v[56:59]
	v_mfma_f32_16x16x32_bf16 v[52:55], v[150:153], v[202:205], v[52:55]
	v_mfma_f32_16x16x32_bf16 v[48:51], v[158:161], v[202:205], v[48:51]
	v_mfma_f32_16x16x32_bf16 v[44:47], v[150:153], v[210:213], v[44:47]
	v_mfma_f32_16x16x32_bf16 v[40:43], v[158:161], v[210:213], v[40:43]
	v_mfma_f32_16x16x32_bf16 v[36:39], v[150:153], v[218:221], v[36:39]
	v_mfma_f32_16x16x32_bf16 v[32:35], v[158:161], v[218:221], v[32:35]
	s_setprio 0
	s_barrier
	s_mov_b32 m0, s57
	v_lshl_add_u64 v[194:195], s[50:51], 0, v[166:167]
	ds_read_b128 v[178:181], v175 offset:16384
	ds_read_b128 v[182:185], v175 offset:17408
	ds_read_b128 v[198:201], v175 offset:18432
	ds_read_b128 v[202:205], v175 offset:19456
	ds_read_b128 v[206:209], v175 offset:20480
	ds_read_b128 v[210:213], v175 offset:21504
	ds_read_b128 v[214:217], v175 offset:22528
	ds_read_b128 v[218:221], v175 offset:23552
	global_load_lds_dwordx4 v[194:195], off
	v_lshl_add_u64 v[196:197], s[50:51], 0, v[162:163]
	s_mov_b32 m0, s76
	v_lshl_add_u64 v[222:223], s[62:63], 0, v[166:167]
	global_load_lds_dwordx4 v[196:197], off
	s_mov_b32 m0, s75
	v_lshl_add_u64 v[234:235], s[44:45], 0, v[164:165]
	global_load_lds_dwordx4 v[222:223], off
	v_lshl_add_u64 v[222:223], s[62:63], 0, v[162:163]
	s_mov_b32 m0, s3
	s_nop 0
	global_load_lds_dwordx4 v[222:223], off
	v_lshl_add_u64 v[222:223], s[44:45], 0, v[168:169]
	s_mov_b32 m0, s56
	s_nop 0
	global_load_lds_dwordx4 v[222:223], off
	s_mov_b32 m0, s69
	s_nop 0
	global_load_lds_dwordx4 v[234:235], off
	s_waitcnt vmcnt(8)
	s_waitcnt lgkmcnt(0)
	s_barrier
	s_setprio 1
	s_waitcnt lgkmcnt(0)
	v_mfma_f32_16x16x32_bf16 v[92:95], v[130:133], v[178:181], 0
	v_mfma_f32_16x16x32_bf16 v[88:91], v[138:141], v[178:181], 0
	v_mfma_f32_16x16x32_bf16 v[84:87], v[130:133], v[198:201], 0
	v_mfma_f32_16x16x32_bf16 v[80:83], v[138:141], v[198:201], 0
	v_mfma_f32_16x16x32_bf16 v[76:79], v[130:133], v[206:209], 0
	v_mfma_f32_16x16x32_bf16 v[72:75], v[138:141], v[206:209], 0
	v_mfma_f32_16x16x32_bf16 v[68:71], v[130:133], v[214:217], 0
	v_mfma_f32_16x16x32_bf16 v[64:67], v[138:141], v[214:217], 0
	v_mfma_f32_16x16x32_bf16 v[92:95], v[134:137], v[182:185], v[92:95]
	v_mfma_f32_16x16x32_bf16 v[88:91], v[142:145], v[182:185], v[88:91]
	v_mfma_f32_16x16x32_bf16 v[84:87], v[134:137], v[202:205], v[84:87]
	v_mfma_f32_16x16x32_bf16 v[80:83], v[142:145], v[202:205], v[80:83]
	v_mfma_f32_16x16x32_bf16 v[76:79], v[134:137], v[210:213], v[76:79]
	v_mfma_f32_16x16x32_bf16 v[72:75], v[142:145], v[210:213], v[72:75]
	v_mfma_f32_16x16x32_bf16 v[68:71], v[134:137], v[218:221], v[68:71]
	v_mfma_f32_16x16x32_bf16 v[64:67], v[142:145], v[218:221], v[64:67]
	s_setprio 0
	s_setprio 1
	v_mfma_f32_16x16x32_bf16 v[28:31], v[146:149], v[178:181], 0
	v_mfma_f32_16x16x32_bf16 v[24:27], v[154:157], v[178:181], 0
	v_mfma_f32_16x16x32_bf16 v[20:23], v[146:149], v[198:201], 0
	v_mfma_f32_16x16x32_bf16 v[16:19], v[154:157], v[198:201], 0
	v_mfma_f32_16x16x32_bf16 v[12:15], v[146:149], v[206:209], 0
	v_mfma_f32_16x16x32_bf16 v[8:11], v[154:157], v[206:209], 0
	v_mfma_f32_16x16x32_bf16 v[4:7], v[146:149], v[214:217], 0
	v_mfma_f32_16x16x32_bf16 v[0:3], v[154:157], v[214:217], 0
	v_mfma_f32_16x16x32_bf16 v[28:31], v[150:153], v[182:185], v[28:31]
	v_mfma_f32_16x16x32_bf16 v[24:27], v[158:161], v[182:185], v[24:27]
	v_mfma_f32_16x16x32_bf16 v[20:23], v[150:153], v[202:205], v[20:23]
	v_mfma_f32_16x16x32_bf16 v[16:19], v[158:161], v[202:205], v[16:19]
	v_mfma_f32_16x16x32_bf16 v[12:15], v[150:153], v[210:213], v[12:15]
	v_mfma_f32_16x16x32_bf16 v[8:11], v[158:161], v[210:213], v[8:11]
	v_mfma_f32_16x16x32_bf16 v[4:7], v[150:153], v[218:221], v[4:7]
	v_mfma_f32_16x16x32_bf16 v[0:3], v[158:161], v[218:221], v[0:3]
	s_setprio 0
	s_barrier
	v_add_u32_e32 v112, s87, v173
	ds_read_b128 v[130:133], v112
	ds_read_b128 v[134:137], v112 offset:1024
	ds_read_b128 v[138:141], v112 offset:2048
	ds_read_b128 v[142:145], v112 offset:3072
	v_add_u32_e32 v112, vcc_hi, v173
	ds_read_b128 v[146:149], v112
	ds_read_b128 v[150:153], v112 offset:1024
	ds_read_b128 v[154:157], v112 offset:2048
	ds_read_b128 v[158:161], v112 offset:3072
	s_mov_b32 m0, s70
	v_lshl_add_u64 v[236:237], s[42:43], 0, v[168:169]
	ds_read_b128 v[178:181], v175 offset:32768
	ds_read_b128 v[182:185], v175 offset:33792
	ds_read_b128 v[198:201], v175 offset:34816
	ds_read_b128 v[202:205], v175 offset:35840
	ds_read_b128 v[206:209], v175 offset:36864
	ds_read_b128 v[210:213], v175 offset:37888
	ds_read_b128 v[214:217], v175 offset:38912
	ds_read_b128 v[218:221], v175 offset:39936
	global_load_lds_dwordx4 v[236:237], off
	v_lshl_add_u64 v[236:237], s[42:43], 0, v[164:165]
	s_mov_b32 m0, s71
	s_nop 0
	global_load_lds_dwordx4 v[236:237], off
	s_waitcnt vmcnt(8)
	s_waitcnt lgkmcnt(0)
	s_barrier
	s_setprio 1
	s_waitcnt lgkmcnt(0)
	v_mfma_f32_16x16x32_bf16 v[126:129], v[130:133], v[178:181], v[126:129]
	v_mfma_f32_16x16x32_bf16 v[122:125], v[138:141], v[178:181], v[122:125]
	v_mfma_f32_16x16x32_bf16 v[118:121], v[130:133], v[198:201], v[118:121]
	v_mfma_f32_16x16x32_bf16 v[114:117], v[138:141], v[198:201], v[114:117]
	v_mfma_f32_16x16x32_bf16 v[108:111], v[130:133], v[206:209], v[108:111]
	v_mfma_f32_16x16x32_bf16 v[104:107], v[138:141], v[206:209], v[104:107]
	v_mfma_f32_16x16x32_bf16 v[100:103], v[130:133], v[214:217], v[100:103]
	v_mfma_f32_16x16x32_bf16 v[96:99], v[138:141], v[214:217], v[96:99]
	v_mfma_f32_16x16x32_bf16 v[126:129], v[134:137], v[182:185], v[126:129]
	v_mfma_f32_16x16x32_bf16 v[122:125], v[142:145], v[182:185], v[122:125]
	v_mfma_f32_16x16x32_bf16 v[118:121], v[134:137], v[202:205], v[118:121]
	v_mfma_f32_16x16x32_bf16 v[114:117], v[142:145], v[202:205], v[114:117]
	v_mfma_f32_16x16x32_bf16 v[108:111], v[134:137], v[210:213], v[108:111]
	v_mfma_f32_16x16x32_bf16 v[104:107], v[142:145], v[210:213], v[104:107]
	v_mfma_f32_16x16x32_bf16 v[100:103], v[134:137], v[218:221], v[100:103]
	v_mfma_f32_16x16x32_bf16 v[96:99], v[142:145], v[218:221], v[96:99]
	s_setprio 0
	s_setprio 1
	v_mfma_f32_16x16x32_bf16 v[60:63], v[146:149], v[178:181], v[60:63]
	v_mfma_f32_16x16x32_bf16 v[56:59], v[154:157], v[178:181], v[56:59]
	v_mfma_f32_16x16x32_bf16 v[52:55], v[146:149], v[198:201], v[52:55]
	v_mfma_f32_16x16x32_bf16 v[48:51], v[154:157], v[198:201], v[48:51]
	v_mfma_f32_16x16x32_bf16 v[44:47], v[146:149], v[206:209], v[44:47]
	v_mfma_f32_16x16x32_bf16 v[40:43], v[154:157], v[206:209], v[40:43]
	v_mfma_f32_16x16x32_bf16 v[36:39], v[146:149], v[214:217], v[36:39]
	v_mfma_f32_16x16x32_bf16 v[32:35], v[154:157], v[214:217], v[32:35]
	v_mfma_f32_16x16x32_bf16 v[60:63], v[150:153], v[182:185], v[60:63]
	v_mfma_f32_16x16x32_bf16 v[56:59], v[158:161], v[182:185], v[56:59]
	v_mfma_f32_16x16x32_bf16 v[52:55], v[150:153], v[202:205], v[52:55]
	v_mfma_f32_16x16x32_bf16 v[48:51], v[158:161], v[202:205], v[48:51]
	v_mfma_f32_16x16x32_bf16 v[44:47], v[150:153], v[210:213], v[44:47]
	v_mfma_f32_16x16x32_bf16 v[40:43], v[158:161], v[210:213], v[40:43]
	v_mfma_f32_16x16x32_bf16 v[36:39], v[150:153], v[218:221], v[36:39]
	v_mfma_f32_16x16x32_bf16 v[32:35], v[158:161], v[218:221], v[32:35]
	s_setprio 0
	s_barrier
	s_mov_b32 m0, vcc_lo
	v_lshl_add_u64 v[194:195], v[194:195], 0, s[60:61]
	ds_read_b128 v[178:181], v175 offset:49152
	ds_read_b128 v[182:185], v175 offset:50176
	ds_read_b128 v[198:201], v175 offset:51200
	ds_read_b128 v[202:205], v175 offset:52224
	ds_read_b128 v[206:209], v175 offset:53248
	ds_read_b128 v[210:213], v175 offset:54272
	ds_read_b128 v[214:217], v175 offset:55296
	ds_read_b128 v[218:221], v175 offset:56320
	global_load_lds_dwordx4 v[194:195], off
	v_lshl_add_u64 v[194:195], v[196:197], 0, s[60:61]
	s_mov_b32 m0, s96
	s_nop 0
	global_load_lds_dwordx4 v[194:195], off
	v_lshl_add_u64 v[194:195], s[40:41], 0, v[166:167]
	s_mov_b32 m0, s97
	s_nop 0
	global_load_lds_dwordx4 v[194:195], off
	v_lshl_add_u64 v[194:195], s[40:41], 0, v[162:163]
	s_mov_b32 m0, s95
	s_nop 0
	global_load_lds_dwordx4 v[194:195], off
	v_lshl_add_u64 v[194:195], v[222:223], 0, s[60:61]
	s_mov_b32 m0, s84
	s_nop 0
	global_load_lds_dwordx4 v[194:195], off
	v_lshl_add_u64 v[194:195], v[234:235], 0, s[60:61]
	s_mov_b32 m0, s85
	s_nop 0
	global_load_lds_dwordx4 v[194:195], off
	s_waitcnt vmcnt(8)
	s_waitcnt lgkmcnt(0)
	s_barrier
	s_setprio 1
	s_waitcnt lgkmcnt(0)
	v_mfma_f32_16x16x32_bf16 v[92:95], v[130:133], v[178:181], v[92:95]
	v_mfma_f32_16x16x32_bf16 v[88:91], v[138:141], v[178:181], v[88:91]
	v_mfma_f32_16x16x32_bf16 v[84:87], v[130:133], v[198:201], v[84:87]
	v_mfma_f32_16x16x32_bf16 v[80:83], v[138:141], v[198:201], v[80:83]
	v_mfma_f32_16x16x32_bf16 v[76:79], v[130:133], v[206:209], v[76:79]
	v_mfma_f32_16x16x32_bf16 v[72:75], v[138:141], v[206:209], v[72:75]
	v_mfma_f32_16x16x32_bf16 v[68:71], v[130:133], v[214:217], v[68:71]
	v_mfma_f32_16x16x32_bf16 v[64:67], v[138:141], v[214:217], v[64:67]
	v_mfma_f32_16x16x32_bf16 v[92:95], v[134:137], v[182:185], v[92:95]
	v_mfma_f32_16x16x32_bf16 v[88:91], v[142:145], v[182:185], v[88:91]
	v_mfma_f32_16x16x32_bf16 v[84:87], v[134:137], v[202:205], v[84:87]
	v_mfma_f32_16x16x32_bf16 v[80:83], v[142:145], v[202:205], v[80:83]
	v_mfma_f32_16x16x32_bf16 v[76:79], v[134:137], v[210:213], v[76:79]
	v_mfma_f32_16x16x32_bf16 v[72:75], v[142:145], v[210:213], v[72:75]
	v_mfma_f32_16x16x32_bf16 v[68:71], v[134:137], v[218:221], v[68:71]
	v_mfma_f32_16x16x32_bf16 v[64:67], v[142:145], v[218:221], v[64:67]
	s_setprio 0
	s_setprio 1
	v_mfma_f32_16x16x32_bf16 v[28:31], v[146:149], v[178:181], v[28:31]
	v_mfma_f32_16x16x32_bf16 v[24:27], v[154:157], v[178:181], v[24:27]
	v_mfma_f32_16x16x32_bf16 v[20:23], v[146:149], v[198:201], v[20:23]
	v_mfma_f32_16x16x32_bf16 v[16:19], v[154:157], v[198:201], v[16:19]
	v_mfma_f32_16x16x32_bf16 v[12:15], v[146:149], v[206:209], v[12:15]
	v_mfma_f32_16x16x32_bf16 v[8:11], v[154:157], v[206:209], v[8:11]
	v_mfma_f32_16x16x32_bf16 v[4:7], v[146:149], v[214:217], v[4:7]
	v_mfma_f32_16x16x32_bf16 v[0:3], v[154:157], v[214:217], v[0:3]
	v_mfma_f32_16x16x32_bf16 v[28:31], v[150:153], v[182:185], v[28:31]
	v_mfma_f32_16x16x32_bf16 v[24:27], v[158:161], v[182:185], v[24:27]
	v_mfma_f32_16x16x32_bf16 v[20:23], v[150:153], v[202:205], v[20:23]
	v_mfma_f32_16x16x32_bf16 v[16:19], v[158:161], v[202:205], v[16:19]
	v_mfma_f32_16x16x32_bf16 v[12:15], v[150:153], v[210:213], v[12:15]
	v_mfma_f32_16x16x32_bf16 v[8:11], v[158:161], v[210:213], v[8:11]
	v_mfma_f32_16x16x32_bf16 v[4:7], v[150:153], v[218:221], v[4:7]
	v_mfma_f32_16x16x32_bf16 v[0:3], v[158:161], v[218:221], v[0:3]
	s_setprio 0
	s_barrier
	s_andn2_b64 vcc, exec, s[36:37]
	s_mov_b64 s[40:41], -1
	s_mov_b64 s[36:37], 0
	s_mov_b64 s[42:43], 0x100
	s_cbranch_vccz .LBB0_829
	s_branch .Lpeel_after_6

.Lpeel_after_6:
	s_and_b64 vcc, exec, s[14:15]
	s_cbranch_vccz .LBB0_832
	s_barrier

.Lattn_h0_nok1:
	s_or_b64 exec, exec, s[8:9]
	s_lshl_b32 s90, s14, 13
	v_lshl_add_u64 v[182:183], v[164:165], 0, s[90:91]
	global_load_dwordx4 v[154:157], v[182:183], off
	s_setprio 1
	s_add_i32 s15, s13, 0
	s_add_i32 s14, s10, 0
	s_add_i32 s16, s11, 0
	v_add3_u32 v177, s15, v174, v112
	v_add3_u32 v178, s14, v176, v112
	ds_read_b128 v[202:205], v177
	ds_read_b128 v[206:209], v177 offset:6656
	ds_read_b128 v[210:213], v177 offset:32
	v_mfma_f32_32x32x16_bf16 v[16:31], v[194:197], v[214:217], v[16:31]
	ds_read_b128 v[194:197], v177 offset:6688
	v_exp_f32_e32 v64, v64
	v_exp_f32_e32 v65, v65
	v_exp_f32_e32 v66, v66
	v_mfma_f32_32x32x16_bf16 v[0:15], v[198:201], v[214:217], v[0:15]
	ds_read_b128 v[198:201], v177 offset:64
	v_exp_f32_e32 v67, v67
	v_exp_f32_e32 v68, v68
	v_exp_f32_e32 v69, v69
	s_waitcnt lgkmcnt(4)
	v_mfma_f32_32x32x16_bf16 v[96:111], v[202:205], v[126:129], v[32:47]
	ds_read_b128 v[202:205], v177 offset:6720
	v_exp_f32_e32 v70, v70
	v_exp_f32_e32 v71, v71
	v_exp_f32_e32 v72, v72
	s_waitcnt lgkmcnt(4)
	v_mfma_f32_32x32x16_bf16 v[80:95], v[206:209], v[126:129], v[32:47]
	ds_read_b128 v[206:209], v177 offset:96
	v_add_f32_e32 v179, v179, v64
	v_exp_f32_e32 v73, v73
	v_add_f32_e32 v218, v218, v65
	v_exp_f32_e32 v74, v74
	s_waitcnt lgkmcnt(4)
	v_mfma_f32_32x32x16_bf16 v[96:111], v[210:213], v[130:133], v[96:111]
	ds_read_b128 v[210:213], v177 offset:6752
	v_add_f32_e32 v179, v179, v66
	v_exp_f32_e32 v75, v75
	v_add_f32_e32 v218, v218, v67
	s_waitcnt lgkmcnt(4)
	v_mfma_f32_32x32x16_bf16 v[80:95], v[194:197], v[130:133], v[80:95]
	ds_read_b128 v[194:197], v177 offset:128
	v_exp_f32_e32 v76, v76
	v_add_f32_e32 v179, v179, v68
	v_exp_f32_e32 v77, v77
	v_add_f32_e32 v218, v218, v69
	s_waitcnt lgkmcnt(4)
	v_mfma_f32_32x32x16_bf16 v[96:111], v[198:201], v[134:137], v[96:111]
	ds_read_b128 v[198:201], v177 offset:6784
	v_exp_f32_e32 v78, v78
	v_add_f32_e32 v179, v179, v70
	v_exp_f32_e32 v79, v79
	v_add_f32_e32 v218, v218, v71
	s_waitcnt lgkmcnt(4)
	v_mfma_f32_32x32x16_bf16 v[80:95], v[202:205], v[134:137], v[80:95]
	ds_read_b128 v[202:205], v177 offset:160
	v_cvt_pk_bf16_f32 v64, v64, v65
	v_cvt_pk_bf16_f32 v65, v66, v67
	v_cvt_pk_bf16_f32 v66, v68, v69
	v_cvt_pk_bf16_f32 v67, v70, v71
	v_exp_f32_e32 v48, v48
	s_waitcnt lgkmcnt(4)
	v_mfma_f32_32x32x16_bf16 v[96:111], v[206:209], v[138:141], v[96:111]
	ds_read_b128 v[206:209], v177 offset:6816
	v_add_f32_e32 v179, v179, v72
	v_exp_f32_e32 v49, v49
	v_add_f32_e32 v218, v218, v73
	v_exp_f32_e32 v50, v50
	v_add_u32_e32 v180, s16, v170
	s_waitcnt vmcnt(3)
	ds_write_b128 v180, v[122:125]
	s_and_saveexec_b64 s[6:7], s[4:5]
	v_add_u32_e32 v180, s16, v173
	ds_write_b128 v180, v[118:121]
	s_or_b64 exec, exec, s[6:7]
	v_add_u32_e32 v180, s16, v172
	v_add_u32_e32 v180, 0x3000, v180
	s_waitcnt vmcnt(2)
	ds_write2_b64 v180, v[150:151], v[152:153] offset0:128 offset1:130
	s_waitcnt lgkmcnt(6)
	v_mfma_f32_32x32x16_bf16 v[80:95], v[210:213], v[138:141], v[80:95]
	ds_read_b128 v[210:213], v178 offset:13312
	v_add_f32_e32 v179, v179, v74
	v_exp_f32_e32 v51, v51
	v_add_f32_e32 v218, v218, v75
	s_waitcnt lgkmcnt(6)
	v_mfma_f32_32x32x16_bf16 v[96:111], v[194:197], v[142:145], v[96:111]
	ds_read_b128 v[194:197], v178 offset:17920
	v_exp_f32_e32 v52, v52
	v_add_f32_e32 v179, v179, v76
	v_exp_f32_e32 v53, v53
	v_add_f32_e32 v218, v218, v77
	s_waitcnt lgkmcnt(6)
	v_mfma_f32_32x32x16_bf16 v[80:95], v[198:201], v[142:145], v[80:95]
	ds_read_b128 v[198:201], v178 offset:13344
	v_exp_f32_e32 v54, v54
	v_add_f32_e32 v179, v179, v78
	v_exp_f32_e32 v55, v55
	v_add_f32_e32 v218, v218, v79
	s_waitcnt lgkmcnt(6)
	v_mfma_f32_32x32x16_bf16 v[96:111], v[202:205], v[146:149], v[96:111]
	ds_read_b128 v[202:205], v178 offset:17952
	v_cvt_pk_bf16_f32 v72, v72, v73
	v_cvt_pk_bf16_f32 v73, v74, v75
	v_cvt_pk_bf16_f32 v74, v76, v77
	v_cvt_pk_bf16_f32 v75, v78, v79
	v_add_f32_e32 v179, v179, v48
	s_waitcnt lgkmcnt(6)
	v_mfma_f32_32x32x16_bf16 v[80:95], v[206:209], v[146:149], v[80:95]
	ds_read_b128 v[206:209], v178 offset:13376
	v_add_f32_e32 v218, v218, v49
	v_add_f32_e32 v179, v179, v50
	v_add_f32_e32 v218, v218, v51
	v_add_f32_e32 v179, v179, v52
	v_add_f32_e32 v218, v218, v53
	v_add_f32_e32 v179, v179, v54
	s_waitcnt lgkmcnt(4)
	v_mfma_f32_32x32x16_bf16 v[16:31], v[210:213], v[64:67], v[16:31]
	ds_read_b128 v[210:213], v178 offset:17984
	v_add_f32_e32 v218, v218, v55
	v_cvt_pk_bf16_f32 v48, v48, v49
	v_cvt_pk_bf16_f32 v49, v50, v51
	v_cvt_pk_bf16_f32 v50, v52, v53
	v_cvt_pk_bf16_f32 v51, v54, v55
	s_waitcnt lgkmcnt(4)
	v_mfma_f32_32x32x16_bf16 v[0:15], v[194:197], v[64:67], v[0:15]
	ds_read_b128 v[194:197], v178 offset:13408
	v_exp_f32_e32 v56, v56
	v_exp_f32_e32 v57, v57
	v_exp_f32_e32 v58, v58
	s_waitcnt lgkmcnt(4)
	v_mfma_f32_32x32x16_bf16 v[16:31], v[198:201], v[72:75], v[16:31]
	ds_read_b128 v[198:201], v178 offset:18016
	v_exp_f32_e32 v59, v59
	v_exp_f32_e32 v60, v60
	v_exp_f32_e32 v61, v61
	s_waitcnt lgkmcnt(4)
	v_mfma_f32_32x32x16_bf16 v[0:15], v[202:205], v[72:75], v[0:15]
	v_exp_f32_e32 v62, v62
	v_exp_f32_e32 v63, v63
	v_add_f32_e32 v179, v179, v56
	s_waitcnt lgkmcnt(3)
	v_mfma_f32_32x32x16_bf16 v[16:31], v[206:209], v[48:51], v[16:31]
	v_add_f32_e32 v218, v218, v57
	v_add_f32_e32 v179, v179, v58
	v_add_f32_e32 v218, v218, v59
	v_add_f32_e32 v179, v179, v60
	v_add_f32_e32 v218, v218, v61
	v_add_f32_e32 v179, v179, v62
	s_waitcnt lgkmcnt(2)
	v_mfma_f32_32x32x16_bf16 v[0:15], v[210:213], v[48:51], v[0:15]
	v_add_f32_e32 v218, v218, v63
	v_cvt_pk_bf16_f32 v214, v56, v57
	v_cvt_pk_bf16_f32 v215, v58, v59
	v_cvt_pk_bf16_f32 v216, v60, v61
	v_cvt_pk_bf16_f32 v217, v62, v63
	s_setprio 0
	s_waitcnt lgkmcnt(0)
	s_barrier
	s_min_u32 s17, s12, 0xfb
	s_add_i32 s17, s17, 4
	s_mul_i32 s3, s17, 0x3000
	s_add_u32 s6, s42, s3
	s_addc_u32 s7, s43, 0
	v_lshl_add_u64 v[182:183], v[162:163], 1, s[6:7]
	global_load_dwordx4 v[122:125], v[182:183], off
	s_and_saveexec_b64 s[8:9], s[4:5]
	s_cbranch_execz .Lattn_h1_nok1
	v_lshl_add_u64 v[182:183], s[6:7], 0, v[168:169]
	global_load_dwordx4 v[118:121], v[182:183], off
.Lattn_h1_nok1:
	s_or_b64 exec, exec, s[8:9]
	s_lshl_b32 s90, s17, 13
	v_lshl_add_u64 v[182:183], v[164:165], 0, s[90:91]
	global_load_dwordx4 v[150:153], v[182:183], off
	s_setprio 1
	v_add3_u32 v177, s16, v174, v112
	v_add3_u32 v178, s15, v176, v112
	ds_read_b128 v[202:205], v177
	ds_read_b128 v[206:209], v177 offset:6656
	ds_read_b128 v[210:213], v177 offset:32
	v_mfma_f32_32x32x16_bf16 v[16:31], v[194:197], v[214:217], v[16:31]
	ds_read_b128 v[194:197], v177 offset:6688
	v_exp_f32_e32 v96, v96
	v_exp_f32_e32 v97, v97
	v_exp_f32_e32 v98, v98
	v_mfma_f32_32x32x16_bf16 v[0:15], v[198:201], v[214:217], v[0:15]
	ds_read_b128 v[198:201], v177 offset:64
	v_exp_f32_e32 v99, v99
	v_exp_f32_e32 v100, v100
	v_exp_f32_e32 v101, v101
	s_waitcnt lgkmcnt(4)
	v_mfma_f32_32x32x16_bf16 v[64:79], v[202:205], v[126:129], v[32:47]
	ds_read_b128 v[202:205], v177 offset:6720
	v_exp_f32_e32 v102, v102
	v_exp_f32_e32 v103, v103
	v_exp_f32_e32 v104, v104
	s_waitcnt lgkmcnt(4)
	v_mfma_f32_32x32x16_bf16 v[48:63], v[206:209], v[126:129], v[32:47]
	ds_read_b128 v[206:209], v177 offset:96
	v_add_f32_e32 v179, v179, v96
	v_exp_f32_e32 v105, v105
	v_add_f32_e32 v218, v218, v97
	v_exp_f32_e32 v106, v106
	s_waitcnt lgkmcnt(4)
	v_mfma_f32_32x32x16_bf16 v[64:79], v[210:213], v[130:133], v[64:79]
	ds_read_b128 v[210:213], v177 offset:6752
	v_add_f32_e32 v179, v179, v98
	v_exp_f32_e32 v107, v107
	v_add_f32_e32 v218, v218, v99
	s_waitcnt lgkmcnt(4)
	v_mfma_f32_32x32x16_bf16 v[48:63], v[194:197], v[130:133], v[48:63]
	ds_read_b128 v[194:197], v177 offset:128
	v_exp_f32_e32 v108, v108
	v_add_f32_e32 v179, v179, v100
	v_exp_f32_e32 v109, v109
	v_add_f32_e32 v218, v218, v101
	s_waitcnt lgkmcnt(4)
	v_mfma_f32_32x32x16_bf16 v[64:79], v[198:201], v[134:137], v[64:79]
	ds_read_b128 v[198:201], v177 offset:6784
	v_exp_f32_e32 v110, v110
	v_add_f32_e32 v179, v179, v102
	v_exp_f32_e32 v111, v111
	v_add_f32_e32 v218, v218, v103
	s_waitcnt lgkmcnt(4)
	v_mfma_f32_32x32x16_bf16 v[48:63], v[202:205], v[134:137], v[48:63]
	ds_read_b128 v[202:205], v177 offset:160
	v_cvt_pk_bf16_f32 v96, v96, v97
	v_cvt_pk_bf16_f32 v97, v98, v99
	v_cvt_pk_bf16_f32 v98, v100, v101
	v_cvt_pk_bf16_f32 v99, v102, v103
	v_exp_f32_e32 v80, v80
	s_waitcnt lgkmcnt(4)
	v_mfma_f32_32x32x16_bf16 v[64:79], v[206:209], v[138:141], v[64:79]
	ds_read_b128 v[206:209], v177 offset:6816
	v_add_f32_e32 v179, v179, v104
	v_exp_f32_e32 v81, v81
	v_add_f32_e32 v218, v218, v105
	v_exp_f32_e32 v82, v82
	v_add_u32_e32 v180, s14, v170
	s_waitcnt vmcnt(3)
	ds_write_b128 v180, v[158:161]
	s_and_saveexec_b64 s[6:7], s[4:5]
	v_add_u32_e32 v180, s14, v173
	ds_write_b128 v180, v[114:117]
	s_or_b64 exec, exec, s[6:7]
	v_add_u32_e32 v180, s14, v172
	v_add_u32_e32 v180, 0x3000, v180
	s_waitcnt vmcnt(2)
	ds_write2_b64 v180, v[154:155], v[156:157] offset0:128 offset1:130
	s_waitcnt lgkmcnt(6)
	v_mfma_f32_32x32x16_bf16 v[48:63], v[210:213], v[138:141], v[48:63]
	ds_read_b128 v[210:213], v178 offset:13312
	v_add_f32_e32 v179, v179, v106
	v_exp_f32_e32 v83, v83
	v_add_f32_e32 v218, v218, v107
	s_waitcnt lgkmcnt(6)
	v_mfma_f32_32x32x16_bf16 v[64:79], v[194:197], v[142:145], v[64:79]
	ds_read_b128 v[194:197], v178 offset:17920
	v_exp_f32_e32 v84, v84
	v_add_f32_e32 v179, v179, v108
	v_exp_f32_e32 v85, v85
	v_add_f32_e32 v218, v218, v109
	s_waitcnt lgkmcnt(6)
	v_mfma_f32_32x32x16_bf16 v[48:63], v[198:201], v[142:145], v[48:63]
	ds_read_b128 v[198:201], v178 offset:13344
	v_exp_f32_e32 v86, v86
	v_add_f32_e32 v179, v179, v110
	v_exp_f32_e32 v87, v87
	v_add_f32_e32 v218, v218, v111
	s_waitcnt lgkmcnt(6)
	v_mfma_f32_32x32x16_bf16 v[64:79], v[202:205], v[146:149], v[64:79]
	ds_read_b128 v[202:205], v178 offset:17952
	v_cvt_pk_bf16_f32 v104, v104, v105
	v_cvt_pk_bf16_f32 v105, v106, v107
	v_cvt_pk_bf16_f32 v106, v108, v109
	v_cvt_pk_bf16_f32 v107, v110, v111
	v_add_f32_e32 v179, v179, v80
	s_waitcnt lgkmcnt(6)
	v_mfma_f32_32x32x16_bf16 v[48:63], v[206:209], v[146:149], v[48:63]
	ds_read_b128 v[206:209], v178 offset:13376
	v_add_f32_e32 v218, v218, v81
	v_add_f32_e32 v179, v179, v82
	v_add_f32_e32 v218, v218, v83
	v_add_f32_e32 v179, v179, v84
	v_add_f32_e32 v218, v218, v85
	v_add_f32_e32 v179, v179, v86
	s_waitcnt lgkmcnt(4)
	v_mfma_f32_32x32x16_bf16 v[16:31], v[210:213], v[96:99], v[16:31]
	ds_read_b128 v[210:213], v178 offset:17984
	v_add_f32_e32 v218, v218, v87
	v_cvt_pk_bf16_f32 v80, v80, v81
	v_cvt_pk_bf16_f32 v81, v82, v83
	v_cvt_pk_bf16_f32 v82, v84, v85
	v_cvt_pk_bf16_f32 v83, v86, v87
	s_waitcnt lgkmcnt(4)
	v_mfma_f32_32x32x16_bf16 v[0:15], v[194:197], v[96:99], v[0:15]
	ds_read_b128 v[194:197], v178 offset:13408
	v_exp_f32_e32 v88, v88
	v_exp_f32_e32 v89, v89
	v_exp_f32_e32 v90, v90
	s_waitcnt lgkmcnt(4)
	v_mfma_f32_32x32x16_bf16 v[16:31], v[198:201], v[104:107], v[16:31]
	ds_read_b128 v[198:201], v178 offset:18016
	v_exp_f32_e32 v91, v91
	v_exp_f32_e32 v92, v92
	v_exp_f32_e32 v93, v93
	s_waitcnt lgkmcnt(4)
	v_mfma_f32_32x32x16_bf16 v[0:15], v[202:205], v[104:107], v[0:15]
	v_exp_f32_e32 v94, v94
	v_exp_f32_e32 v95, v95
	v_add_f32_e32 v179, v179, v88
	s_waitcnt lgkmcnt(3)
	v_mfma_f32_32x32x16_bf16 v[16:31], v[206:209], v[80:83], v[16:31]
	v_add_f32_e32 v218, v218, v89
	v_add_f32_e32 v179, v179, v90
	v_add_f32_e32 v218, v218, v91
	v_add_f32_e32 v179, v179, v92
	v_add_f32_e32 v218, v218, v93
	v_add_f32_e32 v179, v179, v94
	s_waitcnt lgkmcnt(2)
	v_mfma_f32_32x32x16_bf16 v[0:15], v[210:213], v[80:83], v[0:15]
	v_add_f32_e32 v218, v218, v95
	v_cvt_pk_bf16_f32 v214, v88, v89
	v_cvt_pk_bf16_f32 v215, v90, v91
	v_cvt_pk_bf16_f32 v216, v92, v93
	v_cvt_pk_bf16_f32 v217, v94, v95
	s_setprio 0
	s_cmpk_lt_u32 s12, 0xfe
	s_waitcnt lgkmcnt(0)
	s_barrier
	s_cbranch_scc0 .Lattn_exit
	s_mov_b32 s6, s11
	s_mov_b32 s11, s13
	s_branch .LBB0_1048

.LBB0_1385:
	s_ashr_i32 s31, s30, 31
	s_lshl_b64 s[24:25], s[30:31], 19
	s_add_u32 s34, s38, s24
	s_addc_u32 s35, s39, s25
	s_and_b64 s[24:25], s[6:7], exec
	s_cselect_b32 s24, s35, s45
	s_cselect_b32 s25, s34, s44
	s_ashr_i32 s23, s22, 31
	s_lshl_b64 s[36:37], s[22:23], 19
	s_add_u32 s36, s47, s36
	s_addc_u32 s37, s55, s37
	s_and_b64 s[56:57], s[6:7], exec
	s_cselect_b32 s23, s37, s51
	s_cselect_b32 s31, s36, s50
	s_add_u32 s44, s44, 0x40080
	s_addc_u32 s45, s45, 0
	s_add_u32 s41, s50, 0x100
	s_addc_u32 s84, s51, 0
	s_mov_b32 s85, -2
	s_waitcnt lgkmcnt(0)
	s_add_u32 s3, s44, 0xfffc0080
	s_addc_u32 s50, s45, -1
	s_add_i32 s56, 0, 0x10000
	s_cmp_eq_u32 s85, 12
	s_cselect_b32 s63, s24, s50
	s_cselect_b32 s62, s25, s3
	s_cselect_b32 s51, s23, s84
	s_cselect_b32 s50, s31, s41
	s_add_i32 s3, 0, 0x14000
	v_add_u32_e32 v142, s56, v213
	v_add_u32_e32 v158, s3, v213
	ds_read_b128 v[130:133], v142
	ds_read_b128 v[134:137], v142 offset:1024
	ds_read_b128 v[138:141], v142 offset:2048
	ds_read_b128 v[142:145], v142 offset:3072
	ds_read_b128 v[146:149], v158
	ds_read_b128 v[150:153], v158 offset:1024
	ds_read_b128 v[154:157], v158 offset:2048
	ds_read_b128 v[158:161], v158 offset:3072
	v_lshl_add_u64 v[216:217], s[44:45], 0, v[184:185]
	s_add_i32 m0, s43, 0xc000
	ds_read_b128 v[162:165], v215
	ds_read_b128 v[166:169], v215 offset:1024
	ds_read_b128 v[170:173], v215 offset:2048
	ds_read_b128 v[174:177], v215 offset:3072
	ds_read_b128 v[194:197], v215 offset:4096
	ds_read_b128 v[200:203], v215 offset:5120
	ds_read_b128 v[204:207], v215 offset:6144
	ds_read_b128 v[208:211], v215 offset:7168
	global_load_lds_dwordx4 v[216:217], off
	v_lshl_add_u64 v[216:217], s[44:45], 0, v[198:199]
	s_add_i32 m0, s43, 0xe000
	s_nop 0
	global_load_lds_dwordx4 v[216:217], off
	s_waitcnt vmcnt(8)
	s_waitcnt lgkmcnt(0)
	s_barrier
	s_setprio 1
	s_waitcnt lgkmcnt(0)
	v_mfma_f32_16x16x32_bf16 v[126:129], v[130:133], v[162:165], 0
	v_mfma_f32_16x16x32_bf16 v[122:125], v[138:141], v[162:165], 0
	v_mfma_f32_16x16x32_bf16 v[108:111], v[130:133], v[170:173], 0
	v_mfma_f32_16x16x32_bf16 v[104:107], v[138:141], v[170:173], 0
	v_mfma_f32_16x16x32_bf16 v[92:95], v[130:133], v[194:197], 0
	v_mfma_f32_16x16x32_bf16 v[88:91], v[138:141], v[194:197], 0
	v_mfma_f32_16x16x32_bf16 v[76:79], v[130:133], v[204:207], 0
	v_mfma_f32_16x16x32_bf16 v[72:75], v[138:141], v[204:207], 0
	v_mfma_f32_16x16x32_bf16 v[126:129], v[134:137], v[166:169], v[126:129]
	v_mfma_f32_16x16x32_bf16 v[122:125], v[142:145], v[166:169], v[122:125]
	v_mfma_f32_16x16x32_bf16 v[108:111], v[134:137], v[174:177], v[108:111]
	v_mfma_f32_16x16x32_bf16 v[104:107], v[142:145], v[174:177], v[104:107]
	v_mfma_f32_16x16x32_bf16 v[92:95], v[134:137], v[200:203], v[92:95]
	v_mfma_f32_16x16x32_bf16 v[88:91], v[142:145], v[200:203], v[88:91]
	v_mfma_f32_16x16x32_bf16 v[76:79], v[134:137], v[208:211], v[76:79]
	v_mfma_f32_16x16x32_bf16 v[72:75], v[142:145], v[208:211], v[72:75]
	s_setprio 0
	s_setprio 1
	v_mfma_f32_16x16x32_bf16 v[118:121], v[146:149], v[162:165], 0
	v_mfma_f32_16x16x32_bf16 v[114:117], v[154:157], v[162:165], 0
	v_mfma_f32_16x16x32_bf16 v[100:103], v[146:149], v[170:173], 0
	v_mfma_f32_16x16x32_bf16 v[96:99], v[154:157], v[170:173], 0
	v_mfma_f32_16x16x32_bf16 v[84:87], v[146:149], v[194:197], 0
	v_mfma_f32_16x16x32_bf16 v[80:83], v[154:157], v[194:197], 0
	v_mfma_f32_16x16x32_bf16 v[68:71], v[146:149], v[204:207], 0
	v_mfma_f32_16x16x32_bf16 v[64:67], v[154:157], v[204:207], 0
	v_mfma_f32_16x16x32_bf16 v[118:121], v[150:153], v[166:169], v[118:121]
	v_mfma_f32_16x16x32_bf16 v[114:117], v[158:161], v[166:169], v[114:117]
	v_mfma_f32_16x16x32_bf16 v[100:103], v[150:153], v[174:177], v[100:103]
	v_mfma_f32_16x16x32_bf16 v[96:99], v[158:161], v[174:177], v[96:99]
	v_mfma_f32_16x16x32_bf16 v[84:87], v[150:153], v[200:203], v[84:87]
	v_mfma_f32_16x16x32_bf16 v[80:83], v[158:161], v[200:203], v[80:83]
	v_mfma_f32_16x16x32_bf16 v[68:71], v[150:153], v[208:211], v[68:71]
	v_mfma_f32_16x16x32_bf16 v[64:67], v[158:161], v[208:211], v[64:67]
	s_setprio 0
	s_barrier
	s_add_i32 s56, s56, s58
	v_lshl_add_u64 v[216:217], s[50:51], 0, v[112:113]
	s_mov_b32 m0, s56
	ds_read_b128 v[162:165], v215 offset:16384
	ds_read_b128 v[166:169], v215 offset:17408
	ds_read_b128 v[170:173], v215 offset:18432
	ds_read_b128 v[174:177], v215 offset:19456
	ds_read_b128 v[194:197], v215 offset:20480
	ds_read_b128 v[200:203], v215 offset:21504
	ds_read_b128 v[204:207], v215 offset:22528
	ds_read_b128 v[208:211], v215 offset:23552
	global_load_lds_dwordx4 v[216:217], off
	s_add_i32 m0, s56, 0x2000
	s_add_u32 s56, s50, 0x40000
	v_lshl_add_u64 v[218:219], s[50:51], 0, v[182:183]
	s_addc_u32 s57, s51, 0
	s_add_i32 s3, s3, s58
	global_load_lds_dwordx4 v[218:219], off
	v_lshl_add_u64 v[220:221], s[56:57], 0, v[112:113]
	s_mov_b32 m0, s3
	v_lshl_add_u64 v[222:223], s[62:63], 0, v[180:181]
	global_load_lds_dwordx4 v[220:221], off
	v_lshl_add_u64 v[220:221], s[56:57], 0, v[182:183]
	s_add_i32 m0, s3, 0x2000
	s_nop 0
	global_load_lds_dwordx4 v[220:221], off
	v_lshl_add_u64 v[220:221], s[62:63], 0, v[178:179]
	s_mov_b32 m0, s43
	s_nop 0
	global_load_lds_dwordx4 v[220:221], off
	s_mov_b32 m0, s59
	s_nop 0
	global_load_lds_dwordx4 v[222:223], off
	s_waitcnt vmcnt(8)
	s_waitcnt lgkmcnt(0)
	s_barrier
	s_setprio 1
	s_waitcnt lgkmcnt(0)
	v_mfma_f32_16x16x32_bf16 v[60:63], v[130:133], v[162:165], 0
	v_mfma_f32_16x16x32_bf16 v[56:59], v[138:141], v[162:165], 0
	v_mfma_f32_16x16x32_bf16 v[44:47], v[130:133], v[170:173], 0
	v_mfma_f32_16x16x32_bf16 v[40:43], v[138:141], v[170:173], 0
	v_mfma_f32_16x16x32_bf16 v[28:31], v[130:133], v[194:197], 0
	v_mfma_f32_16x16x32_bf16 v[24:27], v[138:141], v[194:197], 0
	v_mfma_f32_16x16x32_bf16 v[12:15], v[130:133], v[204:207], 0
	v_mfma_f32_16x16x32_bf16 v[8:11], v[138:141], v[204:207], 0
	v_mfma_f32_16x16x32_bf16 v[60:63], v[134:137], v[166:169], v[60:63]
	v_mfma_f32_16x16x32_bf16 v[56:59], v[142:145], v[166:169], v[56:59]
	v_mfma_f32_16x16x32_bf16 v[44:47], v[134:137], v[174:177], v[44:47]
	v_mfma_f32_16x16x32_bf16 v[40:43], v[142:145], v[174:177], v[40:43]
	v_mfma_f32_16x16x32_bf16 v[28:31], v[134:137], v[200:203], v[28:31]
	v_mfma_f32_16x16x32_bf16 v[24:27], v[142:145], v[200:203], v[24:27]
	v_mfma_f32_16x16x32_bf16 v[12:15], v[134:137], v[208:211], v[12:15]
	v_mfma_f32_16x16x32_bf16 v[8:11], v[142:145], v[208:211], v[8:11]
	s_setprio 0
	s_setprio 1
	v_mfma_f32_16x16x32_bf16 v[52:55], v[146:149], v[162:165], 0
	v_mfma_f32_16x16x32_bf16 v[48:51], v[154:157], v[162:165], 0
	v_mfma_f32_16x16x32_bf16 v[36:39], v[146:149], v[170:173], 0
	v_mfma_f32_16x16x32_bf16 v[32:35], v[154:157], v[170:173], 0
	v_mfma_f32_16x16x32_bf16 v[20:23], v[146:149], v[194:197], 0
	v_mfma_f32_16x16x32_bf16 v[16:19], v[154:157], v[194:197], 0
	v_mfma_f32_16x16x32_bf16 v[4:7], v[146:149], v[204:207], 0
	v_mfma_f32_16x16x32_bf16 v[0:3], v[154:157], v[204:207], 0
	v_mfma_f32_16x16x32_bf16 v[52:55], v[150:153], v[166:169], v[52:55]
	v_mfma_f32_16x16x32_bf16 v[48:51], v[158:161], v[166:169], v[48:51]
	v_mfma_f32_16x16x32_bf16 v[36:39], v[150:153], v[174:177], v[36:39]
	v_mfma_f32_16x16x32_bf16 v[32:35], v[158:161], v[174:177], v[32:35]
	v_mfma_f32_16x16x32_bf16 v[20:23], v[150:153], v[200:203], v[20:23]
	v_mfma_f32_16x16x32_bf16 v[16:19], v[158:161], v[200:203], v[16:19]
	v_mfma_f32_16x16x32_bf16 v[4:7], v[150:153], v[208:211], v[4:7]
	v_mfma_f32_16x16x32_bf16 v[0:3], v[158:161], v[208:211], v[0:3]
	s_setprio 0
	s_barrier
	s_add_i32 s3, 0, 0x18000
	s_add_i32 s64, 0, 0x1c000
	v_add_u32_e32 v142, s3, v213
	v_add_u32_e32 v158, s64, v213
	ds_read_b128 v[130:133], v142
	ds_read_b128 v[134:137], v142 offset:1024
	ds_read_b128 v[138:141], v142 offset:2048
	ds_read_b128 v[142:145], v142 offset:3072
	ds_read_b128 v[146:149], v158
	ds_read_b128 v[150:153], v158 offset:1024
	ds_read_b128 v[154:157], v158 offset:2048
	ds_read_b128 v[158:161], v158 offset:3072
	s_add_u32 s56, s62, 0x40000
	s_addc_u32 s57, s63, 0
	s_mov_b32 m0, s69
	v_lshl_add_u64 v[234:235], s[56:57], 0, v[178:179]
	ds_read_b128 v[162:165], v215 offset:32768
	ds_read_b128 v[166:169], v215 offset:33792
	ds_read_b128 v[170:173], v215 offset:34816
	ds_read_b128 v[174:177], v215 offset:35840
	ds_read_b128 v[194:197], v215 offset:36864
	ds_read_b128 v[200:203], v215 offset:37888
	ds_read_b128 v[204:207], v215 offset:38912
	ds_read_b128 v[208:211], v215 offset:39936
	global_load_lds_dwordx4 v[234:235], off
	v_lshl_add_u64 v[234:235], s[56:57], 0, v[180:181]
	s_mov_b32 m0, s70
	s_nop 0
	global_load_lds_dwordx4 v[234:235], off
	s_waitcnt vmcnt(8)
	s_waitcnt lgkmcnt(0)
	s_barrier
	s_setprio 1
	s_waitcnt lgkmcnt(0)
	v_mfma_f32_16x16x32_bf16 v[126:129], v[130:133], v[162:165], v[126:129]
	v_mfma_f32_16x16x32_bf16 v[122:125], v[138:141], v[162:165], v[122:125]
	v_mfma_f32_16x16x32_bf16 v[108:111], v[130:133], v[170:173], v[108:111]
	v_mfma_f32_16x16x32_bf16 v[104:107], v[138:141], v[170:173], v[104:107]
	v_mfma_f32_16x16x32_bf16 v[92:95], v[130:133], v[194:197], v[92:95]
	v_mfma_f32_16x16x32_bf16 v[88:91], v[138:141], v[194:197], v[88:91]
	v_mfma_f32_16x16x32_bf16 v[76:79], v[130:133], v[204:207], v[76:79]
	v_mfma_f32_16x16x32_bf16 v[72:75], v[138:141], v[204:207], v[72:75]
	v_mfma_f32_16x16x32_bf16 v[126:129], v[134:137], v[166:169], v[126:129]
	v_mfma_f32_16x16x32_bf16 v[122:125], v[142:145], v[166:169], v[122:125]
	v_mfma_f32_16x16x32_bf16 v[108:111], v[134:137], v[174:177], v[108:111]
	v_mfma_f32_16x16x32_bf16 v[104:107], v[142:145], v[174:177], v[104:107]
	v_mfma_f32_16x16x32_bf16 v[92:95], v[134:137], v[200:203], v[92:95]
	v_mfma_f32_16x16x32_bf16 v[88:91], v[142:145], v[200:203], v[88:91]
	v_mfma_f32_16x16x32_bf16 v[76:79], v[134:137], v[208:211], v[76:79]
	v_mfma_f32_16x16x32_bf16 v[72:75], v[142:145], v[208:211], v[72:75]
	s_setprio 0
	s_setprio 1
	v_mfma_f32_16x16x32_bf16 v[118:121], v[146:149], v[162:165], v[118:121]
	v_mfma_f32_16x16x32_bf16 v[114:117], v[154:157], v[162:165], v[114:117]
	v_mfma_f32_16x16x32_bf16 v[100:103], v[146:149], v[170:173], v[100:103]
	v_mfma_f32_16x16x32_bf16 v[96:99], v[154:157], v[170:173], v[96:99]
	v_mfma_f32_16x16x32_bf16 v[84:87], v[146:149], v[194:197], v[84:87]
	v_mfma_f32_16x16x32_bf16 v[80:83], v[154:157], v[194:197], v[80:83]
	v_mfma_f32_16x16x32_bf16 v[68:71], v[146:149], v[204:207], v[68:71]
	v_mfma_f32_16x16x32_bf16 v[64:67], v[154:157], v[204:207], v[64:67]
	v_mfma_f32_16x16x32_bf16 v[118:121], v[150:153], v[166:169], v[118:121]
	v_mfma_f32_16x16x32_bf16 v[114:117], v[158:161], v[166:169], v[114:117]
	v_mfma_f32_16x16x32_bf16 v[100:103], v[150:153], v[174:177], v[100:103]
	v_mfma_f32_16x16x32_bf16 v[96:99], v[158:161], v[174:177], v[96:99]
	v_mfma_f32_16x16x32_bf16 v[84:87], v[150:153], v[200:203], v[84:87]
	v_mfma_f32_16x16x32_bf16 v[80:83], v[158:161], v[200:203], v[80:83]
	v_mfma_f32_16x16x32_bf16 v[68:71], v[150:153], v[208:211], v[68:71]
	v_mfma_f32_16x16x32_bf16 v[64:67], v[158:161], v[208:211], v[64:67]
	s_setprio 0
	s_barrier
	s_add_i32 s3, s3, s58
	v_lshl_add_u64 v[216:217], v[216:217], 0, s[60:61]
	s_mov_b32 m0, s3
	ds_read_b128 v[162:165], v215 offset:49152
	ds_read_b128 v[166:169], v215 offset:50176
	ds_read_b128 v[170:173], v215 offset:51200
	ds_read_b128 v[174:177], v215 offset:52224
	ds_read_b128 v[194:197], v215 offset:53248
	ds_read_b128 v[200:203], v215 offset:54272
	ds_read_b128 v[204:207], v215 offset:55296
	ds_read_b128 v[208:211], v215 offset:56320
	global_load_lds_dwordx4 v[216:217], off
	s_add_i32 m0, s3, 0x2000
	s_add_u32 s50, s50, 0x40080
	v_lshl_add_u64 v[216:217], v[218:219], 0, s[60:61]
	s_addc_u32 s51, s51, 0
	s_add_i32 s3, s64, s58
	global_load_lds_dwordx4 v[216:217], off
	v_lshl_add_u64 v[216:217], s[50:51], 0, v[112:113]
	s_mov_b32 m0, s3
	s_nop 0
	global_load_lds_dwordx4 v[216:217], off
	v_lshl_add_u64 v[216:217], s[50:51], 0, v[182:183]
	s_add_i32 m0, s3, 0x2000
	s_nop 0
	global_load_lds_dwordx4 v[216:217], off
	v_lshl_add_u64 v[216:217], v[220:221], 0, s[60:61]
	s_mov_b32 m0, s72
	s_nop 0
	global_load_lds_dwordx4 v[216:217], off
	v_lshl_add_u64 v[216:217], v[222:223], 0, s[60:61]
	s_mov_b32 m0, s73
	s_nop 0
	global_load_lds_dwordx4 v[216:217], off
	s_waitcnt vmcnt(8)
	s_waitcnt lgkmcnt(0)
	s_barrier
	s_setprio 1
	s_waitcnt lgkmcnt(0)
	v_mfma_f32_16x16x32_bf16 v[60:63], v[130:133], v[162:165], v[60:63]
	v_mfma_f32_16x16x32_bf16 v[56:59], v[138:141], v[162:165], v[56:59]
	v_mfma_f32_16x16x32_bf16 v[44:47], v[130:133], v[170:173], v[44:47]
	v_mfma_f32_16x16x32_bf16 v[40:43], v[138:141], v[170:173], v[40:43]
	v_mfma_f32_16x16x32_bf16 v[28:31], v[130:133], v[194:197], v[28:31]
	v_mfma_f32_16x16x32_bf16 v[24:27], v[138:141], v[194:197], v[24:27]
	v_mfma_f32_16x16x32_bf16 v[12:15], v[130:133], v[204:207], v[12:15]
	v_mfma_f32_16x16x32_bf16 v[8:11], v[138:141], v[204:207], v[8:11]
	v_mfma_f32_16x16x32_bf16 v[60:63], v[134:137], v[166:169], v[60:63]
	v_mfma_f32_16x16x32_bf16 v[56:59], v[142:145], v[166:169], v[56:59]
	v_mfma_f32_16x16x32_bf16 v[44:47], v[134:137], v[174:177], v[44:47]
	v_mfma_f32_16x16x32_bf16 v[40:43], v[142:145], v[174:177], v[40:43]
	v_mfma_f32_16x16x32_bf16 v[28:31], v[134:137], v[200:203], v[28:31]
	v_mfma_f32_16x16x32_bf16 v[24:27], v[142:145], v[200:203], v[24:27]
	v_mfma_f32_16x16x32_bf16 v[12:15], v[134:137], v[208:211], v[12:15]
	v_mfma_f32_16x16x32_bf16 v[8:11], v[142:145], v[208:211], v[8:11]
	s_setprio 0
	s_setprio 1
	v_mfma_f32_16x16x32_bf16 v[52:55], v[146:149], v[162:165], v[52:55]
	v_mfma_f32_16x16x32_bf16 v[48:51], v[154:157], v[162:165], v[48:51]
	v_mfma_f32_16x16x32_bf16 v[36:39], v[146:149], v[170:173], v[36:39]
	v_mfma_f32_16x16x32_bf16 v[32:35], v[154:157], v[170:173], v[32:35]
	v_mfma_f32_16x16x32_bf16 v[20:23], v[146:149], v[194:197], v[20:23]
	v_mfma_f32_16x16x32_bf16 v[16:19], v[154:157], v[194:197], v[16:19]
	v_mfma_f32_16x16x32_bf16 v[4:7], v[146:149], v[204:207], v[4:7]
	v_mfma_f32_16x16x32_bf16 v[0:3], v[154:157], v[204:207], v[0:3]
	v_mfma_f32_16x16x32_bf16 v[52:55], v[150:153], v[166:169], v[52:55]
	v_mfma_f32_16x16x32_bf16 v[48:51], v[158:161], v[166:169], v[48:51]
	v_mfma_f32_16x16x32_bf16 v[36:39], v[150:153], v[174:177], v[36:39]
	v_mfma_f32_16x16x32_bf16 v[32:35], v[158:161], v[174:177], v[32:35]
	v_mfma_f32_16x16x32_bf16 v[20:23], v[150:153], v[200:203], v[20:23]
	v_mfma_f32_16x16x32_bf16 v[16:19], v[158:161], v[200:203], v[16:19]
	v_mfma_f32_16x16x32_bf16 v[4:7], v[150:153], v[208:211], v[4:7]
	v_mfma_f32_16x16x32_bf16 v[0:3], v[158:161], v[208:211], v[0:3]
	s_setprio 0
	s_barrier
	s_add_i32 s85, s85, 2
	s_add_u32 s44, s44, 0x100
	s_addc_u32 s45, s45, 0
	s_add_u32 s41, s41, 0x100
	s_addc_u32 s84, s84, 0
	s_cmp_gt_u32 s85, 13
	s_cbranch_scc0 .LBB0_1386
	s_branch .Lpeel_after_7

.LBB0_1470:
	s_ashr_i32 s17, s16, 31
	s_lshl_b64 s[18:19], s[16:17], 19
	s_add_u32 s18, s25, s18
	s_addc_u32 s19, s29, s19
	s_and_b64 s[20:21], s[4:5], exec
	s_cselect_b32 s17, s19, s23
	s_cselect_b32 s50, s18, s22
	s_ashr_i32 s15, s14, 31
	s_lshl_b64 s[20:21], s[14:15], 19
	s_add_u32 s20, s36, s20
	s_addc_u32 s21, s37, s21
	s_and_b64 s[34:35], s[4:5], exec
	s_cselect_b32 s15, s21, s31
	s_cselect_b32 s51, s20, s30
	s_add_u32 s22, s22, 0x40080
	s_addc_u32 s23, s23, 0
	s_add_u32 s55, s30, 0x100
	s_addc_u32 s58, s31, 0
	s_mov_b32 s59, -2
	s_add_u32 s3, s22, 0xfffc0080
	s_addc_u32 s30, s23, -1
	s_add_i32 s56, 0, 0x10000
	s_cmp_eq_u32 s59, 12
	s_cselect_b32 s35, s17, s30
	s_cselect_b32 s34, s50, s3
	s_cselect_b32 s31, s15, s58
	s_cselect_b32 s30, s51, s55
	s_add_i32 s3, 0, 0x14000
	v_add_u32_e32 v122, s56, v204
	v_add_u32_e32 v170, s3, v204
	ds_read_b128 v[76:79], v122
	ds_read_b128 v[80:83], v122 offset:1024
	ds_read_b128 v[118:121], v122 offset:2048
	ds_read_b128 v[122:125], v122 offset:3072
	ds_read_b128 v[146:149], v170
	ds_read_b128 v[150:153], v170 offset:1024
	ds_read_b128 v[166:169], v170 offset:2048
	ds_read_b128 v[170:173], v170 offset:3072
	v_lshl_add_u64 v[220:221], s[22:23], 0, v[162:163]
	s_add_i32 m0, s40, 0xc000
	ds_read_b128 v[174:177], v206
	ds_read_b128 v[178:181], v206 offset:1024
	ds_read_b128 v[182:185], v206 offset:2048
	ds_read_b128 v[194:197], v206 offset:3072
	ds_read_b128 v[198:201], v206 offset:4096
	ds_read_b128 v[208:211], v206 offset:5120
	ds_read_b128 v[212:215], v206 offset:6144
	ds_read_b128 v[216:219], v206 offset:7168
	global_load_lds_dwordx4 v[220:221], off
	v_lshl_add_u64 v[220:221], s[22:23], 0, v[164:165]
	s_add_i32 m0, s40, 0xe000
	s_nop 0
	global_load_lds_dwordx4 v[220:221], off
	s_waitcnt vmcnt(8)
	s_waitcnt lgkmcnt(0)
	s_barrier
	s_setprio 1
	s_waitcnt lgkmcnt(0)
	v_mfma_f32_16x16x32_bf16 v[142:145], v[76:79], v[174:177], 0
	v_mfma_f32_16x16x32_bf16 v[134:137], v[118:121], v[174:177], 0
	v_mfma_f32_16x16x32_bf16 v[126:129], v[76:79], v[182:185], 0
	v_mfma_f32_16x16x32_bf16 v[108:111], v[118:121], v[182:185], 0
	v_mfma_f32_16x16x32_bf16 v[100:103], v[76:79], v[198:201], 0
	v_mfma_f32_16x16x32_bf16 v[92:95], v[118:121], v[198:201], 0
	v_mfma_f32_16x16x32_bf16 v[84:87], v[76:79], v[212:215], 0
	v_mfma_f32_16x16x32_bf16 v[68:71], v[118:121], v[212:215], 0
	v_mfma_f32_16x16x32_bf16 v[142:145], v[80:83], v[178:181], v[142:145]
	v_mfma_f32_16x16x32_bf16 v[134:137], v[122:125], v[178:181], v[134:137]
	v_mfma_f32_16x16x32_bf16 v[126:129], v[80:83], v[194:197], v[126:129]
	v_mfma_f32_16x16x32_bf16 v[108:111], v[122:125], v[194:197], v[108:111]
	v_mfma_f32_16x16x32_bf16 v[100:103], v[80:83], v[208:211], v[100:103]
	v_mfma_f32_16x16x32_bf16 v[92:95], v[122:125], v[208:211], v[92:95]
	v_mfma_f32_16x16x32_bf16 v[84:87], v[80:83], v[216:219], v[84:87]
	v_mfma_f32_16x16x32_bf16 v[68:71], v[122:125], v[216:219], v[68:71]
	s_setprio 0
	s_setprio 1
	v_mfma_f32_16x16x32_bf16 v[138:141], v[146:149], v[174:177], 0
	v_mfma_f32_16x16x32_bf16 v[130:133], v[166:169], v[174:177], 0
	v_mfma_f32_16x16x32_bf16 v[114:117], v[146:149], v[182:185], 0
	v_mfma_f32_16x16x32_bf16 v[104:107], v[166:169], v[182:185], 0
	v_mfma_f32_16x16x32_bf16 v[96:99], v[146:149], v[198:201], 0
	v_mfma_f32_16x16x32_bf16 v[88:91], v[166:169], v[198:201], 0
	v_mfma_f32_16x16x32_bf16 v[72:75], v[146:149], v[212:215], 0
	v_mfma_f32_16x16x32_bf16 v[64:67], v[166:169], v[212:215], 0
	v_mfma_f32_16x16x32_bf16 v[138:141], v[150:153], v[178:181], v[138:141]
	v_mfma_f32_16x16x32_bf16 v[130:133], v[170:173], v[178:181], v[130:133]
	v_mfma_f32_16x16x32_bf16 v[114:117], v[150:153], v[194:197], v[114:117]
	v_mfma_f32_16x16x32_bf16 v[104:107], v[170:173], v[194:197], v[104:107]
	v_mfma_f32_16x16x32_bf16 v[96:99], v[150:153], v[208:211], v[96:99]
	v_mfma_f32_16x16x32_bf16 v[88:91], v[170:173], v[208:211], v[88:91]
	v_mfma_f32_16x16x32_bf16 v[72:75], v[150:153], v[216:219], v[72:75]
	v_mfma_f32_16x16x32_bf16 v[64:67], v[170:173], v[216:219], v[64:67]
	s_setprio 0
	s_barrier
	s_add_i32 s56, s56, s39
	v_lshl_add_u64 v[220:221], s[30:31], 0, v[112:113]
	s_mov_b32 m0, s56
	ds_read_b128 v[174:177], v206 offset:16384
	ds_read_b128 v[178:181], v206 offset:17408
	ds_read_b128 v[182:185], v206 offset:18432
	ds_read_b128 v[194:197], v206 offset:19456
	ds_read_b128 v[198:201], v206 offset:20480
	ds_read_b128 v[208:211], v206 offset:21504
	ds_read_b128 v[212:215], v206 offset:22528
	ds_read_b128 v[216:219], v206 offset:23552
	global_load_lds_dwordx4 v[220:221], off
	s_add_i32 m0, s56, 0x2000
	s_add_u32 s56, s30, 0x40000
	v_lshl_add_u64 v[222:223], s[30:31], 0, v[154:155]
	s_addc_u32 s57, s31, 0
	s_add_i32 s3, s3, s39
	global_load_lds_dwordx4 v[222:223], off
	v_lshl_add_u64 v[234:235], s[56:57], 0, v[112:113]
	s_mov_b32 m0, s3
	v_lshl_add_u64 v[236:237], s[34:35], 0, v[156:157]
	global_load_lds_dwordx4 v[234:235], off
	v_lshl_add_u64 v[234:235], s[56:57], 0, v[154:155]
	s_add_i32 m0, s3, 0x2000
	s_nop 0
	global_load_lds_dwordx4 v[234:235], off
	v_lshl_add_u64 v[234:235], s[34:35], 0, v[158:159]
	s_mov_b32 m0, s40
	s_nop 0
	global_load_lds_dwordx4 v[234:235], off
	s_mov_b32 m0, s41
	s_nop 0
	global_load_lds_dwordx4 v[236:237], off
	s_waitcnt vmcnt(8)
	s_waitcnt lgkmcnt(0)
	s_barrier
	s_setprio 1
	s_waitcnt lgkmcnt(0)
	v_mfma_f32_16x16x32_bf16 v[60:63], v[76:79], v[174:177], 0
	v_mfma_f32_16x16x32_bf16 v[52:55], v[118:121], v[174:177], 0
	v_mfma_f32_16x16x32_bf16 v[44:47], v[76:79], v[182:185], 0
	v_mfma_f32_16x16x32_bf16 v[36:39], v[118:121], v[182:185], 0
	v_mfma_f32_16x16x32_bf16 v[28:31], v[76:79], v[198:201], 0
	v_mfma_f32_16x16x32_bf16 v[20:23], v[118:121], v[198:201], 0
	v_mfma_f32_16x16x32_bf16 v[12:15], v[76:79], v[212:215], 0
	v_mfma_f32_16x16x32_bf16 v[4:7], v[118:121], v[212:215], 0
	v_mfma_f32_16x16x32_bf16 v[60:63], v[80:83], v[178:181], v[60:63]
	v_mfma_f32_16x16x32_bf16 v[52:55], v[122:125], v[178:181], v[52:55]
	v_mfma_f32_16x16x32_bf16 v[44:47], v[80:83], v[194:197], v[44:47]
	v_mfma_f32_16x16x32_bf16 v[36:39], v[122:125], v[194:197], v[36:39]
	v_mfma_f32_16x16x32_bf16 v[28:31], v[80:83], v[208:211], v[28:31]
	v_mfma_f32_16x16x32_bf16 v[20:23], v[122:125], v[208:211], v[20:23]
	v_mfma_f32_16x16x32_bf16 v[12:15], v[80:83], v[216:219], v[12:15]
	v_mfma_f32_16x16x32_bf16 v[4:7], v[122:125], v[216:219], v[4:7]
	s_setprio 0
	s_setprio 1
	v_mfma_f32_16x16x32_bf16 v[56:59], v[146:149], v[174:177], 0
	v_mfma_f32_16x16x32_bf16 v[48:51], v[166:169], v[174:177], 0
	v_mfma_f32_16x16x32_bf16 v[40:43], v[146:149], v[182:185], 0
	v_mfma_f32_16x16x32_bf16 v[32:35], v[166:169], v[182:185], 0
	v_mfma_f32_16x16x32_bf16 v[24:27], v[146:149], v[198:201], 0
	v_mfma_f32_16x16x32_bf16 v[16:19], v[166:169], v[198:201], 0
	v_mfma_f32_16x16x32_bf16 v[8:11], v[146:149], v[212:215], 0
	v_mfma_f32_16x16x32_bf16 v[0:3], v[166:169], v[212:215], 0
	v_mfma_f32_16x16x32_bf16 v[56:59], v[150:153], v[178:181], v[56:59]
	v_mfma_f32_16x16x32_bf16 v[48:51], v[170:173], v[178:181], v[48:51]
	v_mfma_f32_16x16x32_bf16 v[40:43], v[150:153], v[194:197], v[40:43]
	v_mfma_f32_16x16x32_bf16 v[32:35], v[170:173], v[194:197], v[32:35]
	v_mfma_f32_16x16x32_bf16 v[24:27], v[150:153], v[208:211], v[24:27]
	v_mfma_f32_16x16x32_bf16 v[16:19], v[170:173], v[208:211], v[16:19]
	v_mfma_f32_16x16x32_bf16 v[8:11], v[150:153], v[216:219], v[8:11]
	v_mfma_f32_16x16x32_bf16 v[0:3], v[170:173], v[216:219], v[0:3]
	s_setprio 0
	s_barrier
	s_add_i32 s3, 0, 0x18000
	s_add_i32 s56, 0, 0x1c000
	v_add_u32_e32 v122, s3, v204
	v_add_u32_e32 v170, s56, v204
	ds_read_b128 v[76:79], v122
	ds_read_b128 v[80:83], v122 offset:1024
	ds_read_b128 v[118:121], v122 offset:2048
	ds_read_b128 v[122:125], v122 offset:3072
	ds_read_b128 v[146:149], v170
	ds_read_b128 v[150:153], v170 offset:1024
	ds_read_b128 v[166:169], v170 offset:2048
	ds_read_b128 v[170:173], v170 offset:3072
	s_add_u32 s34, s34, 0x40000
	s_addc_u32 s35, s35, 0
	s_mov_b32 m0, s42
	v_lshl_add_u64 v[238:239], s[34:35], 0, v[158:159]
	ds_read_b128 v[174:177], v206 offset:32768
	ds_read_b128 v[178:181], v206 offset:33792
	ds_read_b128 v[182:185], v206 offset:34816
	ds_read_b128 v[194:197], v206 offset:35840
	ds_read_b128 v[198:201], v206 offset:36864
	ds_read_b128 v[208:211], v206 offset:37888
	ds_read_b128 v[212:215], v206 offset:38912
	ds_read_b128 v[216:219], v206 offset:39936
	global_load_lds_dwordx4 v[238:239], off
	v_lshl_add_u64 v[238:239], s[34:35], 0, v[156:157]
	s_mov_b32 m0, s43
	s_nop 0
	global_load_lds_dwordx4 v[238:239], off
	s_waitcnt vmcnt(8)
	s_waitcnt lgkmcnt(0)
	s_barrier
	s_setprio 1
	s_waitcnt lgkmcnt(0)
	v_mfma_f32_16x16x32_bf16 v[142:145], v[76:79], v[174:177], v[142:145]
	v_mfma_f32_16x16x32_bf16 v[134:137], v[118:121], v[174:177], v[134:137]
	v_mfma_f32_16x16x32_bf16 v[126:129], v[76:79], v[182:185], v[126:129]
	v_mfma_f32_16x16x32_bf16 v[108:111], v[118:121], v[182:185], v[108:111]
	v_mfma_f32_16x16x32_bf16 v[100:103], v[76:79], v[198:201], v[100:103]
	v_mfma_f32_16x16x32_bf16 v[92:95], v[118:121], v[198:201], v[92:95]
	v_mfma_f32_16x16x32_bf16 v[84:87], v[76:79], v[212:215], v[84:87]
	v_mfma_f32_16x16x32_bf16 v[68:71], v[118:121], v[212:215], v[68:71]
	v_mfma_f32_16x16x32_bf16 v[142:145], v[80:83], v[178:181], v[142:145]
	v_mfma_f32_16x16x32_bf16 v[134:137], v[122:125], v[178:181], v[134:137]
	v_mfma_f32_16x16x32_bf16 v[126:129], v[80:83], v[194:197], v[126:129]
	v_mfma_f32_16x16x32_bf16 v[108:111], v[122:125], v[194:197], v[108:111]
	v_mfma_f32_16x16x32_bf16 v[100:103], v[80:83], v[208:211], v[100:103]
	v_mfma_f32_16x16x32_bf16 v[92:95], v[122:125], v[208:211], v[92:95]
	v_mfma_f32_16x16x32_bf16 v[84:87], v[80:83], v[216:219], v[84:87]
	v_mfma_f32_16x16x32_bf16 v[68:71], v[122:125], v[216:219], v[68:71]
	s_setprio 0
	s_setprio 1
	v_mfma_f32_16x16x32_bf16 v[138:141], v[146:149], v[174:177], v[138:141]
	v_mfma_f32_16x16x32_bf16 v[130:133], v[166:169], v[174:177], v[130:133]
	v_mfma_f32_16x16x32_bf16 v[114:117], v[146:149], v[182:185], v[114:117]
	v_mfma_f32_16x16x32_bf16 v[104:107], v[166:169], v[182:185], v[104:107]
	v_mfma_f32_16x16x32_bf16 v[96:99], v[146:149], v[198:201], v[96:99]
	v_mfma_f32_16x16x32_bf16 v[88:91], v[166:169], v[198:201], v[88:91]
	v_mfma_f32_16x16x32_bf16 v[72:75], v[146:149], v[212:215], v[72:75]
	v_mfma_f32_16x16x32_bf16 v[64:67], v[166:169], v[212:215], v[64:67]
	v_mfma_f32_16x16x32_bf16 v[138:141], v[150:153], v[178:181], v[138:141]
	v_mfma_f32_16x16x32_bf16 v[130:133], v[170:173], v[178:181], v[130:133]
	v_mfma_f32_16x16x32_bf16 v[114:117], v[150:153], v[194:197], v[114:117]
	v_mfma_f32_16x16x32_bf16 v[104:107], v[170:173], v[194:197], v[104:107]
	v_mfma_f32_16x16x32_bf16 v[96:99], v[150:153], v[208:211], v[96:99]
	v_mfma_f32_16x16x32_bf16 v[88:91], v[170:173], v[208:211], v[88:91]
	v_mfma_f32_16x16x32_bf16 v[72:75], v[150:153], v[216:219], v[72:75]
	v_mfma_f32_16x16x32_bf16 v[64:67], v[170:173], v[216:219], v[64:67]
	s_setprio 0
	s_barrier
	s_add_i32 s3, s3, s39
	v_lshl_add_u64 v[220:221], v[220:221], 0, s[60:61]
	s_mov_b32 m0, s3
	ds_read_b128 v[174:177], v206 offset:49152
	ds_read_b128 v[178:181], v206 offset:50176
	ds_read_b128 v[182:185], v206 offset:51200
	ds_read_b128 v[194:197], v206 offset:52224
	ds_read_b128 v[198:201], v206 offset:53248
	ds_read_b128 v[208:211], v206 offset:54272
	ds_read_b128 v[212:215], v206 offset:55296
	ds_read_b128 v[216:219], v206 offset:56320
	global_load_lds_dwordx4 v[220:221], off
	s_add_i32 m0, s3, 0x2000
	s_add_u32 s30, s30, 0x40080
	v_lshl_add_u64 v[220:221], v[222:223], 0, s[60:61]
	s_addc_u32 s31, s31, 0
	s_add_i32 s3, s56, s39
	global_load_lds_dwordx4 v[220:221], off
	v_lshl_add_u64 v[220:221], s[30:31], 0, v[112:113]
	s_mov_b32 m0, s3
	s_nop 0
	global_load_lds_dwordx4 v[220:221], off
	v_lshl_add_u64 v[220:221], s[30:31], 0, v[154:155]
	s_add_i32 m0, s3, 0x2000
	s_nop 0
	global_load_lds_dwordx4 v[220:221], off
	v_lshl_add_u64 v[220:221], v[234:235], 0, s[60:61]
	s_mov_b32 m0, s44
	s_nop 0
	global_load_lds_dwordx4 v[220:221], off
	v_lshl_add_u64 v[220:221], v[236:237], 0, s[60:61]
	s_mov_b32 m0, s45
	s_nop 0
	global_load_lds_dwordx4 v[220:221], off
	s_waitcnt vmcnt(8)
	s_waitcnt lgkmcnt(0)
	s_barrier
	s_setprio 1
	s_waitcnt lgkmcnt(0)
	v_mfma_f32_16x16x32_bf16 v[60:63], v[76:79], v[174:177], v[60:63]
	v_mfma_f32_16x16x32_bf16 v[52:55], v[118:121], v[174:177], v[52:55]
	v_mfma_f32_16x16x32_bf16 v[44:47], v[76:79], v[182:185], v[44:47]
	v_mfma_f32_16x16x32_bf16 v[36:39], v[118:121], v[182:185], v[36:39]
	v_mfma_f32_16x16x32_bf16 v[28:31], v[76:79], v[198:201], v[28:31]
	v_mfma_f32_16x16x32_bf16 v[20:23], v[118:121], v[198:201], v[20:23]
	v_mfma_f32_16x16x32_bf16 v[12:15], v[76:79], v[212:215], v[12:15]
	v_mfma_f32_16x16x32_bf16 v[4:7], v[118:121], v[212:215], v[4:7]
	v_mfma_f32_16x16x32_bf16 v[60:63], v[80:83], v[178:181], v[60:63]
	v_mfma_f32_16x16x32_bf16 v[52:55], v[122:125], v[178:181], v[52:55]
	v_mfma_f32_16x16x32_bf16 v[44:47], v[80:83], v[194:197], v[44:47]
	v_mfma_f32_16x16x32_bf16 v[36:39], v[122:125], v[194:197], v[36:39]
	v_mfma_f32_16x16x32_bf16 v[28:31], v[80:83], v[208:211], v[28:31]
	v_mfma_f32_16x16x32_bf16 v[20:23], v[122:125], v[208:211], v[20:23]
	v_mfma_f32_16x16x32_bf16 v[12:15], v[80:83], v[216:219], v[12:15]
	v_mfma_f32_16x16x32_bf16 v[4:7], v[122:125], v[216:219], v[4:7]
	s_setprio 0
	s_setprio 1
	v_mfma_f32_16x16x32_bf16 v[56:59], v[146:149], v[174:177], v[56:59]
	v_mfma_f32_16x16x32_bf16 v[48:51], v[166:169], v[174:177], v[48:51]
	v_mfma_f32_16x16x32_bf16 v[40:43], v[146:149], v[182:185], v[40:43]
	v_mfma_f32_16x16x32_bf16 v[32:35], v[166:169], v[182:185], v[32:35]
	v_mfma_f32_16x16x32_bf16 v[24:27], v[146:149], v[198:201], v[24:27]
	v_mfma_f32_16x16x32_bf16 v[16:19], v[166:169], v[198:201], v[16:19]
	v_mfma_f32_16x16x32_bf16 v[8:11], v[146:149], v[212:215], v[8:11]
	v_mfma_f32_16x16x32_bf16 v[0:3], v[166:169], v[212:215], v[0:3]
	v_mfma_f32_16x16x32_bf16 v[56:59], v[150:153], v[178:181], v[56:59]
	v_mfma_f32_16x16x32_bf16 v[48:51], v[170:173], v[178:181], v[48:51]
	v_mfma_f32_16x16x32_bf16 v[40:43], v[150:153], v[194:197], v[40:43]
	v_mfma_f32_16x16x32_bf16 v[32:35], v[170:173], v[194:197], v[32:35]
	v_mfma_f32_16x16x32_bf16 v[24:27], v[150:153], v[208:211], v[24:27]
	v_mfma_f32_16x16x32_bf16 v[16:19], v[170:173], v[208:211], v[16:19]
	v_mfma_f32_16x16x32_bf16 v[8:11], v[150:153], v[216:219], v[8:11]
	v_mfma_f32_16x16x32_bf16 v[0:3], v[170:173], v[216:219], v[0:3]
	s_setprio 0
	s_barrier
	s_add_i32 s59, s59, 2
	s_add_u32 s22, s22, 0x100
	s_addc_u32 s23, s23, 0
	s_add_u32 s55, s55, 0x100
	s_addc_u32 s58, s58, 0
	s_cmp_gt_u32 s59, 13
	s_cbranch_scc0 .LBB0_1471
	s_branch .Lpeel_after_8

.LBB0_1556:
	s_add_u32 s73, s40, 0x100
	s_addc_u32 s82, s41, 0
	s_mov_b32 s83, -2
	s_waitcnt lgkmcnt(0)
	s_add_u32 s6, s36, 0x100
	s_addc_u32 s7, s37, 0
	s_add_i32 s3, 0, 0x10000
	s_cmp_eq_u32 s83, 40
	s_cselect_b32 s41, s31, s7
	s_cselect_b32 s40, s30, s6
	s_cselect_b32 s39, s35, s82
	s_cselect_b32 s38, s34, s73
	s_add_i32 s56, 0, 0x14000
	v_add_u32_e32 v142, s3, v248
	v_add_u32_e32 v158, s56, v248
	ds_read_b128 v[130:133], v142
	ds_read_b128 v[134:137], v142 offset:1024
	ds_read_b128 v[138:141], v142 offset:2048
	ds_read_b128 v[142:145], v142 offset:3072
	ds_read_b128 v[146:149], v158
	ds_read_b128 v[150:153], v158 offset:1024
	ds_read_b128 v[154:157], v158 offset:2048
	ds_read_b128 v[158:161], v158 offset:3072
	v_lshl_add_u64 v[212:213], s[36:37], 0, v[204:205]
	s_add_i32 m0, s50, 0xc000
	ds_read_b128 v[162:165], v250
	ds_read_b128 v[166:169], v250 offset:1024
	ds_read_b128 v[170:173], v250 offset:2048
	ds_read_b128 v[174:177], v250 offset:3072
	ds_read_b128 v[178:181], v250 offset:4096
	ds_read_b128 v[182:185], v250 offset:5120
	ds_read_b128 v[194:197], v250 offset:6144
	ds_read_b128 v[208:211], v250 offset:7168
	global_load_lds_dwordx4 v[212:213], off
	v_lshl_add_u64 v[212:213], s[36:37], 0, v[206:207]
	s_add_i32 m0, s50, 0xe000
	s_nop 0
	global_load_lds_dwordx4 v[212:213], off
	s_waitcnt vmcnt(8)
	s_waitcnt lgkmcnt(0)
	s_barrier
	s_setprio 1
	s_waitcnt lgkmcnt(0)
	v_mfma_f32_16x16x32_bf16 v[126:129], v[130:133], v[162:165], 0
	v_mfma_f32_16x16x32_bf16 v[122:125], v[138:141], v[162:165], 0
	v_mfma_f32_16x16x32_bf16 v[108:111], v[130:133], v[170:173], 0
	v_mfma_f32_16x16x32_bf16 v[104:107], v[138:141], v[170:173], 0
	v_mfma_f32_16x16x32_bf16 v[92:95], v[130:133], v[178:181], 0
	v_mfma_f32_16x16x32_bf16 v[88:91], v[138:141], v[178:181], 0
	v_mfma_f32_16x16x32_bf16 v[76:79], v[130:133], v[194:197], 0
	v_mfma_f32_16x16x32_bf16 v[72:75], v[138:141], v[194:197], 0
	v_mfma_f32_16x16x32_bf16 v[126:129], v[134:137], v[166:169], v[126:129]
	v_mfma_f32_16x16x32_bf16 v[122:125], v[142:145], v[166:169], v[122:125]
	v_mfma_f32_16x16x32_bf16 v[108:111], v[134:137], v[174:177], v[108:111]
	v_mfma_f32_16x16x32_bf16 v[104:107], v[142:145], v[174:177], v[104:107]
	v_mfma_f32_16x16x32_bf16 v[92:95], v[134:137], v[182:185], v[92:95]
	v_mfma_f32_16x16x32_bf16 v[88:91], v[142:145], v[182:185], v[88:91]
	v_mfma_f32_16x16x32_bf16 v[76:79], v[134:137], v[208:211], v[76:79]
	v_mfma_f32_16x16x32_bf16 v[72:75], v[142:145], v[208:211], v[72:75]
	s_setprio 0
	s_setprio 1
	v_mfma_f32_16x16x32_bf16 v[118:121], v[146:149], v[162:165], 0
	v_mfma_f32_16x16x32_bf16 v[114:117], v[154:157], v[162:165], 0
	v_mfma_f32_16x16x32_bf16 v[100:103], v[146:149], v[170:173], 0
	v_mfma_f32_16x16x32_bf16 v[96:99], v[154:157], v[170:173], 0
	v_mfma_f32_16x16x32_bf16 v[84:87], v[146:149], v[178:181], 0
	v_mfma_f32_16x16x32_bf16 v[80:83], v[154:157], v[178:181], 0
	v_mfma_f32_16x16x32_bf16 v[68:71], v[146:149], v[194:197], 0
	v_mfma_f32_16x16x32_bf16 v[64:67], v[154:157], v[194:197], 0
	v_mfma_f32_16x16x32_bf16 v[118:121], v[150:153], v[166:169], v[118:121]
	v_mfma_f32_16x16x32_bf16 v[114:117], v[158:161], v[166:169], v[114:117]
	v_mfma_f32_16x16x32_bf16 v[100:103], v[150:153], v[174:177], v[100:103]
	v_mfma_f32_16x16x32_bf16 v[96:99], v[158:161], v[174:177], v[96:99]
	v_mfma_f32_16x16x32_bf16 v[84:87], v[150:153], v[182:185], v[84:87]
	v_mfma_f32_16x16x32_bf16 v[80:83], v[158:161], v[182:185], v[80:83]
	v_mfma_f32_16x16x32_bf16 v[68:71], v[150:153], v[208:211], v[68:71]
	v_mfma_f32_16x16x32_bf16 v[64:67], v[158:161], v[208:211], v[64:67]
	s_setprio 0
	s_barrier
	s_add_i32 s3, s3, s42
	v_lshl_add_u64 v[212:213], s[38:39], 0, v[112:113]
	s_mov_b32 m0, s3
	ds_read_b128 v[162:165], v250 offset:16384
	ds_read_b128 v[166:169], v250 offset:17408
	ds_read_b128 v[170:173], v250 offset:18432
	ds_read_b128 v[174:177], v250 offset:19456
	ds_read_b128 v[178:181], v250 offset:20480
	ds_read_b128 v[182:185], v250 offset:21504
	ds_read_b128 v[194:197], v250 offset:22528
	ds_read_b128 v[208:211], v250 offset:23552
	global_load_lds_dwordx4 v[212:213], off
	s_add_i32 m0, s3, 0x2000
	s_add_u32 s36, s38, 0xb0000
	v_lshl_add_u64 v[214:215], s[38:39], 0, v[202:203]
	s_addc_u32 s37, s39, 0
	s_add_i32 s3, s56, s42
	global_load_lds_dwordx4 v[214:215], off
	v_lshl_add_u64 v[216:217], s[36:37], 0, v[112:113]
	s_mov_b32 m0, s3
	v_lshl_add_u64 v[218:219], s[40:41], 0, v[200:201]
	global_load_lds_dwordx4 v[216:217], off
	v_lshl_add_u64 v[216:217], s[36:37], 0, v[202:203]
	s_add_i32 m0, s3, 0x2000
	s_nop 0
	global_load_lds_dwordx4 v[216:217], off
	v_lshl_add_u64 v[216:217], s[40:41], 0, v[198:199]
	s_mov_b32 m0, s50
	s_nop 0
	global_load_lds_dwordx4 v[216:217], off
	s_mov_b32 m0, s51
	s_nop 0
	global_load_lds_dwordx4 v[218:219], off
	s_waitcnt vmcnt(8)
	s_waitcnt lgkmcnt(0)
	s_barrier
	s_setprio 1
	s_waitcnt lgkmcnt(0)
	v_mfma_f32_16x16x32_bf16 v[60:63], v[130:133], v[162:165], 0
	v_mfma_f32_16x16x32_bf16 v[56:59], v[138:141], v[162:165], 0
	v_mfma_f32_16x16x32_bf16 v[44:47], v[130:133], v[170:173], 0
	v_mfma_f32_16x16x32_bf16 v[40:43], v[138:141], v[170:173], 0
	v_mfma_f32_16x16x32_bf16 v[28:31], v[130:133], v[178:181], 0
	v_mfma_f32_16x16x32_bf16 v[24:27], v[138:141], v[178:181], 0
	v_mfma_f32_16x16x32_bf16 v[12:15], v[130:133], v[194:197], 0
	v_mfma_f32_16x16x32_bf16 v[8:11], v[138:141], v[194:197], 0
	v_mfma_f32_16x16x32_bf16 v[60:63], v[134:137], v[166:169], v[60:63]
	v_mfma_f32_16x16x32_bf16 v[56:59], v[142:145], v[166:169], v[56:59]
	v_mfma_f32_16x16x32_bf16 v[44:47], v[134:137], v[174:177], v[44:47]
	v_mfma_f32_16x16x32_bf16 v[40:43], v[142:145], v[174:177], v[40:43]
	v_mfma_f32_16x16x32_bf16 v[28:31], v[134:137], v[182:185], v[28:31]
	v_mfma_f32_16x16x32_bf16 v[24:27], v[142:145], v[182:185], v[24:27]
	v_mfma_f32_16x16x32_bf16 v[12:15], v[134:137], v[208:211], v[12:15]
	v_mfma_f32_16x16x32_bf16 v[8:11], v[142:145], v[208:211], v[8:11]
	s_setprio 0
	s_setprio 1
	v_mfma_f32_16x16x32_bf16 v[52:55], v[146:149], v[162:165], 0
	v_mfma_f32_16x16x32_bf16 v[48:51], v[154:157], v[162:165], 0
	v_mfma_f32_16x16x32_bf16 v[36:39], v[146:149], v[170:173], 0
	v_mfma_f32_16x16x32_bf16 v[32:35], v[154:157], v[170:173], 0
	v_mfma_f32_16x16x32_bf16 v[20:23], v[146:149], v[178:181], 0
	v_mfma_f32_16x16x32_bf16 v[16:19], v[154:157], v[178:181], 0
	v_mfma_f32_16x16x32_bf16 v[4:7], v[146:149], v[194:197], 0
	v_mfma_f32_16x16x32_bf16 v[0:3], v[154:157], v[194:197], 0
	v_mfma_f32_16x16x32_bf16 v[52:55], v[150:153], v[166:169], v[52:55]
	v_mfma_f32_16x16x32_bf16 v[48:51], v[158:161], v[166:169], v[48:51]
	v_mfma_f32_16x16x32_bf16 v[36:39], v[150:153], v[174:177], v[36:39]
	v_mfma_f32_16x16x32_bf16 v[32:35], v[158:161], v[174:177], v[32:35]
	v_mfma_f32_16x16x32_bf16 v[20:23], v[150:153], v[182:185], v[20:23]
	v_mfma_f32_16x16x32_bf16 v[16:19], v[158:161], v[182:185], v[16:19]
	v_mfma_f32_16x16x32_bf16 v[4:7], v[150:153], v[208:211], v[4:7]
	v_mfma_f32_16x16x32_bf16 v[0:3], v[158:161], v[208:211], v[0:3]
	s_setprio 0
	s_barrier
	s_add_i32 s3, 0, 0x18000
	s_add_i32 s56, 0, 0x1c000
	v_add_u32_e32 v142, s3, v248
	v_add_u32_e32 v158, s56, v248
	ds_read_b128 v[130:133], v142
	ds_read_b128 v[134:137], v142 offset:1024
	ds_read_b128 v[138:141], v142 offset:2048
	ds_read_b128 v[142:145], v142 offset:3072
	ds_read_b128 v[146:149], v158
	ds_read_b128 v[150:153], v158 offset:1024
	ds_read_b128 v[154:157], v158 offset:2048
	ds_read_b128 v[158:161], v158 offset:3072
	s_add_u32 s36, s40, 0xb0000
	s_addc_u32 s37, s41, 0
	s_mov_b32 m0, s55
	v_lshl_add_u64 v[220:221], s[36:37], 0, v[198:199]
	ds_read_b128 v[162:165], v250 offset:32768
	ds_read_b128 v[166:169], v250 offset:33792
	ds_read_b128 v[170:173], v250 offset:34816
	ds_read_b128 v[174:177], v250 offset:35840
	ds_read_b128 v[178:181], v250 offset:36864
	ds_read_b128 v[182:185], v250 offset:37888
	ds_read_b128 v[194:197], v250 offset:38912
	ds_read_b128 v[208:211], v250 offset:39936
	global_load_lds_dwordx4 v[220:221], off
	v_lshl_add_u64 v[220:221], s[36:37], 0, v[200:201]
	s_mov_b32 m0, s58
	s_nop 0
	global_load_lds_dwordx4 v[220:221], off
	s_waitcnt vmcnt(8)
	s_waitcnt lgkmcnt(0)
	s_barrier
	s_setprio 1
	s_waitcnt lgkmcnt(0)
	v_mfma_f32_16x16x32_bf16 v[126:129], v[130:133], v[162:165], v[126:129]
	v_mfma_f32_16x16x32_bf16 v[122:125], v[138:141], v[162:165], v[122:125]
	v_mfma_f32_16x16x32_bf16 v[108:111], v[130:133], v[170:173], v[108:111]
	v_mfma_f32_16x16x32_bf16 v[104:107], v[138:141], v[170:173], v[104:107]
	v_mfma_f32_16x16x32_bf16 v[92:95], v[130:133], v[178:181], v[92:95]
	v_mfma_f32_16x16x32_bf16 v[88:91], v[138:141], v[178:181], v[88:91]
	v_mfma_f32_16x16x32_bf16 v[76:79], v[130:133], v[194:197], v[76:79]
	v_mfma_f32_16x16x32_bf16 v[72:75], v[138:141], v[194:197], v[72:75]
	v_mfma_f32_16x16x32_bf16 v[126:129], v[134:137], v[166:169], v[126:129]
	v_mfma_f32_16x16x32_bf16 v[122:125], v[142:145], v[166:169], v[122:125]
	v_mfma_f32_16x16x32_bf16 v[108:111], v[134:137], v[174:177], v[108:111]
	v_mfma_f32_16x16x32_bf16 v[104:107], v[142:145], v[174:177], v[104:107]
	v_mfma_f32_16x16x32_bf16 v[92:95], v[134:137], v[182:185], v[92:95]
	v_mfma_f32_16x16x32_bf16 v[88:91], v[142:145], v[182:185], v[88:91]
	v_mfma_f32_16x16x32_bf16 v[76:79], v[134:137], v[208:211], v[76:79]
	v_mfma_f32_16x16x32_bf16 v[72:75], v[142:145], v[208:211], v[72:75]
	s_setprio 0
	s_setprio 1
	v_mfma_f32_16x16x32_bf16 v[118:121], v[146:149], v[162:165], v[118:121]
	v_mfma_f32_16x16x32_bf16 v[114:117], v[154:157], v[162:165], v[114:117]
	v_mfma_f32_16x16x32_bf16 v[100:103], v[146:149], v[170:173], v[100:103]
	v_mfma_f32_16x16x32_bf16 v[96:99], v[154:157], v[170:173], v[96:99]
	v_mfma_f32_16x16x32_bf16 v[84:87], v[146:149], v[178:181], v[84:87]
	v_mfma_f32_16x16x32_bf16 v[80:83], v[154:157], v[178:181], v[80:83]
	v_mfma_f32_16x16x32_bf16 v[68:71], v[146:149], v[194:197], v[68:71]
	v_mfma_f32_16x16x32_bf16 v[64:67], v[154:157], v[194:197], v[64:67]
	v_mfma_f32_16x16x32_bf16 v[118:121], v[150:153], v[166:169], v[118:121]
	v_mfma_f32_16x16x32_bf16 v[114:117], v[158:161], v[166:169], v[114:117]
	v_mfma_f32_16x16x32_bf16 v[100:103], v[150:153], v[174:177], v[100:103]
	v_mfma_f32_16x16x32_bf16 v[96:99], v[158:161], v[174:177], v[96:99]
	v_mfma_f32_16x16x32_bf16 v[84:87], v[150:153], v[182:185], v[84:87]
	v_mfma_f32_16x16x32_bf16 v[80:83], v[158:161], v[182:185], v[80:83]
	v_mfma_f32_16x16x32_bf16 v[68:71], v[150:153], v[208:211], v[68:71]
	v_mfma_f32_16x16x32_bf16 v[64:67], v[158:161], v[208:211], v[64:67]
	s_setprio 0
	s_barrier
	s_add_i32 s3, s3, s42
	v_lshl_add_u64 v[212:213], v[212:213], 0, s[60:61]
	s_mov_b32 m0, s3
	ds_read_b128 v[162:165], v250 offset:49152
	ds_read_b128 v[166:169], v250 offset:50176
	ds_read_b128 v[170:173], v250 offset:51200
	ds_read_b128 v[174:177], v250 offset:52224
	ds_read_b128 v[178:181], v250 offset:53248
	ds_read_b128 v[182:185], v250 offset:54272
	ds_read_b128 v[194:197], v250 offset:55296
	ds_read_b128 v[208:211], v250 offset:56320
	global_load_lds_dwordx4 v[212:213], off
	s_add_i32 m0, s3, 0x2000
	s_add_u32 s36, s38, 0xb0080
	v_lshl_add_u64 v[212:213], v[214:215], 0, s[60:61]
	s_addc_u32 s37, s39, 0
	s_add_i32 s3, s56, s42
	global_load_lds_dwordx4 v[212:213], off
	v_lshl_add_u64 v[212:213], s[36:37], 0, v[112:113]
	s_mov_b32 m0, s3
	s_nop 0
	global_load_lds_dwordx4 v[212:213], off
	v_lshl_add_u64 v[212:213], s[36:37], 0, v[202:203]
	s_add_i32 m0, s3, 0x2000
	s_nop 0
	global_load_lds_dwordx4 v[212:213], off
	v_lshl_add_u64 v[212:213], v[216:217], 0, s[60:61]
	s_mov_b32 m0, s62
	s_nop 0
	global_load_lds_dwordx4 v[212:213], off
	v_lshl_add_u64 v[212:213], v[218:219], 0, s[60:61]
	s_mov_b32 m0, s63
	s_nop 0
	global_load_lds_dwordx4 v[212:213], off
	s_waitcnt vmcnt(8)
	s_waitcnt lgkmcnt(0)
	s_barrier
	s_setprio 1
	s_waitcnt lgkmcnt(0)
	v_mfma_f32_16x16x32_bf16 v[60:63], v[130:133], v[162:165], v[60:63]
	v_mfma_f32_16x16x32_bf16 v[56:59], v[138:141], v[162:165], v[56:59]
	v_mfma_f32_16x16x32_bf16 v[44:47], v[130:133], v[170:173], v[44:47]
	v_mfma_f32_16x16x32_bf16 v[40:43], v[138:141], v[170:173], v[40:43]
	v_mfma_f32_16x16x32_bf16 v[28:31], v[130:133], v[178:181], v[28:31]
	v_mfma_f32_16x16x32_bf16 v[24:27], v[138:141], v[178:181], v[24:27]
	v_mfma_f32_16x16x32_bf16 v[12:15], v[130:133], v[194:197], v[12:15]
	v_mfma_f32_16x16x32_bf16 v[8:11], v[138:141], v[194:197], v[8:11]
	v_mfma_f32_16x16x32_bf16 v[60:63], v[134:137], v[166:169], v[60:63]
	v_mfma_f32_16x16x32_bf16 v[56:59], v[142:145], v[166:169], v[56:59]
	v_mfma_f32_16x16x32_bf16 v[44:47], v[134:137], v[174:177], v[44:47]
	v_mfma_f32_16x16x32_bf16 v[40:43], v[142:145], v[174:177], v[40:43]
	v_mfma_f32_16x16x32_bf16 v[28:31], v[134:137], v[182:185], v[28:31]
	v_mfma_f32_16x16x32_bf16 v[24:27], v[142:145], v[182:185], v[24:27]
	v_mfma_f32_16x16x32_bf16 v[12:15], v[134:137], v[208:211], v[12:15]
	v_mfma_f32_16x16x32_bf16 v[8:11], v[142:145], v[208:211], v[8:11]
	s_setprio 0
	s_setprio 1
	v_mfma_f32_16x16x32_bf16 v[52:55], v[146:149], v[162:165], v[52:55]
	v_mfma_f32_16x16x32_bf16 v[48:51], v[154:157], v[162:165], v[48:51]
	v_mfma_f32_16x16x32_bf16 v[36:39], v[146:149], v[170:173], v[36:39]
	v_mfma_f32_16x16x32_bf16 v[32:35], v[154:157], v[170:173], v[32:35]
	v_mfma_f32_16x16x32_bf16 v[20:23], v[146:149], v[178:181], v[20:23]
	v_mfma_f32_16x16x32_bf16 v[16:19], v[154:157], v[178:181], v[16:19]
	v_mfma_f32_16x16x32_bf16 v[4:7], v[146:149], v[194:197], v[4:7]
	v_mfma_f32_16x16x32_bf16 v[0:3], v[154:157], v[194:197], v[0:3]
	v_mfma_f32_16x16x32_bf16 v[52:55], v[150:153], v[166:169], v[52:55]
	v_mfma_f32_16x16x32_bf16 v[48:51], v[158:161], v[166:169], v[48:51]
	v_mfma_f32_16x16x32_bf16 v[36:39], v[150:153], v[174:177], v[36:39]
	v_mfma_f32_16x16x32_bf16 v[32:35], v[158:161], v[174:177], v[32:35]
	v_mfma_f32_16x16x32_bf16 v[20:23], v[150:153], v[182:185], v[20:23]
	v_mfma_f32_16x16x32_bf16 v[16:19], v[158:161], v[182:185], v[16:19]
	v_mfma_f32_16x16x32_bf16 v[4:7], v[150:153], v[208:211], v[4:7]
	v_mfma_f32_16x16x32_bf16 v[0:3], v[158:161], v[208:211], v[0:3]
	s_setprio 0
	s_barrier
	s_add_i32 s83, s83, 2
	s_add_u32 s73, s73, 0x100
	s_addc_u32 s82, s82, 0
	s_cmp_gt_u32 s83, 41
	s_mov_b64 s[36:37], s[6:7]
	s_cbranch_scc0 .LBB0_1557
	s_branch .Lpeel_after_9
